# Hyena FFT loop: 676 pairs of independent scalar f32 add/sub/mul/fma merged into packed VOP3P ops (bit-identical lanes)
# baseline (speedup 1.0000x reference)
.LBB0_411:
	s_or_b64 exec, exec, s[54:55]
	s_add_u32 s28, s36, 0xe000000
	s_addc_u32 s29, s37, 0
	s_add_i32 s0, 0, 0x27dc0
	s_waitcnt lgkmcnt(0)
	s_barrier
	v_mov_b32_e32 v0, s0
	s_waitcnt lgkmcnt(0)
	ds_read_b128 v[0:3], v0
	v_mov_b32_e32 v4, s82
	ds_read_b128 v[4:7], v4
	s_add_u32 s0, s24, s26
	s_addc_u32 s1, s25, s27
	s_waitcnt lgkmcnt(0)
	v_add_f32_e32 v0, 0, v0
	v_add_f32_e32 v0, v0, v1
	v_add_f32_e32 v0, v0, v2
	v_add_f32_e32 v0, v0, v3
	v_add_f32_e32 v0, v0, v4
	v_add_f32_e32 v0, v0, v5
	v_add_f32_e32 v0, v0, v6
	v_add_f32_e32 v0, v0, v7
	v_add_f32_e32 v34, 0x358637bd, v0
	global_load_dword v177, v83, s[0:1]
	ds_read_b64 v[28:29], v136
	ds_read_b64 v[22:23], v137 offset:4096
	ds_read_b64 v[178:179], v136 offset:544
	ds_read_b64 v[14:15], v137 offset:4640
	ds_read_b64 v[180:181], v136 offset:1088
	ds_read_b64 v[6:7], v137 offset:5184
	ds_read_b64 v[182:183], v136 offset:1632
	ds_read_b64 v[0:1], v137 offset:5728
	ds_read_b64 v[184:185], v136 offset:2176
	ds_read_b64 v[26:27], v137 offset:6272
	ds_read_b64 v[186:187], v136 offset:2720
	ds_read_b64 v[18:19], v137 offset:6816
	ds_read_b64 v[188:189], v136 offset:3264
	ds_read_b64 v[10:11], v137 offset:7360
	ds_read_b64 v[190:191], v136 offset:3808
	ds_read_b64 v[2:3], v137 offset:7904
	ds_read_b64 v[192:193], v136 offset:4352
	ds_read_b64 v[30:31], v137 offset:8448
	ds_read_b64 v[194:195], v136 offset:4896
	ds_read_b64 v[20:21], v137 offset:8992
	ds_read_b64 v[196:197], v136 offset:5440
	ds_read_b64 v[12:13], v137 offset:9536
	ds_read_b64 v[198:199], v136 offset:5984
	ds_read_b64 v[4:5], v137 offset:10080
	ds_read_b64 v[200:201], v136 offset:6528
	ds_read_b64 v[32:33], v137 offset:10624
	ds_read_b64 v[202:203], v136 offset:7072
	ds_read_b64 v[24:25], v137 offset:11168
	ds_read_b64 v[204:205], v136 offset:7616
	ds_read_b64 v[16:17], v137 offset:11712
	ds_read_b64 v[206:207], v136 offset:8160
	ds_read_b64 v[8:9], v137 offset:12256
	s_waitcnt lgkmcnt(0)
	v_pk_add_f32 v[208:209], v[28:29], v[192:193] op_sel:[0,0] op_sel_hi:[1,1]
	v_pk_add_f32 v[28:29], v[28:29], v[192:193] op_sel:[0,0] op_sel_hi:[1,1] neg_lo:[0,1] neg_hi:[0,1]
	v_pk_add_f32 v[192:193], v[184:185], v[200:201] op_sel:[0,0] op_sel_hi:[1,1]
	v_pk_add_f32 v[184:185], v[184:185], v[200:201] op_sel:[0,0] op_sel_hi:[1,1] neg_lo:[0,1] neg_hi:[0,1]
	v_mov_b32_e32 v35, v139
	v_pk_add_f32 v[200:201], v[208:209], v[192:193] op_sel:[0,0] op_sel_hi:[1,1]
	v_pk_add_f32 v[192:193], v[208:209], v[192:193] op_sel:[0,0] op_sel_hi:[1,1] neg_lo:[0,1] neg_hi:[0,1]
	v_pk_add_f32 v[208:209], v[28:29], v[184:185] op_sel:[0,1] op_sel_hi:[1,0] neg_lo:[0,0] neg_hi:[0,1]
	v_pk_add_f32 v[184:185], v[28:29], v[184:185] op_sel:[1,0] op_sel_hi:[0,1] neg_lo:[0,0] neg_hi:[0,1]
	v_pk_add_f32 v[28:29], v[178:179], v[194:195] op_sel:[0,0] op_sel_hi:[1,1]
	v_pk_add_f32 v[178:179], v[178:179], v[194:195] op_sel:[0,0] op_sel_hi:[1,1] neg_lo:[0,1] neg_hi:[0,1]
	v_pk_add_f32 v[194:195], v[186:187], v[202:203] op_sel:[0,0] op_sel_hi:[1,1]
	v_pk_add_f32 v[186:187], v[186:187], v[202:203] op_sel:[0,0] op_sel_hi:[1,1] neg_lo:[0,1] neg_hi:[0,1]
	v_mov_b32_e32 v132, v140
	v_pk_add_f32 v[202:203], v[28:29], v[194:195] op_sel:[0,0] op_sel_hi:[1,1]
	v_pk_add_f32 v[28:29], v[28:29], v[194:195] op_sel:[0,0] op_sel_hi:[1,1] neg_lo:[0,1] neg_hi:[0,1]
	v_pk_add_f32 v[194:195], v[178:179], v[186:187] op_sel:[0,1] op_sel_hi:[1,0] neg_lo:[0,0] neg_hi:[0,1]
	v_pk_add_f32 v[178:179], v[178:179], v[186:187] op_sel:[0,1] op_sel_hi:[1,0] neg_lo:[0,1] neg_hi:[0,0]
	v_pk_add_f32 v[186:187], v[180:181], v[196:197] op_sel:[0,0] op_sel_hi:[1,1]
	v_pk_add_f32 v[180:181], v[180:181], v[196:197] op_sel:[0,0] op_sel_hi:[1,1] neg_lo:[0,1] neg_hi:[0,1]
	v_pk_add_f32 v[196:197], v[188:189], v[204:205] op_sel:[0,0] op_sel_hi:[1,1]
	v_pk_add_f32 v[188:189], v[188:189], v[204:205] op_sel:[0,0] op_sel_hi:[1,1] neg_lo:[0,1] neg_hi:[0,1]
	s_nop 1
	s_mov_b32 m0, s92
	v_pk_add_f32 v[204:205], v[186:187], v[196:197] op_sel:[0,0] op_sel_hi:[1,1]
	v_sub_f32_e32 v186, v186, v196
	v_sub_f32_e32 v196, v187, v197
	v_add_f32_e32 v187, v180, v189
	v_sub_f32_e32 v197, v181, v188
	v_pk_add_f32 v[180:181], v[180:181], v[188:189] op_sel:[0,1] op_sel_hi:[1,0] neg_lo:[0,1] neg_hi:[0,0]
	v_pk_add_f32 v[188:189], v[182:183], v[198:199] op_sel:[0,0] op_sel_hi:[1,1]
	v_pk_add_f32 v[182:183], v[182:183], v[198:199] op_sel:[0,0] op_sel_hi:[1,1] neg_lo:[0,1] neg_hi:[0,1]
	v_pk_add_f32 v[198:199], v[190:191], v[206:207] op_sel:[0,0] op_sel_hi:[1,1]
	v_pk_add_f32 v[190:191], v[190:191], v[206:207] op_sel:[0,0] op_sel_hi:[1,1] neg_lo:[0,1] neg_hi:[0,1]
	s_nop 0
	v_xor_b32_e32 v211, 0x80000000, v186
	v_pk_add_f32 v[206:207], v[188:189], v[198:199] op_sel:[0,0] op_sel_hi:[1,1]
	v_pk_add_f32 v[188:189], v[188:189], v[198:199] op_sel:[0,0] op_sel_hi:[1,1] neg_lo:[0,1] neg_hi:[0,1]
	v_pk_add_f32 v[198:199], v[182:183], v[190:191] op_sel:[0,1] op_sel_hi:[1,0] neg_lo:[0,0] neg_hi:[0,1]
	v_pk_add_f32 v[182:183], v[182:183], v[190:191] op_sel:[0,1] op_sel_hi:[1,0] neg_lo:[0,1] neg_hi:[0,0]
	v_pk_mul_f32 v[190:191], v[194:195], v[152:153] op_sel:[0,0] op_sel_hi:[0,1]
	v_mul_f32_e32 v194, v187, v154
	v_mul_f32_e32 v187, v187, v155
	v_xor_b32_e32 v134, 0x80000000, v35
	v_pk_fma_f32 v[190:191], v[194:195], v[152:153], v[190:191] op_sel:[1,1,0] op_sel_hi:[1,0,1] neg_lo:[1,0,0] neg_hi:[0,0,0]
	v_fma_f32 v195, v197, v154, v187
	v_mul_f32_e32 v187, v198, v156
	v_fma_f32 v194, -v197, v155, v194
	v_mul_f32_e32 v35, v132, v132
	s_nop 0
	v_fma_f32 v197, -v199, v157, v187
	v_mul_f32_e32 v187, v198, v157
	v_fma_f32 v130, -v134, v134, v35
	v_mul_f32_e32 v35, v132, v134
	s_nop 0
	v_fma_f32 v198, v199, v156, v187
	v_mul_f32_e32 v187, v28, v154
	v_mul_f32_e32 v28, v28, v155
	v_fma_f32 v131, v134, v132, v35
	v_mul_f32_e32 v35, v130, v132
	s_nop 0
	v_fma_f32 v210, v29, v154, v28
	v_mul_f32_e32 v28, v188, v155
	v_fma_f32 v199, -v29, v155, v187
	v_fma_f32 v128, -v131, v134, v35
	v_mul_f32_e32 v35, v130, v134
	s_nop 0
	v_fma_f32 v213, -v189, v155, v28
	v_fma_f32 v214, v189, v155, v28
	v_mul_f32_e32 v28, v178, v156
	v_pk_add_f32 v[188:189], v[202:203], v[206:207] op_sel:[0,0] op_sel_hi:[1,1] neg_lo:[0,1] neg_hi:[0,1]
	v_fma_f32 v129, v131, v132, v35
	v_mul_f32_e32 v35, v130, v130
	s_nop 0
	v_fma_f32 v215, -v179, v157, v28
	v_mul_f32_e32 v28, v178, v157
	v_fma_f32 v126, -v131, v131, v35
	v_mul_f32_e32 v35, v130, v131
	s_nop 0
	v_fma_f32 v216, v179, v156, v28
	v_mul_f32_e32 v28, v180, v155
	v_pk_add_f32 v[178:179], v[200:201], v[204:205] op_sel:[0,0] op_sel_hi:[1,1]
	v_fma_f32 v127, v131, v130, v35
	v_mul_f32_e32 v35, v126, v132
	s_nop 0
	v_fma_f32 v217, -v181, v155, v28
	v_fma_f32 v218, v181, v155, v28
	v_mul_f32_e32 v28, v182, v157
	v_pk_add_f32 v[180:181], v[200:201], v[204:205] op_sel:[0,0] op_sel_hi:[1,1] neg_lo:[0,1] neg_hi:[0,1]
	v_fma_f32 v124, -v127, v134, v35
	v_mul_f32_e32 v35, v126, v134
	s_nop 0
	v_fma_f32 v219, -v183, v156, v28
	v_mul_f32_e32 v28, v182, v156
	v_add_f32_e32 v182, v202, v206
	v_pk_add_f32 v[200:201], v[180:181], v[188:189] op_sel:[0,1] op_sel_hi:[1,0] neg_lo:[0,0] neg_hi:[0,1]
	v_fma_f32 v125, v127, v132, v35
	v_mul_f32_e32 v35, v128, v128
	s_nop 0
	v_sub_f32_e32 v206, v215, v219
	v_fma_f32 v220, v183, v157, v28
	v_add_f32_e32 v183, v203, v207
	v_pk_add_f32 v[28:29], v[178:179], v[182:183] op_sel:[0,0] op_sel_hi:[1,1]
	v_pk_add_f32 v[186:187], v[178:179], v[182:183] op_sel:[0,0] op_sel_hi:[1,1] neg_lo:[0,1] neg_hi:[0,1]
	v_pk_add_f32 v[178:179], v[180:181], v[188:189] op_sel:[0,1] op_sel_hi:[1,0] neg_lo:[0,1] neg_hi:[0,0]
	s_nop 0
	v_pk_add_f32 v[180:181], v[208:209], v[194:195] op_sel:[0,0] op_sel_hi:[1,1]
	v_pk_add_f32 v[182:183], v[208:209], v[194:195] op_sel:[0,0] op_sel_hi:[1,1] neg_lo:[0,1] neg_hi:[0,1]
	v_add_f32_e32 v188, v190, v197
	v_add_f32_e32 v189, v191, v198
	v_sub_f32_e32 v190, v190, v197
	v_sub_f32_e32 v191, v191, v198
	v_sub_f32_e32 v207, v216, v220
	v_fma_f32 v122, -v129, v129, v35
	s_nop 0
	v_pk_add_f32 v[194:195], v[180:181], v[188:189] op_sel:[0,0] op_sel_hi:[1,1]
	v_pk_add_f32 v[188:189], v[180:181], v[188:189] op_sel:[0,0] op_sel_hi:[1,1] neg_lo:[0,1] neg_hi:[0,1]
	v_add_f32_e32 v197, v182, v191
	v_sub_f32_e32 v198, v183, v190
	v_pk_add_f32 v[180:181], v[182:183], v[190:191] op_sel:[0,1] op_sel_hi:[1,0] neg_lo:[0,1] neg_hi:[0,0]
	v_add_f32_e32 v182, v192, v196
	v_add_f32_e32 v183, v193, v211
	v_sub_f32_e32 v192, v192, v196
	v_sub_f32_e32 v193, v193, v211
	v_add_f32_e32 v190, v199, v213
	v_add_f32_e32 v191, v210, v214
	v_sub_f32_e32 v196, v199, v213
	v_sub_f32_e32 v199, v210, v214
	v_mul_f32_e32 v35, v128, v129
	s_nop 0
	v_pk_add_f32 v[202:203], v[182:183], v[190:191] op_sel:[0,0] op_sel_hi:[1,1]
	v_pk_add_f32 v[190:191], v[182:183], v[190:191] op_sel:[0,0] op_sel_hi:[1,1] neg_lo:[0,1] neg_hi:[0,1]
	v_add_f32_e32 v204, v192, v199
	v_sub_f32_e32 v205, v193, v196
	v_sub_f32_e32 v182, v192, v199
	v_add_f32_e32 v183, v193, v196
	v_add_f32_e32 v192, v185, v217
	v_add_f32_e32 v193, v184, v218
	v_sub_f32_e32 v185, v185, v217
	v_sub_f32_e32 v196, v184, v218
	v_add_f32_e32 v184, v215, v219
	v_add_f32_e32 v199, v216, v220
	v_fma_f32 v123, v129, v128, v35
	v_mul_f32_e32 v35, v126, v128
	s_nop 0
	v_add_f32_e32 v208, v192, v184
	v_add_f32_e32 v209, v193, v199
	v_sub_f32_e32 v192, v192, v184
	v_sub_f32_e32 v193, v193, v199
	v_add_f32_e32 v199, v185, v207
	v_sub_f32_e32 v210, v196, v206
	v_sub_f32_e32 v184, v185, v207
	v_add_f32_e32 v185, v196, v206
	v_add_f32_e32 v196, v22, v30
	v_add_f32_e32 v206, v23, v31
	v_pk_add_f32 v[22:23], v[22:23], v[30:31] op_sel:[0,0] op_sel_hi:[1,1] neg_lo:[0,1] neg_hi:[0,1]
	v_pk_add_f32 v[30:31], v[26:27], v[32:33] op_sel:[0,0] op_sel_hi:[1,1]
	v_pk_add_f32 v[26:27], v[26:27], v[32:33] op_sel:[0,0] op_sel_hi:[1,1] neg_lo:[0,1] neg_hi:[0,1]
	v_fma_f32 v120, -v127, v129, v35
	v_mul_f32_e32 v35, v126, v129
	s_nop 0
	v_add_f32_e32 v32, v196, v30
	v_add_f32_e32 v33, v206, v31
	v_sub_f32_e32 v30, v196, v30
	v_sub_f32_e32 v31, v206, v31
	v_add_f32_e32 v196, v22, v27
	v_sub_f32_e32 v206, v23, v26
	v_pk_add_f32 v[22:23], v[22:23], v[26:27] op_sel:[0,1] op_sel_hi:[1,0] neg_lo:[0,1] neg_hi:[0,0]
	v_pk_add_f32 v[26:27], v[14:15], v[20:21] op_sel:[0,0] op_sel_hi:[1,1]
	v_pk_add_f32 v[14:15], v[14:15], v[20:21] op_sel:[0,0] op_sel_hi:[1,1] neg_lo:[0,1] neg_hi:[0,1]
	v_pk_add_f32 v[20:21], v[18:19], v[24:25] op_sel:[0,0] op_sel_hi:[1,1]
	v_pk_add_f32 v[18:19], v[18:19], v[24:25] op_sel:[0,0] op_sel_hi:[1,1] neg_lo:[0,1] neg_hi:[0,1]
	v_fma_f32 v121, v127, v128, v35
	v_mul_f32_e32 v35, v126, v126
	s_nop 0
	v_pk_add_f32 v[24:25], v[26:27], v[20:21] op_sel:[0,0] op_sel_hi:[1,1]
	v_pk_add_f32 v[20:21], v[26:27], v[20:21] op_sel:[0,0] op_sel_hi:[1,1] neg_lo:[0,1] neg_hi:[0,1]
	v_pk_add_f32 v[26:27], v[14:15], v[18:19] op_sel:[0,1] op_sel_hi:[1,0] neg_lo:[0,0] neg_hi:[0,1]
	v_pk_add_f32 v[14:15], v[14:15], v[18:19] op_sel:[0,1] op_sel_hi:[1,0] neg_lo:[0,1] neg_hi:[0,0]
	v_pk_add_f32 v[18:19], v[6:7], v[12:13] op_sel:[0,0] op_sel_hi:[1,1]
	v_pk_add_f32 v[6:7], v[6:7], v[12:13] op_sel:[0,0] op_sel_hi:[1,1] neg_lo:[0,1] neg_hi:[0,1]
	v_pk_add_f32 v[12:13], v[10:11], v[16:17] op_sel:[0,0] op_sel_hi:[1,1]
	v_pk_add_f32 v[10:11], v[10:11], v[16:17] op_sel:[0,0] op_sel_hi:[1,1] neg_lo:[0,1] neg_hi:[0,1]
	v_fma_f32 v49, -v127, v127, v35
	v_mul_f32_e32 v35, v126, v127
	s_nop 0
	v_pk_add_f32 v[16:17], v[18:19], v[12:13] op_sel:[0,0] op_sel_hi:[1,1]
	v_pk_add_f32 v[12:13], v[18:19], v[12:13] op_sel:[0,0] op_sel_hi:[1,1] neg_lo:[0,1] neg_hi:[0,1]
	v_pk_add_f32 v[18:19], v[6:7], v[10:11] op_sel:[0,1] op_sel_hi:[1,0] neg_lo:[0,0] neg_hi:[0,1]
	v_pk_add_f32 v[6:7], v[6:7], v[10:11] op_sel:[0,1] op_sel_hi:[1,0] neg_lo:[0,1] neg_hi:[0,0]
	v_pk_add_f32 v[10:11], v[0:1], v[4:5] op_sel:[0,0] op_sel_hi:[1,1]
	v_pk_add_f32 v[0:1], v[0:1], v[4:5] op_sel:[0,0] op_sel_hi:[1,1] neg_lo:[0,1] neg_hi:[0,1]
	v_pk_add_f32 v[4:5], v[2:3], v[8:9] op_sel:[0,0] op_sel_hi:[1,1]
	v_pk_add_f32 v[2:3], v[2:3], v[8:9] op_sel:[0,0] op_sel_hi:[1,1] neg_lo:[0,1] neg_hi:[0,1]
	s_nop 0
	v_mul_f32_e32 v6, v6, v155
	v_add_f32_e32 v207, v32, v16
	v_pk_add_f32 v[8:9], v[10:11], v[4:5] op_sel:[0,0] op_sel_hi:[1,1]
	v_pk_add_f32 v[4:5], v[10:11], v[4:5] op_sel:[0,0] op_sel_hi:[1,1] neg_lo:[0,1] neg_hi:[0,1]
	v_pk_add_f32 v[10:11], v[0:1], v[2:3] op_sel:[0,1] op_sel_hi:[1,0] neg_lo:[0,0] neg_hi:[0,1]
	v_pk_add_f32 v[0:1], v[0:1], v[2:3] op_sel:[0,1] op_sel_hi:[1,0] neg_lo:[0,1] neg_hi:[0,0]
	v_pk_mul_f32 v[2:3], v[26:27], v[152:153] op_sel:[0,0] op_sel_hi:[0,1]
	v_mul_f32_e32 v26, v18, v154
	v_mul_f32_e32 v18, v18, v155
	s_nop 0
	v_mul_f32_e32 v4, v4, v155
	v_add_f32_e32 v211, v33, v17
	v_pk_fma_f32 v[2:3], v[26:27], v[152:153], v[2:3] op_sel:[1,1,0] op_sel_hi:[1,0,1] neg_lo:[1,0,0] neg_hi:[0,0,0]
	v_fma_f32 v26, -v19, v155, v26
	v_fma_f32 v18, v19, v154, v18
	v_mul_f32_e32 v19, v10, v156
	v_mul_f32_e32 v10, v10, v157
	v_pk_add_f32 v[16:17], v[32:33], v[16:17] op_sel:[0,0] op_sel_hi:[1,1] neg_lo:[0,1] neg_hi:[0,1]
	v_pk_add_f32 v[32:33], v[24:25], v[8:9] op_sel:[0,0] op_sel_hi:[1,1]
	s_nop 0
	v_fma_f32 v19, -v11, v157, v19
	v_fma_f32 v10, v11, v156, v10
	v_mul_f32_e32 v11, v20, v154
	v_mul_f32_e32 v20, v20, v155
	v_pk_add_f32 v[8:9], v[24:25], v[8:9] op_sel:[0,0] op_sel_hi:[1,1] neg_lo:[0,1] neg_hi:[0,1]
	v_xor_b32_e32 v12, 0x80000000, v12
	v_fma_f32 v11, -v21, v155, v11
	v_fma_f32 v20, v21, v154, v20
	v_fma_f32 v21, -v5, v155, v4
	v_fma_f32 v4, v5, v155, v4
	v_mul_f32_e32 v5, v14, v156
	v_mul_f32_e32 v14, v14, v157
	v_sub_f32_e32 v24, v207, v32
	v_sub_f32_e32 v25, v211, v33
	v_fma_f32 v82, v127, v126, v35
	v_mul_f32_e32 v35, v49, v132
	s_nop 0
	v_fma_f32 v5, -v15, v157, v5
	v_fma_f32 v14, v15, v156, v14
	v_fma_f32 v15, -v7, v155, v6
	v_fma_f32 v6, v7, v155, v6
	v_mul_f32_e32 v7, v0, v157
	v_mul_f32_e32 v0, v0, v156
	v_fma_f32 v47, -v82, v134, v35
	v_mul_f32_e32 v35, v49, v134
	v_mul_f32_e32 v36, v49, v121
	s_nop 0
	v_fma_f32 v7, -v1, v156, v7
	v_fma_f32 v27, v1, v157, v0
	v_add_f32_e32 v0, v207, v32
	v_add_f32_e32 v1, v211, v33
	v_pk_add_f32 v[32:33], v[16:17], v[8:9] op_sel:[0,1] op_sel_hi:[1,0] neg_lo:[0,0] neg_hi:[0,1]
	v_pk_add_f32 v[8:9], v[16:17], v[8:9] op_sel:[1,0] op_sel_hi:[0,1] neg_lo:[0,0] neg_hi:[0,1]
	v_add_f32_e32 v16, v196, v26
	v_add_f32_e32 v17, v206, v18
	v_sub_f32_e32 v26, v196, v26
	v_sub_f32_e32 v18, v206, v18
	v_add_f32_e32 v196, v2, v19
	v_add_f32_e32 v206, v3, v10
	v_sub_f32_e32 v2, v2, v19
	v_sub_f32_e32 v3, v3, v10
	ds_write_b64 v138, v[28:29]
	ds_write_b64 v137, v[0:1] offset:4096
	v_add_f32_e32 v10, v16, v196
	v_add_f32_e32 v19, v17, v206
	v_sub_f32_e32 v16, v16, v196
	v_sub_f32_e32 v17, v17, v206
	v_add_f32_e32 v196, v26, v3
	v_sub_f32_e32 v206, v18, v2
	v_sub_f32_e32 v26, v26, v3
	v_add_f32_e32 v18, v18, v2
	v_pk_add_f32 v[2:3], v[30:31], v[12:13] op_sel:[0,1] op_sel_hi:[1,0]
	v_pk_add_f32 v[12:13], v[30:31], v[12:13] op_sel:[1,0] op_sel_hi:[0,1] neg_lo:[0,1] neg_hi:[0,1]
	v_add_f32_e32 v30, v11, v21
	v_add_f32_e32 v31, v20, v4
	v_sub_f32_e32 v11, v11, v21
	v_sub_f32_e32 v4, v20, v4
	v_mul_f32_e32 v0, v194, v132
	v_mul_f32_e32 v1, v194, v134
	s_nop 0
	v_pk_add_f32 v[20:21], v[2:3], v[30:31] op_sel:[0,0] op_sel_hi:[1,1]
	v_pk_add_f32 v[30:31], v[2:3], v[30:31] op_sel:[0,0] op_sel_hi:[1,1] neg_lo:[0,1] neg_hi:[0,1]
	v_add_f32_e32 v207, v13, v4
	v_sub_f32_e32 v211, v12, v11
	v_sub_f32_e32 v4, v13, v4
	v_add_f32_e32 v11, v12, v11
	v_add_f32_e32 v2, v22, v15
	v_add_f32_e32 v3, v23, v6
	v_sub_f32_e32 v12, v22, v15
	v_add_f32_e32 v13, v5, v7
	v_add_f32_e32 v15, v14, v27
	v_sub_f32_e32 v5, v5, v7
	v_sub_f32_e32 v7, v14, v27
	v_fma_f32 v0, -v195, v134, v0
	v_fma_f32 v1, v195, v132, v1
	s_nop 0
	v_add_f32_e32 v14, v2, v13
	v_add_f32_e32 v22, v3, v15
	v_sub_f32_e32 v13, v2, v13
	v_sub_f32_e32 v15, v3, v15
	v_mul_f32_e32 v2, v10, v132
	v_mul_f32_e32 v3, v10, v134
	v_sub_f32_e32 v6, v23, v6
	v_add_f32_e32 v23, v12, v7
	v_fma_f32 v48, v82, v132, v35
	v_mul_f32_e32 v35, v124, v124
	s_nop 0
	v_fma_f32 v2, -v19, v134, v2
	v_fma_f32 v3, v19, v132, v3
	ds_write_b64 v138, v[0:1] offset:544
	ds_write_b64 v137, v[2:3] offset:4640
	v_pk_mul_f32 v[0:1], v[202:203], v[130:131] op_sel:[0,0] op_sel_hi:[0,1]
	v_pk_mul_f32 v[2:3], v[20:21], v[130:131] op_sel:[0,0] op_sel_hi:[0,1]
	v_sub_f32_e32 v27, v6, v5
	v_fma_f32 v45, -v125, v125, v35
	s_nop 0
	v_pk_fma_f32 v[0:1], v[202:203], v[130:131], v[0:1] op_sel:[1,1,0] op_sel_hi:[1,0,1] neg_lo:[1,0,0] neg_hi:[0,0,0]
	v_pk_fma_f32 v[2:3], v[20:21], v[130:131], v[2:3] op_sel:[1,1,0] op_sel_hi:[1,0,1] neg_lo:[1,0,0] neg_hi:[0,0,0]
	ds_write_b64 v138, v[0:1] offset:1088
	ds_write_b64 v137, v[2:3] offset:5184
	v_pk_mul_f32 v[0:1], v[208:209], v[128:129] op_sel:[0,0] op_sel_hi:[0,1]
	v_pk_mul_f32 v[2:3], v[14:15], v[128:129] op_sel:[0,0] op_sel_hi:[0,1]
	v_mul_f32_e32 v35, v124, v125
	v_fma_f32 v36, v82, v120, v36
	s_nop 0
	v_pk_fma_f32 v[0:1], v[208:209], v[128:129], v[0:1] op_sel:[1,1,0] op_sel_hi:[1,0,1] neg_lo:[1,0,0] neg_hi:[0,0,0]
	v_pk_fma_f32 v[2:3], v[22:23], v[128:129], v[2:3] op_sel:[0,1,0] op_sel_hi:[0,0,1] neg_lo:[1,0,0] neg_hi:[0,0,0]
	ds_write_b64 v138, v[0:1] offset:1632
	ds_write_b64 v137, v[2:3] offset:5728
	v_pk_mul_f32 v[0:1], v[200:201], v[126:127] op_sel:[0,0] op_sel_hi:[0,1]
	v_pk_mul_f32 v[2:3], v[32:33], v[126:127] op_sel:[0,0] op_sel_hi:[0,1]
	v_fma_f32 v46, v125, v124, v35
	v_mul_f32_e32 v35, v49, v128
	s_nop 0
	v_pk_fma_f32 v[0:1], v[200:201], v[126:127], v[0:1] op_sel:[1,1,0] op_sel_hi:[1,0,1] neg_lo:[1,0,0] neg_hi:[0,0,0]
	v_pk_fma_f32 v[2:3], v[32:33], v[126:127], v[2:3] op_sel:[1,1,0] op_sel_hi:[1,0,1] neg_lo:[1,0,0] neg_hi:[0,0,0]
	ds_write_b64 v138, v[0:1] offset:2176
	ds_write_b64 v137, v[2:3] offset:6272
	v_pk_mul_f32 v[0:1], v[196:197], v[124:125] op_sel:[1,0] op_sel_hi:[1,1]
	v_pk_mul_f32 v[2:3], v[196:197], v[124:125] op_sel:[0,0] op_sel_hi:[0,1]
	v_fma_f32 v43, -v82, v129, v35
	v_mul_f32_e32 v35, v49, v129
	s_nop 0
	v_pk_fma_f32 v[0:1], v[198:199], v[124:125], v[0:1] op_sel:[0,1,0] op_sel_hi:[0,0,1] neg_lo:[1,0,0] neg_hi:[0,0,0]
	v_pk_fma_f32 v[2:3], v[206:207], v[124:125], v[2:3] op_sel:[0,1,0] op_sel_hi:[0,0,1] neg_lo:[1,0,0] neg_hi:[0,0,0]
	ds_write_b64 v138, v[0:1] offset:2720
	ds_write_b64 v137, v[2:3] offset:6816
	v_pk_mul_f32 v[0:1], v[204:205], v[122:123] op_sel:[0,0] op_sel_hi:[0,1]
	v_pk_mul_f32 v[2:3], v[206:207], v[122:123] op_sel:[1,0] op_sel_hi:[1,1]
	v_fma_f32 v44, v82, v128, v35
	v_mul_f32_e32 v35, v122, v122
	s_nop 0
	v_pk_fma_f32 v[0:1], v[204:205], v[122:123], v[0:1] op_sel:[1,1,0] op_sel_hi:[1,0,1] neg_lo:[1,0,0] neg_hi:[0,0,0]
	v_pk_fma_f32 v[2:3], v[210:211], v[122:123], v[2:3] op_sel:[1,1,0] op_sel_hi:[1,0,1] neg_lo:[1,0,0] neg_hi:[0,0,0]
	ds_write_b64 v138, v[0:1] offset:3264
	ds_write_b64 v137, v[2:3] offset:7360
	v_pk_mul_f32 v[0:1], v[198:199], v[120:121] op_sel:[1,0] op_sel_hi:[1,1]
	v_pk_mul_f32 v[2:3], v[22:23], v[120:121] op_sel:[1,0] op_sel_hi:[1,1]
	v_fma_f32 v41, -v123, v123, v35
	v_mul_f32_e32 v35, v122, v123
	s_nop 0
	v_pk_fma_f32 v[0:1], v[210:211], v[120:121], v[0:1] op_sel:[0,1,0] op_sel_hi:[0,0,1] neg_lo:[1,0,0] neg_hi:[0,0,0]
	v_pk_fma_f32 v[2:3], v[26:27], v[120:121], v[2:3] op_sel:[1,1,0] op_sel_hi:[1,0,1] neg_lo:[1,0,0] neg_hi:[0,0,0]
	ds_write_b64 v138, v[0:1] offset:3808
	ds_write_b64 v137, v[2:3] offset:7904
	v_mul_f32_e32 v0, v186, v49
	v_mul_f32_e32 v1, v186, v82
	v_mul_f32_e32 v2, v24, v49
	v_mul_f32_e32 v3, v24, v82
	v_fma_f32 v42, v123, v122, v35
	v_mul_f32_e32 v35, v49, v124
	s_nop 0
	v_fma_f32 v0, -v187, v82, v0
	v_fma_f32 v1, v187, v49, v1
	v_fma_f32 v2, -v25, v82, v2
	v_fma_f32 v3, v25, v49, v3
	ds_write_b64 v138, v[0:1] offset:4352
	ds_write_b64 v137, v[2:3] offset:8448
	v_mul_f32_e32 v0, v188, v47
	v_mul_f32_e32 v1, v188, v48
	v_mul_f32_e32 v2, v16, v47
	v_mul_f32_e32 v3, v16, v48
	v_fma_f32 v39, -v82, v125, v35
	v_mul_f32_e32 v35, v49, v125
	s_nop 0
	v_fma_f32 v0, -v189, v48, v0
	v_fma_f32 v1, v189, v47, v1
	v_fma_f32 v2, -v17, v48, v2
	v_fma_f32 v3, v17, v47, v3
	ds_write_b64 v138, v[0:1] offset:4896
	ds_write_b64 v137, v[2:3] offset:8992
	v_mul_f32_e32 v0, v190, v45
	v_mul_f32_e32 v1, v190, v46
	v_mul_f32_e32 v2, v30, v45
	v_mul_f32_e32 v3, v30, v46
	v_fma_f32 v40, v82, v124, v35
	v_mul_f32_e32 v35, v120, v120
	s_nop 0
	v_fma_f32 v0, -v191, v46, v0
	v_fma_f32 v1, v191, v45, v1
	v_fma_f32 v2, -v31, v46, v2
	v_fma_f32 v3, v31, v45, v3
	ds_write_b64 v138, v[0:1] offset:5440
	ds_write_b64 v137, v[2:3] offset:9536
	v_mul_f32_e32 v0, v192, v43
	v_mul_f32_e32 v1, v192, v44
	v_mul_f32_e32 v2, v13, v43
	v_mul_f32_e32 v3, v13, v44
	v_fma_f32 v37, -v121, v121, v35
	v_mul_f32_e32 v35, v120, v121
	s_nop 0
	v_fma_f32 v0, -v193, v44, v0
	v_fma_f32 v1, v193, v43, v1
	v_fma_f32 v2, -v15, v44, v2
	v_fma_f32 v3, v15, v43, v3
	ds_write_b64 v138, v[0:1] offset:5984
	ds_write_b64 v137, v[2:3] offset:10080
	v_mul_f32_e32 v0, v178, v41
	v_mul_f32_e32 v1, v178, v42
	v_mul_f32_e32 v2, v9, v41
	v_mul_f32_e32 v3, v9, v42
	v_fma_f32 v38, v121, v120, v35
	v_mul_f32_e32 v35, v49, v120
	s_nop 0
	v_fma_f32 v0, -v179, v42, v0
	v_fma_f32 v1, v179, v41, v1
	v_fma_f32 v2, -v8, v42, v2
	v_fma_f32 v3, v8, v41, v3
	ds_write_b64 v138, v[0:1] offset:6528
	ds_write_b64 v137, v[2:3] offset:10624
	v_mul_f32_e32 v0, v180, v39
	v_mul_f32_e32 v1, v180, v40
	v_mul_f32_e32 v2, v26, v39
	v_mul_f32_e32 v3, v26, v40
	v_fma_f32 v35, -v82, v121, v35
	v_sub_f32_e32 v7, v12, v7
	s_nop 0
	v_fma_f32 v0, -v181, v40, v0
	v_fma_f32 v1, v181, v39, v1
	v_fma_f32 v2, -v18, v40, v2
	v_fma_f32 v3, v18, v39, v3
	ds_write_b64 v138, v[0:1] offset:7072
	ds_write_b64 v137, v[2:3] offset:11168
	v_mul_f32_e32 v0, v182, v37
	v_mul_f32_e32 v1, v182, v38
	v_mul_f32_e32 v2, v4, v37
	v_mul_f32_e32 v3, v4, v38
	v_add_f32_e32 v5, v6, v5
	v_mov_b32_e32 v132, v144
	v_fma_f32 v0, -v183, v38, v0
	v_fma_f32 v1, v183, v37, v1
	v_fma_f32 v2, -v11, v38, v2
	v_fma_f32 v3, v11, v37, v3
	ds_write_b64 v138, v[0:1] offset:7616
	ds_write_b64 v137, v[2:3] offset:11712
	v_mul_f32_e32 v0, v184, v35
	v_mul_f32_e32 v1, v184, v36
	v_mul_f32_e32 v2, v7, v35
	v_mul_f32_e32 v3, v7, v36
	s_nop 0
	v_fma_f32 v0, -v185, v36, v0
	v_fma_f32 v1, v185, v35, v1
	v_fma_f32 v2, -v5, v36, v2
	v_fma_f32 v3, v5, v35, v3
	ds_write_b64 v138, v[0:1] offset:8160
	ds_write_b64 v137, v[2:3] offset:12256
	ds_read_b64 v[28:29], v93
	ds_read_b64 v[22:23], v141 offset:4096
	ds_read_b64 v[178:179], v93 offset:32
	ds_read_b64 v[14:15], v141 offset:4128
	ds_read_b64 v[180:181], v93 offset:64
	ds_read_b64 v[6:7], v141 offset:4160
	ds_read_b64 v[182:183], v93 offset:96
	ds_read_b64 v[0:1], v141 offset:4192
	ds_read_b64 v[184:185], v93 offset:128
	ds_read_b64 v[26:27], v141 offset:4224
	ds_read_b64 v[186:187], v93 offset:160
	ds_read_b64 v[18:19], v141 offset:4256
	ds_read_b64 v[188:189], v93 offset:192
	ds_read_b64 v[10:11], v141 offset:4288
	ds_read_b64 v[190:191], v93 offset:224
	ds_read_b64 v[2:3], v141 offset:4320
	ds_read_b64 v[192:193], v93 offset:256
	ds_read_b64 v[30:31], v141 offset:4352
	ds_read_b64 v[194:195], v93 offset:288
	ds_read_b64 v[20:21], v141 offset:4384
	ds_read_b64 v[196:197], v93 offset:320
	ds_read_b64 v[12:13], v141 offset:4416
	ds_read_b64 v[198:199], v93 offset:352
	ds_read_b64 v[4:5], v141 offset:4448
	ds_read_b64 v[200:201], v93 offset:384
	ds_read_b64 v[32:33], v141 offset:4480
	ds_read_b64 v[202:203], v93 offset:416
	ds_read_b64 v[24:25], v141 offset:4512
	ds_read_b64 v[204:205], v93 offset:448
	ds_read_b64 v[16:17], v141 offset:4544
	ds_read_b64 v[206:207], v93 offset:480
	ds_read_b64 v[8:9], v141 offset:4576
	s_waitcnt lgkmcnt(0)
	v_pk_add_f32 v[208:209], v[28:29], v[192:193] op_sel:[0,0] op_sel_hi:[1,1]
	v_pk_add_f32 v[28:29], v[28:29], v[192:193] op_sel:[0,0] op_sel_hi:[1,1] neg_lo:[0,1] neg_hi:[0,1]
	v_pk_add_f32 v[192:193], v[184:185], v[200:201] op_sel:[0,0] op_sel_hi:[1,1]
	v_pk_add_f32 v[184:185], v[184:185], v[200:201] op_sel:[0,0] op_sel_hi:[1,1] neg_lo:[0,1] neg_hi:[0,1]
	v_mov_b32_e32 v35, v143
	v_pk_add_f32 v[200:201], v[208:209], v[192:193] op_sel:[0,0] op_sel_hi:[1,1]
	v_pk_add_f32 v[192:193], v[208:209], v[192:193] op_sel:[0,0] op_sel_hi:[1,1] neg_lo:[0,1] neg_hi:[0,1]
	v_pk_add_f32 v[208:209], v[28:29], v[184:185] op_sel:[0,1] op_sel_hi:[1,0] neg_lo:[0,0] neg_hi:[0,1]
	v_pk_add_f32 v[184:185], v[28:29], v[184:185] op_sel:[1,0] op_sel_hi:[0,1] neg_lo:[0,0] neg_hi:[0,1]
	v_pk_add_f32 v[28:29], v[178:179], v[194:195] op_sel:[0,0] op_sel_hi:[1,1]
	v_pk_add_f32 v[178:179], v[178:179], v[194:195] op_sel:[0,0] op_sel_hi:[1,1] neg_lo:[0,1] neg_hi:[0,1]
	v_pk_add_f32 v[194:195], v[186:187], v[202:203] op_sel:[0,0] op_sel_hi:[1,1]
	v_pk_add_f32 v[186:187], v[186:187], v[202:203] op_sel:[0,0] op_sel_hi:[1,1] neg_lo:[0,1] neg_hi:[0,1]
	s_nop 1
	s_nop 0
	v_pk_add_f32 v[202:203], v[28:29], v[194:195] op_sel:[0,0] op_sel_hi:[1,1]
	v_pk_add_f32 v[28:29], v[28:29], v[194:195] op_sel:[0,0] op_sel_hi:[1,1] neg_lo:[0,1] neg_hi:[0,1]
	v_pk_add_f32 v[194:195], v[178:179], v[186:187] op_sel:[0,1] op_sel_hi:[1,0] neg_lo:[0,0] neg_hi:[0,1]
	v_pk_add_f32 v[178:179], v[178:179], v[186:187] op_sel:[0,1] op_sel_hi:[1,0] neg_lo:[0,1] neg_hi:[0,0]
	v_pk_add_f32 v[186:187], v[180:181], v[196:197] op_sel:[0,0] op_sel_hi:[1,1]
	v_pk_add_f32 v[180:181], v[180:181], v[196:197] op_sel:[0,0] op_sel_hi:[1,1] neg_lo:[0,1] neg_hi:[0,1]
	v_pk_add_f32 v[196:197], v[188:189], v[204:205] op_sel:[0,0] op_sel_hi:[1,1]
	v_pk_add_f32 v[188:189], v[188:189], v[204:205] op_sel:[0,0] op_sel_hi:[1,1] neg_lo:[0,1] neg_hi:[0,1]
	v_xor_b32_e32 v134, 0x80000000, v35
	v_pk_add_f32 v[204:205], v[186:187], v[196:197] op_sel:[0,0] op_sel_hi:[1,1]
	v_sub_f32_e32 v186, v186, v196
	v_sub_f32_e32 v196, v187, v197
	v_add_f32_e32 v187, v180, v189
	v_sub_f32_e32 v197, v181, v188
	v_pk_add_f32 v[180:181], v[180:181], v[188:189] op_sel:[0,1] op_sel_hi:[1,0] neg_lo:[0,1] neg_hi:[0,0]
	v_pk_add_f32 v[188:189], v[182:183], v[198:199] op_sel:[0,0] op_sel_hi:[1,1]
	v_pk_add_f32 v[182:183], v[182:183], v[198:199] op_sel:[0,0] op_sel_hi:[1,1] neg_lo:[0,1] neg_hi:[0,1]
	v_pk_add_f32 v[198:199], v[190:191], v[206:207] op_sel:[0,0] op_sel_hi:[1,1]
	v_pk_add_f32 v[190:191], v[190:191], v[206:207] op_sel:[0,0] op_sel_hi:[1,1] neg_lo:[0,1] neg_hi:[0,1]
	s_nop 0
	v_xor_b32_e32 v211, 0x80000000, v186
	v_pk_add_f32 v[206:207], v[188:189], v[198:199] op_sel:[0,0] op_sel_hi:[1,1]
	v_pk_add_f32 v[188:189], v[188:189], v[198:199] op_sel:[0,0] op_sel_hi:[1,1] neg_lo:[0,1] neg_hi:[0,1]
	v_pk_add_f32 v[198:199], v[182:183], v[190:191] op_sel:[0,1] op_sel_hi:[1,0] neg_lo:[0,0] neg_hi:[0,1]
	v_pk_add_f32 v[182:183], v[182:183], v[190:191] op_sel:[0,1] op_sel_hi:[1,0] neg_lo:[0,1] neg_hi:[0,0]
	v_pk_mul_f32 v[190:191], v[194:195], v[152:153] op_sel:[0,0] op_sel_hi:[0,1]
	v_mul_f32_e32 v194, v187, v154
	v_mul_f32_e32 v187, v187, v155
	v_mul_f32_e32 v35, v132, v132
	s_nop 0
	v_pk_fma_f32 v[190:191], v[194:195], v[152:153], v[190:191] op_sel:[1,1,0] op_sel_hi:[1,0,1] neg_lo:[1,0,0] neg_hi:[0,0,0]
	v_fma_f32 v195, v197, v154, v187
	v_mul_f32_e32 v187, v198, v156
	v_fma_f32 v194, -v197, v155, v194
	v_fma_f32 v130, -v134, v134, v35
	v_mul_f32_e32 v35, v132, v134
	s_nop 0
	v_fma_f32 v197, -v199, v157, v187
	v_mul_f32_e32 v187, v198, v157
	v_fma_f32 v131, v134, v132, v35
	v_mul_f32_e32 v35, v130, v132
	s_nop 0
	v_fma_f32 v198, v199, v156, v187
	v_mul_f32_e32 v187, v28, v154
	v_mul_f32_e32 v28, v28, v155
	v_fma_f32 v128, -v131, v134, v35
	v_mul_f32_e32 v35, v130, v134
	s_nop 0
	v_fma_f32 v210, v29, v154, v28
	v_mul_f32_e32 v28, v188, v155
	v_fma_f32 v199, -v29, v155, v187
	v_fma_f32 v129, v131, v132, v35
	v_mul_f32_e32 v35, v130, v130
	s_nop 0
	v_fma_f32 v213, -v189, v155, v28
	v_fma_f32 v214, v189, v155, v28
	v_mul_f32_e32 v28, v178, v156
	v_pk_add_f32 v[188:189], v[202:203], v[206:207] op_sel:[0,0] op_sel_hi:[1,1] neg_lo:[0,1] neg_hi:[0,1]
	v_fma_f32 v126, -v131, v131, v35
	v_mul_f32_e32 v35, v130, v131
	s_nop 0
	v_fma_f32 v215, -v179, v157, v28
	v_mul_f32_e32 v28, v178, v157
	v_fma_f32 v127, v131, v130, v35
	v_mul_f32_e32 v35, v126, v132
	s_nop 0
	v_fma_f32 v216, v179, v156, v28
	v_mul_f32_e32 v28, v180, v155
	v_pk_add_f32 v[178:179], v[200:201], v[204:205] op_sel:[0,0] op_sel_hi:[1,1]
	v_fma_f32 v124, -v127, v134, v35
	v_mul_f32_e32 v35, v126, v134
	s_nop 0
	v_fma_f32 v217, -v181, v155, v28
	v_fma_f32 v218, v181, v155, v28
	v_mul_f32_e32 v28, v182, v157
	v_pk_add_f32 v[180:181], v[200:201], v[204:205] op_sel:[0,0] op_sel_hi:[1,1] neg_lo:[0,1] neg_hi:[0,1]
	v_fma_f32 v125, v127, v132, v35
	v_mul_f32_e32 v35, v128, v128
	s_nop 0
	v_fma_f32 v219, -v183, v156, v28
	v_mul_f32_e32 v28, v182, v156
	v_add_f32_e32 v182, v202, v206
	v_pk_add_f32 v[200:201], v[180:181], v[188:189] op_sel:[0,1] op_sel_hi:[1,0] neg_lo:[0,0] neg_hi:[0,1]
	v_fma_f32 v122, -v129, v129, v35
	v_mul_f32_e32 v35, v128, v129
	s_nop 0
	v_sub_f32_e32 v206, v215, v219
	v_fma_f32 v220, v183, v157, v28
	v_add_f32_e32 v183, v203, v207
	v_pk_add_f32 v[28:29], v[178:179], v[182:183] op_sel:[0,0] op_sel_hi:[1,1]
	v_pk_add_f32 v[186:187], v[178:179], v[182:183] op_sel:[0,0] op_sel_hi:[1,1] neg_lo:[0,1] neg_hi:[0,1]
	v_pk_add_f32 v[178:179], v[180:181], v[188:189] op_sel:[0,1] op_sel_hi:[1,0] neg_lo:[0,1] neg_hi:[0,0]
	s_nop 0
	v_pk_add_f32 v[180:181], v[208:209], v[194:195] op_sel:[0,0] op_sel_hi:[1,1]
	v_pk_add_f32 v[182:183], v[208:209], v[194:195] op_sel:[0,0] op_sel_hi:[1,1] neg_lo:[0,1] neg_hi:[0,1]
	v_add_f32_e32 v188, v190, v197
	v_add_f32_e32 v189, v191, v198
	v_sub_f32_e32 v190, v190, v197
	v_sub_f32_e32 v191, v191, v198
	v_sub_f32_e32 v207, v216, v220
	v_fma_f32 v123, v129, v128, v35
	s_nop 0
	v_pk_add_f32 v[194:195], v[180:181], v[188:189] op_sel:[0,0] op_sel_hi:[1,1]
	v_pk_add_f32 v[188:189], v[180:181], v[188:189] op_sel:[0,0] op_sel_hi:[1,1] neg_lo:[0,1] neg_hi:[0,1]
	v_add_f32_e32 v197, v182, v191
	v_sub_f32_e32 v198, v183, v190
	v_pk_add_f32 v[180:181], v[182:183], v[190:191] op_sel:[0,1] op_sel_hi:[1,0] neg_lo:[0,1] neg_hi:[0,0]
	v_add_f32_e32 v182, v192, v196
	v_add_f32_e32 v183, v193, v211
	v_sub_f32_e32 v192, v192, v196
	v_sub_f32_e32 v193, v193, v211
	v_add_f32_e32 v190, v199, v213
	v_add_f32_e32 v191, v210, v214
	v_sub_f32_e32 v196, v199, v213
	v_sub_f32_e32 v199, v210, v214
	v_mul_f32_e32 v35, v126, v128
	s_nop 0
	v_pk_add_f32 v[202:203], v[182:183], v[190:191] op_sel:[0,0] op_sel_hi:[1,1]
	v_pk_add_f32 v[190:191], v[182:183], v[190:191] op_sel:[0,0] op_sel_hi:[1,1] neg_lo:[0,1] neg_hi:[0,1]
	v_add_f32_e32 v204, v192, v199
	v_sub_f32_e32 v205, v193, v196
	v_sub_f32_e32 v182, v192, v199
	v_add_f32_e32 v183, v193, v196
	v_add_f32_e32 v192, v185, v217
	v_add_f32_e32 v193, v184, v218
	v_sub_f32_e32 v185, v185, v217
	v_sub_f32_e32 v196, v184, v218
	v_add_f32_e32 v184, v215, v219
	v_add_f32_e32 v199, v216, v220
	v_fma_f32 v120, -v127, v129, v35
	v_mul_f32_e32 v35, v126, v129
	s_nop 0
	v_add_f32_e32 v208, v192, v184
	v_add_f32_e32 v209, v193, v199
	v_sub_f32_e32 v192, v192, v184
	v_sub_f32_e32 v193, v193, v199
	v_add_f32_e32 v199, v185, v207
	v_sub_f32_e32 v210, v196, v206
	v_sub_f32_e32 v184, v185, v207
	v_add_f32_e32 v185, v196, v206
	v_add_f32_e32 v196, v22, v30
	v_add_f32_e32 v206, v23, v31
	v_pk_add_f32 v[22:23], v[22:23], v[30:31] op_sel:[0,0] op_sel_hi:[1,1] neg_lo:[0,1] neg_hi:[0,1]
	v_pk_add_f32 v[30:31], v[26:27], v[32:33] op_sel:[0,0] op_sel_hi:[1,1]
	v_pk_add_f32 v[26:27], v[26:27], v[32:33] op_sel:[0,0] op_sel_hi:[1,1] neg_lo:[0,1] neg_hi:[0,1]
	v_fma_f32 v121, v127, v128, v35
	v_mul_f32_e32 v35, v126, v126
	s_nop 0
	v_add_f32_e32 v32, v196, v30
	v_add_f32_e32 v33, v206, v31
	v_sub_f32_e32 v30, v196, v30
	v_sub_f32_e32 v31, v206, v31
	v_add_f32_e32 v196, v22, v27
	v_sub_f32_e32 v206, v23, v26
	v_pk_add_f32 v[22:23], v[22:23], v[26:27] op_sel:[0,1] op_sel_hi:[1,0] neg_lo:[0,1] neg_hi:[0,0]
	v_pk_add_f32 v[26:27], v[14:15], v[20:21] op_sel:[0,0] op_sel_hi:[1,1]
	v_pk_add_f32 v[14:15], v[14:15], v[20:21] op_sel:[0,0] op_sel_hi:[1,1] neg_lo:[0,1] neg_hi:[0,1]
	v_pk_add_f32 v[20:21], v[18:19], v[24:25] op_sel:[0,0] op_sel_hi:[1,1]
	v_pk_add_f32 v[18:19], v[18:19], v[24:25] op_sel:[0,0] op_sel_hi:[1,1] neg_lo:[0,1] neg_hi:[0,1]
	v_fma_f32 v49, -v127, v127, v35
	v_mul_f32_e32 v35, v126, v127
	s_nop 0
	v_pk_add_f32 v[24:25], v[26:27], v[20:21] op_sel:[0,0] op_sel_hi:[1,1]
	v_pk_add_f32 v[20:21], v[26:27], v[20:21] op_sel:[0,0] op_sel_hi:[1,1] neg_lo:[0,1] neg_hi:[0,1]
	v_pk_add_f32 v[26:27], v[14:15], v[18:19] op_sel:[0,1] op_sel_hi:[1,0] neg_lo:[0,0] neg_hi:[0,1]
	v_pk_add_f32 v[14:15], v[14:15], v[18:19] op_sel:[0,1] op_sel_hi:[1,0] neg_lo:[0,1] neg_hi:[0,0]
	v_pk_add_f32 v[18:19], v[6:7], v[12:13] op_sel:[0,0] op_sel_hi:[1,1]
	v_pk_add_f32 v[6:7], v[6:7], v[12:13] op_sel:[0,0] op_sel_hi:[1,1] neg_lo:[0,1] neg_hi:[0,1]
	v_pk_add_f32 v[12:13], v[10:11], v[16:17] op_sel:[0,0] op_sel_hi:[1,1]
	v_pk_add_f32 v[10:11], v[10:11], v[16:17] op_sel:[0,0] op_sel_hi:[1,1] neg_lo:[0,1] neg_hi:[0,1]
	v_fma_f32 v82, v127, v126, v35
	v_mul_f32_e32 v35, v49, v132
	s_nop 0
	v_pk_add_f32 v[16:17], v[18:19], v[12:13] op_sel:[0,0] op_sel_hi:[1,1]
	v_pk_add_f32 v[12:13], v[18:19], v[12:13] op_sel:[0,0] op_sel_hi:[1,1] neg_lo:[0,1] neg_hi:[0,1]
	v_pk_add_f32 v[18:19], v[6:7], v[10:11] op_sel:[0,1] op_sel_hi:[1,0] neg_lo:[0,0] neg_hi:[0,1]
	v_pk_add_f32 v[6:7], v[6:7], v[10:11] op_sel:[0,1] op_sel_hi:[1,0] neg_lo:[0,1] neg_hi:[0,0]
	v_pk_add_f32 v[10:11], v[0:1], v[4:5] op_sel:[0,0] op_sel_hi:[1,1]
	v_pk_add_f32 v[0:1], v[0:1], v[4:5] op_sel:[0,0] op_sel_hi:[1,1] neg_lo:[0,1] neg_hi:[0,1]
	v_pk_add_f32 v[4:5], v[2:3], v[8:9] op_sel:[0,0] op_sel_hi:[1,1]
	v_pk_add_f32 v[2:3], v[2:3], v[8:9] op_sel:[0,0] op_sel_hi:[1,1] neg_lo:[0,1] neg_hi:[0,1]
	s_nop 0
	v_mul_f32_e32 v6, v6, v155
	v_add_f32_e32 v207, v32, v16
	v_pk_add_f32 v[8:9], v[10:11], v[4:5] op_sel:[0,0] op_sel_hi:[1,1]
	v_pk_add_f32 v[4:5], v[10:11], v[4:5] op_sel:[0,0] op_sel_hi:[1,1] neg_lo:[0,1] neg_hi:[0,1]
	v_pk_add_f32 v[10:11], v[0:1], v[2:3] op_sel:[0,1] op_sel_hi:[1,0] neg_lo:[0,0] neg_hi:[0,1]
	v_pk_add_f32 v[0:1], v[0:1], v[2:3] op_sel:[0,1] op_sel_hi:[1,0] neg_lo:[0,1] neg_hi:[0,0]
	v_pk_mul_f32 v[2:3], v[26:27], v[152:153] op_sel:[0,0] op_sel_hi:[0,1]
	v_mul_f32_e32 v26, v18, v154
	v_mul_f32_e32 v18, v18, v155
	s_nop 0
	v_mul_f32_e32 v4, v4, v155
	v_add_f32_e32 v211, v33, v17
	v_pk_fma_f32 v[2:3], v[26:27], v[152:153], v[2:3] op_sel:[1,1,0] op_sel_hi:[1,0,1] neg_lo:[1,0,0] neg_hi:[0,0,0]
	v_fma_f32 v26, -v19, v155, v26
	v_fma_f32 v18, v19, v154, v18
	v_mul_f32_e32 v19, v10, v156
	v_mul_f32_e32 v10, v10, v157
	v_pk_add_f32 v[16:17], v[32:33], v[16:17] op_sel:[0,0] op_sel_hi:[1,1] neg_lo:[0,1] neg_hi:[0,1]
	v_pk_add_f32 v[32:33], v[24:25], v[8:9] op_sel:[0,0] op_sel_hi:[1,1]
	s_nop 0
	v_fma_f32 v19, -v11, v157, v19
	v_fma_f32 v10, v11, v156, v10
	v_mul_f32_e32 v11, v20, v154
	v_mul_f32_e32 v20, v20, v155
	v_pk_add_f32 v[8:9], v[24:25], v[8:9] op_sel:[0,0] op_sel_hi:[1,1] neg_lo:[0,1] neg_hi:[0,1]
	v_xor_b32_e32 v12, 0x80000000, v12
	v_fma_f32 v11, -v21, v155, v11
	v_fma_f32 v20, v21, v154, v20
	v_fma_f32 v21, -v5, v155, v4
	v_fma_f32 v4, v5, v155, v4
	v_mul_f32_e32 v5, v14, v156
	v_mul_f32_e32 v14, v14, v157
	v_sub_f32_e32 v24, v207, v32
	v_sub_f32_e32 v25, v211, v33
	v_fma_f32 v47, -v82, v134, v35
	v_mul_f32_e32 v35, v49, v134
	s_nop 0
	v_fma_f32 v5, -v15, v157, v5
	v_fma_f32 v14, v15, v156, v14
	v_fma_f32 v15, -v7, v155, v6
	v_fma_f32 v6, v7, v155, v6
	v_mul_f32_e32 v7, v0, v157
	v_mul_f32_e32 v0, v0, v156
	v_fma_f32 v48, v82, v132, v35
	v_mul_f32_e32 v35, v124, v124
	v_mul_f32_e32 v36, v49, v121
	s_nop 0
	v_fma_f32 v7, -v1, v156, v7
	v_fma_f32 v27, v1, v157, v0
	v_add_f32_e32 v0, v207, v32
	v_add_f32_e32 v1, v211, v33
	v_pk_add_f32 v[32:33], v[16:17], v[8:9] op_sel:[0,1] op_sel_hi:[1,0] neg_lo:[0,0] neg_hi:[0,1]
	v_pk_add_f32 v[8:9], v[16:17], v[8:9] op_sel:[1,0] op_sel_hi:[0,1] neg_lo:[0,0] neg_hi:[0,1]
	v_add_f32_e32 v16, v196, v26
	v_add_f32_e32 v17, v206, v18
	v_sub_f32_e32 v26, v196, v26
	v_sub_f32_e32 v18, v206, v18
	v_add_f32_e32 v196, v2, v19
	v_add_f32_e32 v206, v3, v10
	v_sub_f32_e32 v2, v2, v19
	v_sub_f32_e32 v3, v3, v10
	ds_write_b64 v142, v[28:29]
	ds_write_b64 v141, v[0:1] offset:4096
	v_add_f32_e32 v10, v16, v196
	v_add_f32_e32 v19, v17, v206
	v_sub_f32_e32 v16, v16, v196
	v_sub_f32_e32 v17, v17, v206
	v_add_f32_e32 v196, v26, v3
	v_sub_f32_e32 v206, v18, v2
	v_sub_f32_e32 v26, v26, v3
	v_add_f32_e32 v18, v18, v2
	v_pk_add_f32 v[2:3], v[30:31], v[12:13] op_sel:[0,1] op_sel_hi:[1,0]
	v_pk_add_f32 v[12:13], v[30:31], v[12:13] op_sel:[1,0] op_sel_hi:[0,1] neg_lo:[0,1] neg_hi:[0,1]
	v_add_f32_e32 v30, v11, v21
	v_add_f32_e32 v31, v20, v4
	v_sub_f32_e32 v11, v11, v21
	v_sub_f32_e32 v4, v20, v4
	v_mul_f32_e32 v0, v194, v132
	v_mul_f32_e32 v1, v194, v134
	s_nop 0
	v_pk_add_f32 v[20:21], v[2:3], v[30:31] op_sel:[0,0] op_sel_hi:[1,1]
	v_pk_add_f32 v[30:31], v[2:3], v[30:31] op_sel:[0,0] op_sel_hi:[1,1] neg_lo:[0,1] neg_hi:[0,1]
	v_add_f32_e32 v207, v13, v4
	v_sub_f32_e32 v211, v12, v11
	v_sub_f32_e32 v4, v13, v4
	v_add_f32_e32 v11, v12, v11
	v_add_f32_e32 v2, v22, v15
	v_add_f32_e32 v3, v23, v6
	v_sub_f32_e32 v12, v22, v15
	v_add_f32_e32 v13, v5, v7
	v_add_f32_e32 v15, v14, v27
	v_sub_f32_e32 v5, v5, v7
	v_sub_f32_e32 v7, v14, v27
	v_fma_f32 v0, -v195, v134, v0
	v_fma_f32 v1, v195, v132, v1
	s_nop 0
	v_add_f32_e32 v14, v2, v13
	v_add_f32_e32 v22, v3, v15
	v_sub_f32_e32 v13, v2, v13
	v_sub_f32_e32 v15, v3, v15
	v_mul_f32_e32 v2, v10, v132
	v_mul_f32_e32 v3, v10, v134
	v_sub_f32_e32 v6, v23, v6
	v_add_f32_e32 v23, v12, v7
	v_fma_f32 v45, -v125, v125, v35
	v_mul_f32_e32 v35, v124, v125
	s_nop 0
	v_fma_f32 v2, -v19, v134, v2
	v_fma_f32 v3, v19, v132, v3
	ds_write_b64 v142, v[0:1] offset:32
	ds_write_b64 v141, v[2:3] offset:4128
	v_pk_mul_f32 v[0:1], v[202:203], v[130:131] op_sel:[0,0] op_sel_hi:[0,1]
	v_pk_mul_f32 v[2:3], v[20:21], v[130:131] op_sel:[0,0] op_sel_hi:[0,1]
	v_sub_f32_e32 v27, v6, v5
	v_fma_f32 v46, v125, v124, v35
	s_nop 0
	v_pk_fma_f32 v[0:1], v[202:203], v[130:131], v[0:1] op_sel:[1,1,0] op_sel_hi:[1,0,1] neg_lo:[1,0,0] neg_hi:[0,0,0]
	v_pk_fma_f32 v[2:3], v[20:21], v[130:131], v[2:3] op_sel:[1,1,0] op_sel_hi:[1,0,1] neg_lo:[1,0,0] neg_hi:[0,0,0]
	ds_write_b64 v142, v[0:1] offset:64
	ds_write_b64 v141, v[2:3] offset:4160
	v_pk_mul_f32 v[0:1], v[208:209], v[128:129] op_sel:[0,0] op_sel_hi:[0,1]
	v_pk_mul_f32 v[2:3], v[14:15], v[128:129] op_sel:[0,0] op_sel_hi:[0,1]
	v_mul_f32_e32 v35, v49, v128
	v_fma_f32 v36, v82, v120, v36
	s_nop 0
	v_pk_fma_f32 v[0:1], v[208:209], v[128:129], v[0:1] op_sel:[1,1,0] op_sel_hi:[1,0,1] neg_lo:[1,0,0] neg_hi:[0,0,0]
	v_pk_fma_f32 v[2:3], v[22:23], v[128:129], v[2:3] op_sel:[0,1,0] op_sel_hi:[0,0,1] neg_lo:[1,0,0] neg_hi:[0,0,0]
	ds_write_b64 v142, v[0:1] offset:96
	ds_write_b64 v141, v[2:3] offset:4192
	v_pk_mul_f32 v[0:1], v[200:201], v[126:127] op_sel:[0,0] op_sel_hi:[0,1]
	v_pk_mul_f32 v[2:3], v[32:33], v[126:127] op_sel:[0,0] op_sel_hi:[0,1]
	v_fma_f32 v43, -v82, v129, v35
	v_mul_f32_e32 v35, v49, v129
	s_nop 0
	v_pk_fma_f32 v[0:1], v[200:201], v[126:127], v[0:1] op_sel:[1,1,0] op_sel_hi:[1,0,1] neg_lo:[1,0,0] neg_hi:[0,0,0]
	v_pk_fma_f32 v[2:3], v[32:33], v[126:127], v[2:3] op_sel:[1,1,0] op_sel_hi:[1,0,1] neg_lo:[1,0,0] neg_hi:[0,0,0]
	ds_write_b64 v142, v[0:1] offset:128
	ds_write_b64 v141, v[2:3] offset:4224
	v_pk_mul_f32 v[0:1], v[196:197], v[124:125] op_sel:[1,0] op_sel_hi:[1,1]
	v_pk_mul_f32 v[2:3], v[196:197], v[124:125] op_sel:[0,0] op_sel_hi:[0,1]
	v_fma_f32 v44, v82, v128, v35
	v_mul_f32_e32 v35, v122, v122
	s_nop 0
	v_pk_fma_f32 v[0:1], v[198:199], v[124:125], v[0:1] op_sel:[0,1,0] op_sel_hi:[0,0,1] neg_lo:[1,0,0] neg_hi:[0,0,0]
	v_pk_fma_f32 v[2:3], v[206:207], v[124:125], v[2:3] op_sel:[0,1,0] op_sel_hi:[0,0,1] neg_lo:[1,0,0] neg_hi:[0,0,0]
	ds_write_b64 v142, v[0:1] offset:160
	ds_write_b64 v141, v[2:3] offset:4256
	v_pk_mul_f32 v[0:1], v[204:205], v[122:123] op_sel:[0,0] op_sel_hi:[0,1]
	v_pk_mul_f32 v[2:3], v[206:207], v[122:123] op_sel:[1,0] op_sel_hi:[1,1]
	v_fma_f32 v41, -v123, v123, v35
	v_mul_f32_e32 v35, v122, v123
	s_nop 0
	v_pk_fma_f32 v[0:1], v[204:205], v[122:123], v[0:1] op_sel:[1,1,0] op_sel_hi:[1,0,1] neg_lo:[1,0,0] neg_hi:[0,0,0]
	v_pk_fma_f32 v[2:3], v[210:211], v[122:123], v[2:3] op_sel:[1,1,0] op_sel_hi:[1,0,1] neg_lo:[1,0,0] neg_hi:[0,0,0]
	ds_write_b64 v142, v[0:1] offset:192
	ds_write_b64 v141, v[2:3] offset:4288
	v_pk_mul_f32 v[0:1], v[198:199], v[120:121] op_sel:[1,0] op_sel_hi:[1,1]
	v_pk_mul_f32 v[2:3], v[22:23], v[120:121] op_sel:[1,0] op_sel_hi:[1,1]
	v_fma_f32 v42, v123, v122, v35
	v_mul_f32_e32 v35, v49, v124
	s_nop 0
	v_pk_fma_f32 v[0:1], v[210:211], v[120:121], v[0:1] op_sel:[0,1,0] op_sel_hi:[0,0,1] neg_lo:[1,0,0] neg_hi:[0,0,0]
	v_pk_fma_f32 v[2:3], v[26:27], v[120:121], v[2:3] op_sel:[1,1,0] op_sel_hi:[1,0,1] neg_lo:[1,0,0] neg_hi:[0,0,0]
	ds_write_b64 v142, v[0:1] offset:224
	ds_write_b64 v141, v[2:3] offset:4320
	v_mul_f32_e32 v0, v186, v49
	v_mul_f32_e32 v1, v186, v82
	v_mul_f32_e32 v2, v24, v49
	v_mul_f32_e32 v3, v24, v82
	v_fma_f32 v39, -v82, v125, v35
	v_mul_f32_e32 v35, v49, v125
	s_nop 0
	v_fma_f32 v0, -v187, v82, v0
	v_fma_f32 v1, v187, v49, v1
	v_fma_f32 v2, -v25, v82, v2
	v_fma_f32 v3, v25, v49, v3
	ds_write_b64 v142, v[0:1] offset:256
	ds_write_b64 v141, v[2:3] offset:4352
	v_mul_f32_e32 v0, v188, v47
	v_mul_f32_e32 v1, v188, v48
	v_mul_f32_e32 v2, v16, v47
	v_mul_f32_e32 v3, v16, v48
	v_fma_f32 v40, v82, v124, v35
	v_mul_f32_e32 v35, v120, v120
	s_nop 0
	v_fma_f32 v0, -v189, v48, v0
	v_fma_f32 v1, v189, v47, v1
	v_fma_f32 v2, -v17, v48, v2
	v_fma_f32 v3, v17, v47, v3
	ds_write_b64 v142, v[0:1] offset:288
	ds_write_b64 v141, v[2:3] offset:4384
	v_mul_f32_e32 v0, v190, v45
	v_mul_f32_e32 v1, v190, v46
	v_mul_f32_e32 v2, v30, v45
	v_mul_f32_e32 v3, v30, v46
	v_fma_f32 v37, -v121, v121, v35
	v_mul_f32_e32 v35, v120, v121
	s_nop 0
	v_fma_f32 v0, -v191, v46, v0
	v_fma_f32 v1, v191, v45, v1
	v_fma_f32 v2, -v31, v46, v2
	v_fma_f32 v3, v31, v45, v3
	ds_write_b64 v142, v[0:1] offset:320
	ds_write_b64 v141, v[2:3] offset:4416
	v_mul_f32_e32 v0, v192, v43
	v_mul_f32_e32 v1, v192, v44
	v_mul_f32_e32 v2, v13, v43
	v_mul_f32_e32 v3, v13, v44
	v_fma_f32 v38, v121, v120, v35
	v_mul_f32_e32 v35, v49, v120
	s_nop 0
	v_fma_f32 v0, -v193, v44, v0
	v_fma_f32 v1, v193, v43, v1
	v_fma_f32 v2, -v15, v44, v2
	v_fma_f32 v3, v15, v43, v3
	ds_write_b64 v142, v[0:1] offset:352
	ds_write_b64 v141, v[2:3] offset:4448
	v_mul_f32_e32 v0, v178, v41
	v_mul_f32_e32 v1, v178, v42
	v_mul_f32_e32 v2, v9, v41
	v_mul_f32_e32 v3, v9, v42
	v_lshl_add_u64 v[14:15], s[50:51], 0, v[86:87]
	v_fma_f32 v0, -v179, v42, v0
	v_fma_f32 v1, v179, v41, v1
	v_fma_f32 v2, -v8, v42, v2
	v_fma_f32 v3, v8, v41, v3
	ds_write_b64 v142, v[0:1] offset:384
	ds_write_b64 v141, v[2:3] offset:4480
	v_mul_f32_e32 v0, v180, v39
	v_mul_f32_e32 v1, v180, v40
	v_mul_f32_e32 v2, v26, v39
	v_mul_f32_e32 v3, v26, v40
	v_div_scale_f32 v26, s[0:1], v34, v34, 1.0
	v_fma_f32 v0, -v181, v40, v0
	v_fma_f32 v1, v181, v39, v1
	v_fma_f32 v2, -v18, v40, v2
	v_fma_f32 v3, v18, v39, v3
	ds_write_b64 v142, v[0:1] offset:416
	ds_write_b64 v141, v[2:3] offset:4512
	v_mul_f32_e32 v0, v182, v37
	v_mul_f32_e32 v1, v182, v38
	v_rcp_f32_e32 v27, v26
	v_fma_f32 v0, -v183, v38, v0
	v_fma_f32 v1, v183, v37, v1
	v_mul_f32_e32 v2, v4, v37
	v_mul_f32_e32 v3, v4, v38
	v_add_co_u32_e32 v24, vcc, s83, v14
	v_fma_f32 v35, -v82, v121, v35
	v_fma_f32 v2, -v11, v38, v2
	v_fma_f32 v3, v11, v37, v3
	ds_write_b64 v142, v[0:1] offset:448
	ds_write_b64 v141, v[2:3] offset:4544
	v_mul_f32_e32 v0, v184, v35
	v_mul_f32_e32 v1, v184, v36
	v_lshl_add_u64 v[8:9], s[52:53], 0, v[86:87]
	v_addc_co_u32_e32 v25, vcc, 0, v15, vcc
	v_sub_f32_e32 v7, v12, v7
	v_fma_f32 v0, -v185, v36, v0
	v_fma_f32 v1, v185, v35, v1
	v_add_co_u32_e32 v22, vcc, s83, v8
	v_mul_f32_e32 v2, v7, v35
	v_mul_f32_e32 v3, v7, v36
	v_add_f32_e32 v5, v6, v5
	s_lshl_b64 s[0:1], s[48:49], 2
	v_fma_f32 v2, -v5, v36, v2
	v_fma_f32 v3, v5, v35, v3
	ds_write_b64 v142, v[0:1] offset:480
	ds_write_b64 v141, v[2:3] offset:4576
	v_addc_co_u32_e32 v23, vcc, 0, v9, vcc
	v_fma_f32 v0, -v26, v27, 1.0
	v_fmac_f32_e32 v27, v0, v27
	v_div_scale_f32 v28, vcc, 1.0, v34, 1.0
	v_mul_f32_e32 v29, v28, v27
	v_fma_f32 v0, -v26, v29, v28
	v_fmac_f32_e32 v29, v0, v27
	ds_read_b128 v[0:3], v162
	ds_read_b128 v[4:7], v162 offset:16
	v_fma_f32 v26, -v26, v29, v28
	v_div_fmas_f32 v26, v26, v27, v29
	v_div_fixup_f32 v82, v26, v34, 1.0
	s_waitcnt lgkmcnt(0)
	v_pk_add_f32 v[26:27], v[0:1], v[4:5] op_sel:[0,0] op_sel_hi:[1,1]
	v_pk_add_f32 v[4:5], v[0:1], v[4:5] op_sel:[0,0] op_sel_hi:[1,1] neg_lo:[0,1] neg_hi:[0,1]
	v_pk_add_f32 v[28:29], v[2:3], v[6:7] op_sel:[0,0] op_sel_hi:[1,1]
	v_pk_add_f32 v[6:7], v[2:3], v[6:7] op_sel:[0,0] op_sel_hi:[1,1] neg_lo:[0,1] neg_hi:[0,1]
	s_add_u32 s30, s16, s0
	v_pk_add_f32 v[0:1], v[26:27], v[28:29] op_sel:[0,0] op_sel_hi:[1,1]
	v_pk_add_f32 v[2:3], v[4:5], v[6:7] op_sel:[0,1] op_sel_hi:[1,0] neg_lo:[0,0] neg_hi:[0,1]
	v_pk_add_f32 v[26:27], v[26:27], v[28:29] op_sel:[0,0] op_sel_hi:[1,1] neg_lo:[0,1] neg_hi:[0,1]
	s_nop 0
	v_pk_mul_f32 v[0:1], v[82:83], v[0:1] op_sel_hi:[0,1]
	v_pk_mul_f32 v[2:3], v[82:83], v[2:3] op_sel_hi:[0,1]
	v_pk_add_f32 v[28:29], v[4:5], v[6:7] op_sel:[0,1] op_sel_hi:[1,0] neg_lo:[0,1] neg_hi:[0,0]
	v_cvt_pk_f16_f32 v193, v0, v1
	v_cvt_pk_f16_f32 v190, v2, v3
	ds_read_b128 v[0:3], v163
	ds_read_b128 v[4:7], v163 offset:16
	v_pk_mul_f32 v[28:29], v[82:83], v[28:29] op_sel_hi:[0,1]
	v_pk_mul_f32 v[26:27], v[82:83], v[26:27] op_sel_hi:[0,1]
	v_cvt_pk_f16_f32 v195, v26, v27
	v_cvt_pk_f16_f32 v192, v28, v29
	s_waitcnt lgkmcnt(0)
	v_pk_add_f32 v[26:27], v[0:1], v[4:5] op_sel:[0,0] op_sel_hi:[1,1]
	v_pk_add_f32 v[4:5], v[0:1], v[4:5] op_sel:[0,0] op_sel_hi:[1,1] neg_lo:[0,1] neg_hi:[0,1]
	v_pk_add_f32 v[28:29], v[2:3], v[6:7] op_sel:[0,0] op_sel_hi:[1,1]
	v_pk_add_f32 v[6:7], v[2:3], v[6:7] op_sel:[0,0] op_sel_hi:[1,1] neg_lo:[0,1] neg_hi:[0,1]
	s_addc_u32 s31, s17, s1
	v_pk_add_f32 v[0:1], v[26:27], v[28:29] op_sel:[0,0] op_sel_hi:[1,1]
	v_pk_add_f32 v[2:3], v[4:5], v[6:7] op_sel:[0,1] op_sel_hi:[1,0] neg_lo:[0,0] neg_hi:[0,1]
	v_pk_add_f32 v[26:27], v[26:27], v[28:29] op_sel:[0,0] op_sel_hi:[1,1] neg_lo:[0,1] neg_hi:[0,1]
	s_nop 0
	v_pk_mul_f32 v[0:1], v[82:83], v[0:1] op_sel_hi:[0,1]
	v_pk_mul_f32 v[2:3], v[82:83], v[2:3] op_sel_hi:[0,1]
	v_pk_add_f32 v[28:29], v[4:5], v[6:7] op_sel:[0,1] op_sel_hi:[1,0] neg_lo:[0,1] neg_hi:[0,0]
	v_cvt_pk_f16_f32 v188, v0, v1
	v_cvt_pk_f16_f32 v186, v2, v3
	ds_read_b128 v[0:3], v164
	ds_read_b128 v[4:7], v164 offset:16
	v_pk_mul_f32 v[28:29], v[82:83], v[28:29] op_sel_hi:[0,1]
	v_pk_mul_f32 v[26:27], v[82:83], v[26:27] op_sel_hi:[0,1]
	v_cvt_pk_f16_f32 v189, v26, v27
	v_cvt_pk_f16_f32 v187, v28, v29
	s_waitcnt lgkmcnt(0)
	v_pk_add_f32 v[26:27], v[0:1], v[4:5] op_sel:[0,0] op_sel_hi:[1,1]
	v_pk_add_f32 v[4:5], v[0:1], v[4:5] op_sel:[0,0] op_sel_hi:[1,1] neg_lo:[0,1] neg_hi:[0,1]
	v_pk_add_f32 v[28:29], v[2:3], v[6:7] op_sel:[0,0] op_sel_hi:[1,1]
	v_pk_add_f32 v[6:7], v[2:3], v[6:7] op_sel:[0,0] op_sel_hi:[1,1] neg_lo:[0,1] neg_hi:[0,1]
	s_add_u32 s48, s42, s26
	v_pk_add_f32 v[0:1], v[26:27], v[28:29] op_sel:[0,0] op_sel_hi:[1,1]
	v_pk_add_f32 v[2:3], v[4:5], v[6:7] op_sel:[0,1] op_sel_hi:[1,0] neg_lo:[0,0] neg_hi:[0,1]
	v_pk_add_f32 v[26:27], v[26:27], v[28:29] op_sel:[0,0] op_sel_hi:[1,1] neg_lo:[0,1] neg_hi:[0,1]
	s_nop 0
	v_pk_mul_f32 v[0:1], v[82:83], v[0:1] op_sel_hi:[0,1]
	v_pk_mul_f32 v[2:3], v[82:83], v[2:3] op_sel_hi:[0,1]
	v_pk_add_f32 v[28:29], v[4:5], v[6:7] op_sel:[0,1] op_sel_hi:[1,0] neg_lo:[0,1] neg_hi:[0,0]
	v_cvt_pk_f16_f32 v184, v0, v1
	v_cvt_pk_f16_f32 v182, v2, v3
	ds_read_b128 v[0:3], v165
	ds_read_b128 v[4:7], v165 offset:16
	v_pk_mul_f32 v[28:29], v[82:83], v[28:29] op_sel_hi:[0,1]
	v_pk_mul_f32 v[26:27], v[82:83], v[26:27] op_sel_hi:[0,1]
	v_cvt_pk_f16_f32 v185, v26, v27
	v_cvt_pk_f16_f32 v183, v28, v29
	s_waitcnt lgkmcnt(0)
	v_pk_add_f32 v[26:27], v[0:1], v[4:5] op_sel:[0,0] op_sel_hi:[1,1]
	v_pk_add_f32 v[28:29], v[0:1], v[4:5] op_sel:[0,0] op_sel_hi:[1,1] neg_lo:[0,1] neg_hi:[0,1]
	v_pk_add_f32 v[4:5], v[2:3], v[6:7] op_sel:[0,0] op_sel_hi:[1,1]
	v_sub_f32_e32 v30, v2, v6
	v_sub_f32_e32 v6, v3, v7
	v_lshl_add_u64 v[12:13], s[50:51], 0, v[110:111]
	v_pk_add_f32 v[0:1], v[26:27], v[4:5] op_sel:[0,0] op_sel_hi:[1,1]
	v_pk_add_f32 v[2:3], v[26:27], v[4:5] op_sel:[0,0] op_sel_hi:[1,1] neg_lo:[0,1] neg_hi:[0,1]
	v_add_f32_e32 v4, v28, v6
	v_sub_f32_e32 v5, v29, v30
	v_sub_f32_e32 v6, v28, v6
	v_add_f32_e32 v7, v29, v30
	ds_read_b128 v[26:29], v166
	ds_read_b128 v[30:33], v166 offset:16
	v_pk_mul_f32 v[0:1], v[82:83], v[0:1] op_sel_hi:[0,1]
	v_lshl_add_u64 v[10:11], s[52:53], 0, v[110:111]
	v_lshl_add_u64 v[38:39], s[50:51], 0, v[112:113]
	v_lshl_add_u64 v[18:19], s[50:51], 0, v[98:99]
	v_lshl_add_u64 v[16:17], s[50:51], 0, v[114:115]
	v_lshl_add_u64 v[20:21], s[52:53], 0, v[98:99]
	v_pk_mul_f32 v[4:5], v[82:83], v[4:5] op_sel_hi:[0,1]
	v_cvt_pk_f16_f32 v180, v0, v1
	v_pk_mul_f32 v[0:1], v[82:83], v[6:7] op_sel_hi:[0,1]
	v_pk_mul_f32 v[2:3], v[82:83], v[2:3] op_sel_hi:[0,1]
	s_addc_u32 s49, s43, s27
	v_lshl_add_u64 v[122:123], s[52:53], 0, v[112:113]
	v_lshl_add_u64 v[120:121], s[52:53], 0, v[114:115]
	v_lshl_add_u64 v[128:129], s[50:51], 0, v[116:117]
	v_lshl_add_u64 v[130:131], s[50:51], 0, v[118:119]
	v_lshl_add_u64 v[124:125], s[52:53], 0, v[116:117]
	v_lshl_add_u64 v[126:127], s[52:53], 0, v[118:119]
	v_cvt_pk_f16_f32 v178, v4, v5
	v_cvt_pk_f16_f32 v181, v2, v3
	v_cvt_pk_f16_f32 v179, v0, v1
	s_waitcnt lgkmcnt(0)
	v_add_f32_e32 v191, v26, v30
	v_add_f32_e32 v194, v27, v31
	v_pk_add_f32 v[208:209], v[26:27], v[30:31] op_sel:[0,0] op_sel_hi:[1,1] neg_lo:[0,1] neg_hi:[0,1]
	v_add_f32_e32 v30, v28, v32
	v_sub_f32_e32 v210, v28, v32
	ds_read_b128 v[34:37], v167
	ds_read_b128 v[42:45], v167 offset:16
	ds_read_b128 v[196:199], v168
	ds_read_b128 v[200:203], v168 offset:16
	ds_read_b128 v[0:3], v169
	ds_read_b128 v[4:7], v169 offset:16
	global_load_dwordx4 v[24:27], v[24:25], off nt
	s_nop 0
	global_load_ushort v211, v159, s[50:51] offset:-2
	global_load_ushort v213, v159, s[52:53] offset:-2
	global_load_ushort v214, v[38:39], off offset:16
	s_nop 0
	global_load_dwordx4 v[38:41], v[14:15], off nt
	global_load_ushort v215, v158, s[50:51] offset:-2
	global_load_ushort v216, v158, s[52:53] offset:-2
	global_load_ushort v217, v[12:13], off offset:16
	global_load_dwordx4 v[46:49], v[22:23], off nt
	global_load_ushort v218, v[122:123], off offset:16
	global_load_dwordx4 v[204:207], v[8:9], off nt
	global_load_ushort v219, v[10:11], off offset:16
	s_nop 0
	global_load_dwordx4 v[8:11], v[128:129], off nt
	global_load_ushort v220, v161, s[50:51] offset:-2
	global_load_ushort v221, v161, s[52:53] offset:-2
	global_load_ushort v222, v[130:131], off offset:16
	global_load_dwordx4 v[12:15], v[18:19], off nt
	global_load_ushort v223, v160, s[50:51] offset:-2
	global_load_ushort v224, v160, s[52:53] offset:-2
	global_load_ushort v225, v[16:17], off offset:16
	s_nop 0
	global_load_dwordx4 v[16:19], v[124:125], off nt
	global_load_ushort v226, v[126:127], off offset:16
	s_nop 0
	global_load_dwordx4 v[20:23], v[20:21], off nt
	s_nop 0
	global_load_ushort v227, v[120:121], off offset:16
	s_waitcnt lgkmcnt(0)
	s_barrier
	v_mov_b32_e32 v28, 0x4000
	s_add_u32 s0, s18, s0
	global_load_dword v124, v28, s[48:49]
	s_addc_u32 s1, s19, s1
	global_load_dword v120, v83, s[30:31]
	global_load_dword v126, v83, s[0:1]
	v_mov_b32_e32 v28, 0x7000
	s_lshl_b64 s[0:1], s[46:47], 2
	global_load_dword v122, v28, s[48:49]
	global_load_dword v128, v172, s[48:49]
	global_load_dword v132, v173, s[48:49]
	global_load_dword v130, v174, s[48:49]
	s_add_u32 s0, s18, s0
	s_addc_u32 s1, s19, s1
	global_load_dword v134, v83, s[0:1]
	v_add_f32_e32 v31, v29, v33
	v_sub_f32_e32 v121, v29, v33
	v_add_f32_e32 v28, v191, v30
	v_sub_f32_e32 v30, v191, v30
	v_sub_f32_e32 v33, v209, v210
	v_add_f32_e32 v209, v209, v210
	s_nop 0
	v_add_f32_e32 v29, v194, v31
	v_sub_f32_e32 v31, v194, v31
	v_add_f32_e32 v32, v208, v121
	v_sub_f32_e32 v208, v208, v121
	s_add_i32 s52, s44, s22
	v_pk_mul_f32 v[28:29], v[82:83], v[28:29] op_sel_hi:[0,1]
	v_pk_mul_f32 v[32:33], v[82:83], v[32:33] op_sel_hi:[0,1]
	v_cvt_pk_f16_f32 v194, v28, v29
	v_pk_mul_f32 v[28:29], v[82:83], v[208:209] op_sel_hi:[0,1]
	v_pk_mul_f32 v[30:31], v[82:83], v[30:31] op_sel_hi:[0,1]
	v_cvt_pk_f16_f32 v191, v32, v33
	v_cvt_pk_f16_f32 v131, v30, v31
	v_cvt_pk_f16_f32 v129, v28, v29
	s_waitcnt lgkmcnt(0)
	v_pk_add_f32 v[30:31], v[34:35], v[42:43] op_sel:[0,0] op_sel_hi:[1,1]
	v_pk_add_f32 v[32:33], v[36:37], v[44:45] op_sel:[0,0] op_sel_hi:[1,1]
	v_pk_add_f32 v[34:35], v[34:35], v[42:43] op_sel:[0,0] op_sel_hi:[1,1] neg_lo:[0,1] neg_hi:[0,1]
	v_pk_add_f32 v[36:37], v[36:37], v[44:45] op_sel:[0,0] op_sel_hi:[1,1] neg_lo:[0,1] neg_hi:[0,1]
	s_nop 0
	v_pk_add_f32 v[28:29], v[30:31], v[32:33] op_sel:[0,0] op_sel_hi:[1,1]
	v_pk_add_f32 v[30:31], v[30:31], v[32:33] op_sel:[0,0] op_sel_hi:[1,1] neg_lo:[0,1] neg_hi:[0,1]
	v_pk_add_f32 v[32:33], v[34:35], v[36:37] op_sel:[0,1] op_sel_hi:[1,0] neg_lo:[0,0] neg_hi:[0,1]
	s_nop 0
	v_pk_mul_f32 v[28:29], v[82:83], v[28:29] op_sel_hi:[0,1]
	v_pk_add_f32 v[34:35], v[34:35], v[36:37] op_sel:[0,1] op_sel_hi:[1,0] neg_lo:[0,1] neg_hi:[0,0]
	v_cvt_pk_f16_f32 v127, v28, v29
	v_pk_mul_f32 v[28:29], v[82:83], v[34:35] op_sel_hi:[0,1]
	v_pk_mul_f32 v[30:31], v[82:83], v[30:31] op_sel_hi:[0,1]
	v_pk_mul_f32 v[32:33], v[82:83], v[32:33] op_sel_hi:[0,1]
	v_cvt_pk_f16_f32 v123, v30, v31
	v_cvt_pk_f16_f32 v121, v28, v29
	v_pk_add_f32 v[28:29], v[196:197], v[200:201] op_sel:[0,0] op_sel_hi:[1,1]
	v_pk_add_f32 v[30:31], v[196:197], v[200:201] op_sel:[0,0] op_sel_hi:[1,1] neg_lo:[0,1] neg_hi:[0,1]
	v_pk_add_f32 v[34:35], v[198:199], v[202:203] op_sel:[0,0] op_sel_hi:[1,1]
	v_pk_add_f32 v[36:37], v[198:199], v[202:203] op_sel:[0,0] op_sel_hi:[1,1] neg_lo:[0,1] neg_hi:[0,1]
	v_cvt_pk_f16_f32 v125, v32, v33
	v_pk_add_f32 v[32:33], v[28:29], v[34:35] op_sel:[0,0] op_sel_hi:[1,1]
	v_pk_add_f32 v[28:29], v[28:29], v[34:35] op_sel:[0,0] op_sel_hi:[1,1] neg_lo:[0,1] neg_hi:[0,1]
	v_pk_add_f32 v[34:35], v[30:31], v[36:37] op_sel:[0,1] op_sel_hi:[1,0] neg_lo:[0,0] neg_hi:[0,1]
	v_pk_add_f32 v[30:31], v[30:31], v[36:37] op_sel:[0,1] op_sel_hi:[1,0] neg_lo:[0,1] neg_hi:[0,0]
	s_waitcnt vmcnt(0)
	v_lshlrev_b32_e32 v37, 16, v24
	v_lshlrev_b32_e32 v36, 16, v38
	v_and_b32_e32 v197, 0xffff0000, v24
	v_and_b32_e32 v196, 0xffff0000, v38
	v_lshlrev_b32_e32 v24, 16, v215
	v_lshlrev_b32_e32 v38, 16, v211
	v_lshlrev_b32_e32 v45, 16, v46
	v_lshlrev_b32_e32 v44, 16, v204
	v_cndmask_b32_e64 v43, 0, v38, s[12:13]
	v_cndmask_b32_e64 v42, 0, v24, s[12:13]
	v_pk_mul_f32 v[200:201], v[124:125], v[36:37] op_sel_hi:[0,1]
	v_lshlrev_b32_e32 v24, 16, v216
	v_lshlrev_b32_e32 v38, 16, v213
	v_pk_fma_f32 v[42:43], v[42:43], v[120:121], v[200:201] op_sel_hi:[1,0,1]
	v_cndmask_b32_e64 v201, 0, v38, s[12:13]
	v_cndmask_b32_e64 v200, 0, v24, s[12:13]
	v_pk_mul_f32 v[202:203], v[132:133], v[44:45] op_sel_hi:[0,1]
	v_and_b32_e32 v199, 0xffff0000, v46
	v_and_b32_e32 v198, 0xffff0000, v204
	v_pk_fma_f32 v[200:201], v[200:201], v[128:129], v[202:203] op_sel_hi:[1,0,1]
	v_pk_fma_f32 v[42:43], v[122:123], v[196:197], v[42:43] op_sel_hi:[0,1,1]
	v_pk_fma_f32 v[200:201], v[130:131], v[198:199], v[200:201] op_sel_hi:[0,1,1]
	v_pk_mul_f32 v[208:209], v[124:125], v[196:197] op_sel_hi:[0,1]
	v_pk_add_f32 v[42:43], v[126:127], v[42:43] op_sel_hi:[0,1]
	v_pk_add_f32 v[200:201], v[134:135], v[200:201] op_sel_hi:[0,1]
	v_pk_fma_f32 v[36:37], v[120:121], v[36:37], v[208:209] op_sel_hi:[0,1,1]
	v_pk_mul_f32 v[208:209], v[132:133], v[198:199] op_sel_hi:[0,1]
	v_pk_mul_f32 v[42:43], v[42:43], v[200:201]
	v_lshlrev_b32_e32 v201, 16, v25
	v_lshlrev_b32_e32 v200, 16, v39
	v_lshlrev_b32_e32 v203, 16, v47
	v_lshlrev_b32_e32 v202, 16, v205
	v_pk_fma_f32 v[44:45], v[128:129], v[44:45], v[208:209] op_sel_hi:[0,1,1]
	v_pk_fma_f32 v[36:37], v[122:123], v[200:201], v[36:37] op_sel_hi:[0,1,1]
	v_pk_fma_f32 v[44:45], v[130:131], v[202:203], v[44:45] op_sel_hi:[0,1,1]
	v_pk_add_f32 v[36:37], v[126:127], v[36:37] op_sel_hi:[0,1]
	v_pk_add_f32 v[44:45], v[134:135], v[44:45] op_sel_hi:[0,1]
	v_and_b32_e32 v25, 0xffff0000, v25
	v_and_b32_e32 v24, 0xffff0000, v39
	v_pk_mul_f32 v[44:45], v[36:37], v[44:45]
	v_pk_mul_f32 v[36:37], v[124:125], v[24:25] op_sel_hi:[0,1]
	ds_write_b128 v145, v[42:45]
	v_lshlrev_b32_e32 v45, 16, v26
	v_lshlrev_b32_e32 v44, 16, v40
	v_pk_fma_f32 v[36:37], v[120:121], v[200:201], v[36:37] op_sel_hi:[0,1,1]
	v_and_b32_e32 v43, 0xffff0000, v47
	v_and_b32_e32 v42, 0xffff0000, v205
	v_pk_mul_f32 v[38:39], v[124:125], v[200:201] op_sel_hi:[0,1]
	v_pk_fma_f32 v[36:37], v[122:123], v[44:45], v[36:37] op_sel_hi:[0,1,1]
	v_pk_fma_f32 v[38:39], v[120:121], v[196:197], v[38:39] op_sel_hi:[0,1,1]
	v_pk_add_f32 v[196:197], v[126:127], v[36:37] op_sel_hi:[0,1]
	v_pk_mul_f32 v[36:37], v[132:133], v[42:43] op_sel_hi:[0,1]
	v_pk_mul_f32 v[200:201], v[132:133], v[202:203] op_sel_hi:[0,1]
	v_lshlrev_b32_e32 v47, 16, v48
	v_lshlrev_b32_e32 v46, 16, v206
	v_pk_fma_f32 v[36:37], v[128:129], v[202:203], v[36:37] op_sel_hi:[0,1,1]
	v_pk_fma_f32 v[198:199], v[128:129], v[198:199], v[200:201] op_sel_hi:[0,1,1]
	v_pk_fma_f32 v[38:39], v[122:123], v[24:25], v[38:39] op_sel_hi:[0,1,1]
	v_pk_fma_f32 v[198:199], v[130:131], v[42:43], v[198:199] op_sel_hi:[0,1,1]
	v_pk_fma_f32 v[36:37], v[130:131], v[46:47], v[36:37] op_sel_hi:[0,1,1]
	v_pk_add_f32 v[38:39], v[126:127], v[38:39] op_sel_hi:[0,1]
	v_pk_add_f32 v[198:199], v[134:135], v[198:199] op_sel_hi:[0,1]
	v_pk_add_f32 v[200:201], v[134:135], v[36:37] op_sel_hi:[0,1]
	v_pk_mul_f32 v[36:37], v[38:39], v[198:199]
	v_pk_mul_f32 v[38:39], v[196:197], v[200:201]
	v_and_b32_e32 v197, 0xffff0000, v26
	v_and_b32_e32 v196, 0xffff0000, v40
	ds_write_b128 v145, v[36:39] offset:16
	v_pk_mul_f32 v[36:37], v[124:125], v[196:197] op_sel_hi:[0,1]
	v_lshlrev_b32_e32 v201, 16, v27
	v_lshlrev_b32_e32 v200, 16, v41
	v_pk_fma_f32 v[36:37], v[120:121], v[44:45], v[36:37] op_sel_hi:[0,1,1]
	v_and_b32_e32 v199, 0xffff0000, v48
	v_and_b32_e32 v198, 0xffff0000, v206
	v_pk_mul_f32 v[38:39], v[124:125], v[44:45] op_sel_hi:[0,1]
	v_pk_fma_f32 v[36:37], v[122:123], v[200:201], v[36:37] op_sel_hi:[0,1,1]
	v_pk_fma_f32 v[24:25], v[120:121], v[24:25], v[38:39] op_sel_hi:[0,1,1]
	v_pk_add_f32 v[38:39], v[126:127], v[36:37] op_sel_hi:[0,1]
	v_pk_mul_f32 v[36:37], v[132:133], v[198:199] op_sel_hi:[0,1]
	v_pk_mul_f32 v[44:45], v[132:133], v[46:47] op_sel_hi:[0,1]
	v_lshlrev_b32_e32 v203, 16, v49
	v_lshlrev_b32_e32 v202, 16, v207
	v_pk_fma_f32 v[36:37], v[128:129], v[46:47], v[36:37] op_sel_hi:[0,1,1]
	v_pk_fma_f32 v[42:43], v[128:129], v[42:43], v[44:45] op_sel_hi:[0,1,1]
	v_pk_fma_f32 v[24:25], v[122:123], v[196:197], v[24:25] op_sel_hi:[0,1,1]
	v_pk_fma_f32 v[42:43], v[130:131], v[198:199], v[42:43] op_sel_hi:[0,1,1]
	v_pk_fma_f32 v[36:37], v[130:131], v[202:203], v[36:37] op_sel_hi:[0,1,1]
	v_pk_add_f32 v[24:25], v[126:127], v[24:25] op_sel_hi:[0,1]
	v_pk_add_f32 v[42:43], v[134:135], v[42:43] op_sel_hi:[0,1]
	v_pk_add_f32 v[44:45], v[134:135], v[36:37] op_sel_hi:[0,1]
	v_pk_mul_f32 v[36:37], v[24:25], v[42:43]
	v_pk_mul_f32 v[38:39], v[38:39], v[44:45]
	ds_write_b128 v145, v[36:39] offset:32
	v_pk_mul_f32 v[24:25], v[124:125], v[200:201] op_sel_hi:[0,1]
	v_pk_mul_f32 v[38:39], v[132:133], v[202:203] op_sel_hi:[0,1]
	v_and_b32_e32 v27, 0xffff0000, v27
	v_and_b32_e32 v26, 0xffff0000, v41
	v_and_b32_e32 v37, 0xffff0000, v49
	v_and_b32_e32 v36, 0xffff0000, v207
	v_pk_fma_f32 v[24:25], v[120:121], v[196:197], v[24:25] op_sel_hi:[0,1,1]
	v_pk_fma_f32 v[38:39], v[128:129], v[198:199], v[38:39] op_sel_hi:[0,1,1]
	v_pk_fma_f32 v[24:25], v[122:123], v[26:27], v[24:25] op_sel_hi:[0,1,1]
	v_pk_fma_f32 v[38:39], v[130:131], v[36:37], v[38:39] op_sel_hi:[0,1,1]
	v_pk_add_f32 v[24:25], v[126:127], v[24:25] op_sel_hi:[0,1]
	v_pk_add_f32 v[38:39], v[134:135], v[38:39] op_sel_hi:[0,1]
	v_pk_mul_f32 v[24:25], v[24:25], v[38:39]
	v_lshlrev_b32_e32 v38, 16, v217
	v_lshlrev_b32_e32 v39, 16, v214
	v_lshlrev_b32_e32 v40, 16, v219
	v_lshlrev_b32_e32 v41, 16, v218
	v_pk_mul_f32 v[26:27], v[124:125], v[26:27] op_sel_hi:[0,1]
	v_pk_mul_f32 v[36:37], v[132:133], v[36:37] op_sel_hi:[0,1]
	v_cndmask_b32_e64 v39, 0, v39, s[4:5]
	v_cndmask_b32_e64 v38, 0, v38, s[4:5]
	v_cndmask_b32_e64 v41, 0, v41, s[4:5]
	v_cndmask_b32_e64 v40, 0, v40, s[4:5]
	v_pk_fma_f32 v[26:27], v[120:121], v[200:201], v[26:27] op_sel_hi:[0,1,1]
	v_pk_fma_f32 v[36:37], v[128:129], v[202:203], v[36:37] op_sel_hi:[0,1,1]
	v_pk_fma_f32 v[26:27], v[38:39], v[122:123], v[26:27] op_sel_hi:[1,0,1]
	v_pk_fma_f32 v[36:37], v[40:41], v[130:131], v[36:37] op_sel_hi:[1,0,1]
	v_pk_add_f32 v[26:27], v[126:127], v[26:27] op_sel_hi:[0,1]
	v_pk_add_f32 v[36:37], v[134:135], v[36:37] op_sel_hi:[0,1]
	v_pk_mul_f32 v[26:27], v[26:27], v[36:37]
	ds_write_b128 v145, v[24:27] offset:48
	v_lshlrev_b32_e32 v27, 16, v8
	v_lshlrev_b32_e32 v26, 16, v12
	v_and_b32_e32 v37, 0xffff0000, v8
	v_and_b32_e32 v36, 0xffff0000, v12
	v_lshlrev_b32_e32 v8, 16, v223
	v_lshlrev_b32_e32 v12, 16, v220
	v_lshlrev_b32_e32 v39, 16, v16
	v_lshlrev_b32_e32 v38, 16, v20
	v_cndmask_b32_e64 v25, 0, v12, s[6:7]
	v_cndmask_b32_e64 v24, 0, v8, s[6:7]
	v_pk_mul_f32 v[42:43], v[124:125], v[26:27] op_sel_hi:[0,1]
	v_lshlrev_b32_e32 v8, 16, v224
	v_lshlrev_b32_e32 v12, 16, v221
	v_pk_fma_f32 v[24:25], v[24:25], v[120:121], v[42:43] op_sel_hi:[1,0,1]
	v_cndmask_b32_e64 v43, 0, v12, s[6:7]
	v_cndmask_b32_e64 v42, 0, v8, s[6:7]
	v_pk_mul_f32 v[44:45], v[132:133], v[38:39] op_sel_hi:[0,1]
	v_and_b32_e32 v41, 0xffff0000, v16
	v_and_b32_e32 v40, 0xffff0000, v20
	v_pk_fma_f32 v[42:43], v[42:43], v[128:129], v[44:45] op_sel_hi:[1,0,1]
	v_pk_fma_f32 v[24:25], v[122:123], v[36:37], v[24:25] op_sel_hi:[0,1,1]
	v_pk_fma_f32 v[42:43], v[130:131], v[40:41], v[42:43] op_sel_hi:[0,1,1]
	v_pk_mul_f32 v[46:47], v[124:125], v[36:37] op_sel_hi:[0,1]
	v_pk_add_f32 v[24:25], v[126:127], v[24:25] op_sel_hi:[0,1]
	v_pk_add_f32 v[42:43], v[134:135], v[42:43] op_sel_hi:[0,1]
	v_pk_fma_f32 v[26:27], v[120:121], v[26:27], v[46:47] op_sel_hi:[0,1,1]
	v_pk_mul_f32 v[46:47], v[132:133], v[40:41] op_sel_hi:[0,1]
	v_pk_mul_f32 v[24:25], v[24:25], v[42:43]
	v_lshlrev_b32_e32 v43, 16, v9
	v_lshlrev_b32_e32 v42, 16, v13
	v_lshlrev_b32_e32 v45, 16, v17
	v_lshlrev_b32_e32 v44, 16, v21
	v_pk_fma_f32 v[38:39], v[128:129], v[38:39], v[46:47] op_sel_hi:[0,1,1]
	v_pk_fma_f32 v[26:27], v[122:123], v[42:43], v[26:27] op_sel_hi:[0,1,1]
	v_pk_fma_f32 v[38:39], v[130:131], v[44:45], v[38:39] op_sel_hi:[0,1,1]
	v_pk_add_f32 v[26:27], v[126:127], v[26:27] op_sel_hi:[0,1]
	v_pk_add_f32 v[38:39], v[134:135], v[38:39] op_sel_hi:[0,1]
	v_pk_mul_f32 v[26:27], v[26:27], v[38:39]
	v_and_b32_e32 v9, 0xffff0000, v9
	v_and_b32_e32 v8, 0xffff0000, v13
	ds_write_b128 v146, v[24:27] offset:32768
	v_pk_mul_f32 v[24:25], v[124:125], v[8:9] op_sel_hi:[0,1]
	v_and_b32_e32 v13, 0xffff0000, v17
	v_lshlrev_b32_e32 v17, 16, v10
	v_lshlrev_b32_e32 v16, 16, v14
	v_pk_fma_f32 v[24:25], v[120:121], v[42:43], v[24:25] op_sel_hi:[0,1,1]
	v_and_b32_e32 v12, 0xffff0000, v21
	v_pk_mul_f32 v[26:27], v[124:125], v[42:43] op_sel_hi:[0,1]
	v_pk_fma_f32 v[24:25], v[122:123], v[16:17], v[24:25] op_sel_hi:[0,1,1]
	v_pk_fma_f32 v[26:27], v[120:121], v[36:37], v[26:27] op_sel_hi:[0,1,1]
	v_pk_add_f32 v[36:37], v[126:127], v[24:25] op_sel_hi:[0,1]
	v_pk_mul_f32 v[24:25], v[132:133], v[12:13] op_sel_hi:[0,1]
	v_pk_mul_f32 v[38:39], v[132:133], v[44:45] op_sel_hi:[0,1]
	v_lshlrev_b32_e32 v21, 16, v18
	v_lshlrev_b32_e32 v20, 16, v22
	v_pk_fma_f32 v[24:25], v[128:129], v[44:45], v[24:25] op_sel_hi:[0,1,1]
	v_pk_fma_f32 v[38:39], v[128:129], v[40:41], v[38:39] op_sel_hi:[0,1,1]
	v_pk_fma_f32 v[26:27], v[122:123], v[8:9], v[26:27] op_sel_hi:[0,1,1]
	v_pk_fma_f32 v[38:39], v[130:131], v[12:13], v[38:39] op_sel_hi:[0,1,1]
	v_pk_fma_f32 v[24:25], v[130:131], v[20:21], v[24:25] op_sel_hi:[0,1,1]
	v_pk_add_f32 v[26:27], v[126:127], v[26:27] op_sel_hi:[0,1]
	v_pk_add_f32 v[38:39], v[134:135], v[38:39] op_sel_hi:[0,1]
	v_pk_add_f32 v[40:41], v[134:135], v[24:25] op_sel_hi:[0,1]
	v_pk_mul_f32 v[24:25], v[26:27], v[38:39]
	v_pk_mul_f32 v[26:27], v[36:37], v[40:41]
	ds_write_b128 v146, v[24:27] offset:32784
	v_pk_mul_f32 v[26:27], v[124:125], v[16:17] op_sel_hi:[0,1]
	v_pk_fma_f32 v[8:9], v[120:121], v[8:9], v[26:27] op_sel_hi:[0,1,1]
	v_pk_mul_f32 v[26:27], v[132:133], v[20:21] op_sel_hi:[0,1]
	v_and_b32_e32 v37, 0xffff0000, v10
	v_and_b32_e32 v36, 0xffff0000, v14
	v_and_b32_e32 v39, 0xffff0000, v18
	v_and_b32_e32 v38, 0xffff0000, v22
	v_pk_fma_f32 v[12:13], v[128:129], v[12:13], v[26:27] op_sel_hi:[0,1,1]
	v_pk_mul_f32 v[24:25], v[124:125], v[36:37] op_sel_hi:[0,1]
	v_pk_fma_f32 v[8:9], v[122:123], v[36:37], v[8:9] op_sel_hi:[0,1,1]
	v_pk_fma_f32 v[12:13], v[130:131], v[38:39], v[12:13] op_sel_hi:[0,1,1]
	v_lshlrev_b32_e32 v41, 16, v11
	v_lshlrev_b32_e32 v40, 16, v15
	v_lshlrev_b32_e32 v43, 16, v19
	v_lshlrev_b32_e32 v42, 16, v23
	v_pk_fma_f32 v[16:17], v[120:121], v[16:17], v[24:25] op_sel_hi:[0,1,1]
	v_pk_add_f32 v[8:9], v[126:127], v[8:9] op_sel_hi:[0,1]
	v_pk_mul_f32 v[24:25], v[132:133], v[38:39] op_sel_hi:[0,1]
	v_pk_add_f32 v[12:13], v[134:135], v[12:13] op_sel_hi:[0,1]
	v_pk_fma_f32 v[20:21], v[128:129], v[20:21], v[24:25] op_sel_hi:[0,1,1]
	v_pk_mul_f32 v[24:25], v[8:9], v[12:13]
	v_and_b32_e32 v10, 0xffff0000, v15
	v_pk_mul_f32 v[8:9], v[124:125], v[40:41] op_sel_hi:[0,1]
	v_pk_mul_f32 v[14:15], v[132:133], v[42:43] op_sel_hi:[0,1]
	v_and_b32_e32 v11, 0xffff0000, v11
	v_and_b32_e32 v13, 0xffff0000, v19
	v_and_b32_e32 v12, 0xffff0000, v23
	v_pk_fma_f32 v[8:9], v[120:121], v[36:37], v[8:9] op_sel_hi:[0,1,1]
	v_pk_fma_f32 v[14:15], v[128:129], v[38:39], v[14:15] op_sel_hi:[0,1,1]
	v_pk_fma_f32 v[16:17], v[122:123], v[40:41], v[16:17] op_sel_hi:[0,1,1]
	v_pk_fma_f32 v[20:21], v[130:131], v[42:43], v[20:21] op_sel_hi:[0,1,1]
	v_pk_fma_f32 v[8:9], v[122:123], v[10:11], v[8:9] op_sel_hi:[0,1,1]
	v_pk_fma_f32 v[14:15], v[130:131], v[12:13], v[14:15] op_sel_hi:[0,1,1]
	v_pk_add_f32 v[16:17], v[126:127], v[16:17] op_sel_hi:[0,1]
	v_pk_add_f32 v[20:21], v[134:135], v[20:21] op_sel_hi:[0,1]
	v_pk_add_f32 v[8:9], v[126:127], v[8:9] op_sel_hi:[0,1]
	v_pk_add_f32 v[14:15], v[134:135], v[14:15] op_sel_hi:[0,1]
	v_pk_mul_f32 v[26:27], v[16:17], v[20:21]
	v_pk_mul_f32 v[8:9], v[8:9], v[14:15]
	v_lshlrev_b32_e32 v14, 16, v225
	v_lshlrev_b32_e32 v15, 16, v222
	v_lshlrev_b32_e32 v16, 16, v227
	v_lshlrev_b32_e32 v17, 16, v226
	v_pk_mul_f32 v[10:11], v[124:125], v[10:11] op_sel_hi:[0,1]
	v_pk_mul_f32 v[12:13], v[132:133], v[12:13] op_sel_hi:[0,1]
	v_cndmask_b32_e64 v15, 0, v15, s[8:9]
	v_cndmask_b32_e64 v14, 0, v14, s[8:9]
	v_cndmask_b32_e64 v17, 0, v17, s[8:9]
	v_cndmask_b32_e64 v16, 0, v16, s[8:9]
	v_pk_fma_f32 v[10:11], v[120:121], v[40:41], v[10:11] op_sel_hi:[0,1,1]
	v_pk_fma_f32 v[12:13], v[128:129], v[42:43], v[12:13] op_sel_hi:[0,1,1]
	s_cmpk_lt_i32 s52, 0x400
	v_pk_fma_f32 v[10:11], v[14:15], v[122:123], v[10:11] op_sel_hi:[1,0,1]
	v_pk_fma_f32 v[12:13], v[16:17], v[130:131], v[12:13] op_sel_hi:[1,0,1]
	s_cselect_b64 s[46:47], -1, 0
	v_pk_add_f32 v[10:11], v[126:127], v[10:11] op_sel_hi:[0,1]
	v_pk_add_f32 v[12:13], v[134:135], v[12:13] op_sel_hi:[0,1]
	s_and_b64 s[0:1], s[46:47], exec
	v_pk_mul_f32 v[10:11], v[10:11], v[12:13]
	s_cselect_b32 s50, s52, s44
	ds_write_b128 v146, v[24:27] offset:32800
	ds_write_b128 v146, v[8:11] offset:32816
	v_mov_b32_e32 v27, v92
	s_add_i32 s44, s50, 0x400
	s_waitcnt lgkmcnt(0)
	s_barrier
	v_mov_b32_e32 v8, s44
	v_mov_b32_e32 v9, s50
	v_cmp_gt_i32_e32 vcc, s86, v27
	v_mov_b32_e32 v10, s29
	s_ashr_i32 s51, s50, 31
	v_cndmask_b32_e32 v8, v8, v9, vcc
	v_ashrrev_i32_e32 v9, 31, v8
	v_lshlrev_b64 v[8:9], 14, v[8:9]
	v_lshl_add_u64 v[8:9], s[14:15], 0, v[8:9]
	v_cmp_gt_i32_e32 vcc, s63, v27
	s_ashr_i32 s45, s44, 31
	s_lshl_b64 s[0:1], s[50:51], 14
	v_cndmask_b32_e32 v9, v9, v10, vcc
	v_mov_b32_e32 v10, s28
	v_cndmask_b32_e32 v8, v8, v10, vcc
	v_and_b32_e32 v10, 0x7f, v27
	v_cndmask_b32_e32 v10, v10, v27, vcc
	v_ashrrev_i32_e32 v11, 31, v10
	v_lshlrev_b64 v[10:11], 7, v[10:11]
	v_lshl_add_u64 v[8:9], v[8:9], 0, v[10:11]
	global_load_lds_dword v[8:9], off
	v_add_u32_e32 v8, 0x200, v27
	v_ashrrev_i32_e32 v9, 31, v27
	v_lshrrev_b32_e32 v9, 22, v9
	v_ashrrev_i32_e32 v10, 31, v8
	v_add_u32_e32 v9, v27, v9
	v_lshrrev_b32_e32 v10, 22, v10
	v_ashrrev_i32_e32 v36, 10, v9
	v_add_u32_e32 v10, v8, v10
	v_mad_i32_i24 v9, v36, s64, v27
	v_ashrrev_i32_e32 v10, 10, v10
	v_mul_i32_i24_e32 v11, 0x3c00, v10
	v_mad_i32_i24 v8, v10, s64, v8
	v_ashrrev_i32_e32 v10, 4, v9
	v_lshlrev_b32_e32 v10, 3, v10
	v_ashrrev_i32_e32 v8, 4, v8
	v_and_b32_e32 v10, 0xffffffe0, v10
	v_lshlrev_b32_e32 v9, 3, v9
	v_lshlrev_b32_e32 v8, 3, v8
	v_add3_u32 v10, 0, v10, v9
	v_and_b32_e32 v8, 0xffffffe0, v8
	v_add_lshl_u32 v9, v11, v27, 3
	v_add3_u32 v26, 0, v8, v9
	ds_read_b64 v[24:25], v10
	ds_read_b64 v[20:21], v26 offset:4096
	ds_read_b64 v[202:203], v10 offset:8704
	ds_read_b64 v[16:17], v26 offset:12800
	ds_read_b64 v[204:205], v10 offset:17408
	ds_read_b64 v[12:13], v26 offset:21504
	ds_read_b64 v[206:207], v10 offset:26112
	ds_read_b64 v[8:9], v26 offset:30208
	ds_read_b64 v[214:215], v10 offset:34816
	ds_read_b64 v[22:23], v26 offset:38912
	ds_read_b64 v[216:217], v10 offset:43520
	ds_read_b64 v[18:19], v26 offset:47616
	ds_read_b64 v[218:219], v10 offset:52224
	ds_read_b64 v[14:15], v26 offset:56320
	ds_read_b64 v[220:221], v10 offset:60928
	ds_read_b64 v[10:11], v26 offset:65024
	s_waitcnt lgkmcnt(0)
	v_add_f32_e32 v200, v25, v215
	v_pk_add_f32 v[222:223], v[24:25], v[214:215] op_sel:[0,0] op_sel_hi:[1,1] neg_lo:[0,1] neg_hi:[0,1]
	v_pk_add_f32 v[224:225], v[24:25], v[214:215] op_sel:[0,1] op_sel_hi:[1,0] neg_lo:[0,0] neg_hi:[0,1]
	v_pk_add_f32 v[226:227], v[24:25], v[214:215] op_sel:[0,1] op_sel_hi:[1,0] neg_lo:[0,1] neg_hi:[0,0]
	v_add_f32_e32 v199, v24, v214
	v_pk_add_f32 v[24:25], v[202:203], v[216:217] op_sel:[0,0] op_sel_hi:[1,1]
	v_sub_f32_e32 v213, v202, v216
	v_pk_add_f32 v[214:215], v[202:203], v[216:217] op_sel:[1,1] op_sel_hi:[0,1] neg_lo:[0,1] neg_hi:[0,0]
	v_sub_f32_e32 v228, v203, v216
	v_pk_add_f32 v[202:203], v[202:203], v[216:217] op_sel:[0,1] op_sel_hi:[1,0] neg_lo:[0,1] neg_hi:[0,0]
	v_pk_add_f32 v[216:217], v[204:205], v[218:219] op_sel:[0,0] op_sel_hi:[1,1]
	v_sub_f32_e32 v229, v204, v218
	v_pk_add_f32 v[230:231], v[204:205], v[218:219] op_sel:[1,1] op_sel_hi:[0,1] neg_lo:[0,1] neg_hi:[0,0]
	v_sub_f32_e32 v232, v205, v218
	v_pk_add_f32 v[204:205], v[204:205], v[218:219] op_sel:[0,1] op_sel_hi:[1,0] neg_lo:[0,1] neg_hi:[0,0]
	v_pk_add_f32 v[218:219], v[206:207], v[220:221] op_sel:[0,0] op_sel_hi:[1,1]
	v_sub_f32_e32 v233, v206, v220
	v_pk_add_f32 v[234:235], v[206:207], v[220:221] op_sel:[1,1] op_sel_hi:[0,1] neg_lo:[0,1] neg_hi:[0,0]
	v_sub_f32_e32 v236, v207, v220
	v_pk_add_f32 v[206:207], v[206:207], v[220:221] op_sel:[0,1] op_sel_hi:[1,0] neg_lo:[0,1] neg_hi:[0,0]
	s_nop 0
	v_mul_f32_e32 v220, v215, v152
	v_mul_f32_e32 v215, v215, v153
	v_mul_f32_e32 v221, v231, v154
	v_xor_b32_e32 v229, 0x80000000, v229
	v_fma_f32 v220, -v228, v153, v220
	v_fma_f32 v215, v228, v152, v215
	v_mul_f32_e32 v228, v231, v155
	v_fma_f32 v221, -v232, v155, v221
	v_mul_f32_e32 v231, v235, v156
	v_sub_f32_e32 v244, v17, v18
	v_sub_f32_e32 v245, v12, v14
	s_nop 0
	v_fma_f32 v228, v232, v154, v228
	v_mul_f32_e32 v232, v235, v157
	v_mul_f32_e32 v235, v213, v154
	v_mul_f32_e32 v213, v213, v155
	v_fma_f32 v231, -v236, v157, v231
	v_pk_add_f32 v[246:247], v[12:13], v[14:15] op_sel:[1,1] op_sel_hi:[0,1] neg_lo:[0,1] neg_hi:[0,0]
	v_sub_f32_e32 v248, v13, v14
	s_nop 0
	v_fma_f32 v232, v236, v156, v232
	v_fma_f32 v235, -v214, v155, v235
	v_fma_f32 v236, v214, v154, v213
	v_mul_f32_e32 v213, v233, v155
	v_sub_f32_e32 v249, v8, v10
	v_pk_add_f32 v[250:251], v[8:9], v[10:11] op_sel:[1,1] op_sel_hi:[0,1] neg_lo:[0,1] neg_hi:[0,0]
	v_sub_f32_e32 v252, v9, v10
	v_mul_i32_i24_e32 v37, 0x400, v36
	v_fma_f32 v233, -v234, v155, v213
	v_fma_f32 v234, v234, v155, v213
	v_mul_f32_e32 v213, v202, v156
	v_mul_f32_e32 v202, v202, v157
	v_sub_u32_e32 v27, v27, v37
	v_fma_f32 v238, v203, v156, v202
	v_mul_f32_e32 v202, v204, v155
	v_fma_f32 v237, -v203, v157, v213
	v_add_f32_e32 v203, v200, v217
	v_sub_f32_e32 v200, v200, v217
	v_sub_f32_e32 v217, v220, v231
	s_nop 0
	v_fma_f32 v239, -v205, v155, v202
	v_fma_f32 v240, v205, v155, v202
	v_mul_f32_e32 v202, v206, v157
	v_pk_add_f32 v[204:205], v[24:25], v[218:219] op_sel:[0,0] op_sel_hi:[1,1]
	v_cvt_f32_i32_e32 v37, v27
	v_fma_f32 v241, -v207, v156, v202
	v_mul_f32_e32 v202, v206, v156
	v_sub_f32_e32 v214, v203, v205
	v_lshl_add_u32 v27, v36, 14, v27
	v_fma_f32 v206, v207, v157, v202
	v_add_f32_e32 v202, v199, v216
	v_sub_f32_e32 v199, v199, v216
	v_sub_f32_e32 v207, v24, v218
	v_sub_f32_e32 v216, v25, v219
	v_pk_add_f32 v[24:25], v[202:203], v[204:205] op_sel:[0,0] op_sel_hi:[1,1]
	v_add_f32_e32 v203, v225, v228
	s_nop 0
	v_sub_f32_e32 v213, v202, v204
	v_sub_f32_e32 v243, v200, v207
	v_add_f32_e32 v242, v199, v216
	v_sub_f32_e32 v199, v199, v216
	v_add_f32_e32 v200, v200, v207
	v_add_f32_e32 v202, v224, v221
	v_sub_f32_e32 v204, v224, v221
	v_sub_f32_e32 v205, v225, v228
	v_add_f32_e32 v207, v220, v231
	v_add_f32_e32 v216, v215, v232
	v_sub_f32_e32 v218, v215, v232
	v_sub_f32_e32 v219, v223, v229
	v_sub_f32_e32 v220, v235, v233
	s_nop 0
	v_sub_f32_e32 v228, v205, v217
	v_add_f32_e32 v221, v202, v207
	v_add_f32_e32 v224, v203, v216
	v_sub_f32_e32 v215, v202, v207
	v_sub_f32_e32 v216, v203, v216
	v_add_f32_e32 v225, v204, v218
	v_sub_f32_e32 v202, v204, v218
	v_add_f32_e32 v203, v205, v217
	v_add_f32_e32 v204, v222, v230
	v_add_f32_e32 v205, v223, v229
	v_sub_f32_e32 v207, v222, v230
	v_add_f32_e32 v217, v235, v233
	v_add_f32_e32 v218, v236, v234
	v_sub_f32_e32 v222, v236, v234
	v_sub_f32_e32 v231, v219, v220
	v_sub_f32_e32 v232, v237, v241
	v_sub_f32_e32 v236, v21, v23
	s_nop 0
	v_add_f32_e32 v223, v204, v217
	v_add_f32_e32 v229, v205, v218
	v_sub_f32_e32 v217, v204, v217
	v_sub_f32_e32 v218, v205, v218
	v_add_f32_e32 v230, v207, v222
	v_sub_f32_e32 v204, v207, v222
	v_add_f32_e32 v205, v219, v220
	v_add_f32_e32 v207, v226, v239
	v_add_f32_e32 v220, v227, v240
	v_sub_f32_e32 v222, v226, v239
	v_sub_f32_e32 v226, v227, v240
	v_add_f32_e32 v219, v237, v241
	v_add_f32_e32 v227, v238, v206
	v_sub_f32_e32 v206, v238, v206
	v_add_f32_e32 v237, v20, v23
	v_sub_f32_e32 v238, v21, v22
	s_nop 0
	v_sub_f32_e32 v235, v226, v232
	v_add_f32_e32 v233, v207, v219
	v_add_f32_e32 v234, v220, v227
	v_sub_f32_e32 v219, v207, v219
	v_sub_f32_e32 v220, v220, v227
	v_add_f32_e32 v227, v222, v206
	v_sub_f32_e32 v206, v222, v206
	v_add_f32_e32 v207, v226, v232
	v_add_f32_e32 v222, v20, v22
	v_add_f32_e32 v226, v21, v23
	v_sub_f32_e32 v232, v20, v22
	v_pk_add_f32 v[20:21], v[20:21], v[22:23] op_sel:[0,1] op_sel_hi:[1,0] neg_lo:[0,1] neg_hi:[0,0]
	v_pk_add_f32 v[22:23], v[16:17], v[18:19] op_sel:[0,0] op_sel_hi:[1,1]
	v_sub_f32_e32 v239, v16, v18
	v_pk_add_f32 v[240:241], v[16:17], v[18:19] op_sel:[1,1] op_sel_hi:[0,1] neg_lo:[0,1] neg_hi:[0,0]
	v_pk_add_f32 v[16:17], v[16:17], v[18:19] op_sel:[0,1] op_sel_hi:[1,0] neg_lo:[0,1] neg_hi:[0,0]
	v_pk_add_f32 v[18:19], v[12:13], v[14:15] op_sel:[0,0] op_sel_hi:[1,1]
	v_pk_add_f32 v[12:13], v[12:13], v[14:15] op_sel:[0,1] op_sel_hi:[1,0] neg_lo:[0,1] neg_hi:[0,0]
	v_pk_add_f32 v[14:15], v[8:9], v[10:11] op_sel:[0,0] op_sel_hi:[1,1]
	v_pk_add_f32 v[8:9], v[8:9], v[10:11] op_sel:[0,1] op_sel_hi:[1,0] neg_lo:[0,1] neg_hi:[0,0]
	s_nop 0
	v_pk_mul_f32 v[10:11], v[240:241], v[152:153] op_sel:[1,0] op_sel_hi:[1,1]
	v_mul_f32_e32 v241, v247, v154
	v_mul_f32_e32 v12, v12, v155
	v_add_f32_e32 v253, v222, v18
	v_add_f32_e32 v254, v226, v19
	s_nop 0
	v_pk_fma_f32 v[10:11], v[244:245], v[152:153], v[10:11] op_sel:[0,1,0] op_sel_hi:[0,0,1] neg_lo:[1,0,0] neg_hi:[0,0,0]
	v_mul_f32_e32 v244, v247, v155
	v_fma_f32 v241, -v248, v155, v241
	v_mul_f32_e32 v247, v251, v156
	v_sub_f32_e32 v18, v222, v18
	v_sub_f32_e32 v19, v226, v19
	v_add_f32_e32 v222, v22, v14
	s_nop 0
	v_fma_f32 v244, v248, v154, v244
	v_mul_f32_e32 v248, v251, v157
	v_mul_f32_e32 v251, v239, v154
	v_mul_f32_e32 v239, v239, v155
	v_add_f32_e32 v226, v23, v15
	v_pk_add_f32 v[14:15], v[22:23], v[14:15] op_sel:[0,0] op_sel_hi:[1,1] neg_lo:[0,1] neg_hi:[0,1]
	v_ashrrev_i32_e32 v36, 4, v27
	v_fma_f32 v251, -v240, v155, v251
	v_fma_f32 v239, v240, v154, v239
	v_xor_b32_e32 v240, 0x80000000, v245
	v_mul_f32_e32 v245, v249, v155
	v_fma_f32 v247, -v252, v157, v247
	v_fma_f32 v248, v252, v156, v248
	v_sub_f32_e32 v22, v253, v222
	v_sub_f32_e32 v23, v254, v226
	v_lshlrev_b32_e32 v36, 3, v36
	v_fma_f32 v249, -v250, v155, v245
	v_fma_f32 v245, v250, v155, v245
	v_mul_f32_e32 v250, v16, v156
	v_mul_f32_e32 v16, v16, v157
	v_mul_f32_e32 v37, 0x38800000, v37
	v_fma_f32 v250, -v17, v157, v250
	v_fma_f32 v16, v17, v156, v16
	v_fma_f32 v17, -v13, v155, v12
	v_fma_f32 v12, v13, v155, v12
	v_mul_f32_e32 v13, v8, v157
	v_mul_f32_e32 v8, v8, v156
	v_and_b32_e32 v36, 0xffffffe0, v36
	v_fma_f32 v13, -v9, v156, v13
	v_fma_f32 v252, v9, v157, v8
	v_add_f32_e32 v8, v253, v222
	v_add_f32_e32 v9, v254, v226
	v_add_f32_e32 v222, v18, v15
	v_sub_f32_e32 v226, v19, v14
	v_pk_add_f32 v[14:15], v[18:19], v[14:15] op_sel:[1,0] op_sel_hi:[0,1] neg_lo:[0,0] neg_hi:[0,1]
	v_add_f32_e32 v18, v237, v241
	v_add_f32_e32 v19, v238, v244
	v_sub_f32_e32 v237, v237, v241
	v_sub_f32_e32 v238, v238, v244
	v_add_f32_e32 v241, v10, v247
	v_add_f32_e32 v244, v11, v248
	v_sub_f32_e32 v10, v10, v247
	v_sub_f32_e32 v11, v11, v248
	v_lshlrev_b32_e32 v27, 3, v27
	v_add_f32_e32 v247, v18, v241
	v_add_f32_e32 v248, v19, v244
	v_sub_f32_e32 v18, v18, v241
	v_sub_f32_e32 v19, v19, v244
	v_add_f32_e32 v241, v237, v11
	v_sub_f32_e32 v244, v238, v10
	v_sub_f32_e32 v237, v237, v11
	v_add_f32_e32 v238, v238, v10
	v_add_f32_e32 v10, v232, v246
	v_add_f32_e32 v11, v236, v240
	v_sub_f32_e32 v232, v232, v246
	v_sub_f32_e32 v236, v236, v240
	v_add_f32_e32 v240, v251, v249
	v_add_f32_e32 v246, v239, v245
	v_sub_f32_e32 v249, v251, v249
	v_sub_f32_e32 v239, v239, v245
	v_sin_f32_e32 v38, v37
	v_add_f32_e32 v245, v10, v240
	v_add_f32_e32 v251, v11, v246
	v_sub_f32_e32 v240, v10, v240
	v_sub_f32_e32 v246, v11, v246
	v_add_f32_e32 v10, v20, v17
	v_add_f32_e32 v11, v21, v12
	v_sub_f32_e32 v17, v20, v17
	v_sub_f32_e32 v12, v21, v12
	v_add_f32_e32 v20, v250, v13
	v_add_f32_e32 v21, v16, v252
	v_cos_f32_e32 v210, v37
	v_add3_u32 v27, 0, v36, v27
	v_add_f32_e32 v253, v232, v239
	v_sub_f32_e32 v254, v236, v249
	v_sub_f32_e32 v232, v232, v239
	v_add_f32_e32 v236, v236, v249
	v_sub_f32_e32 v13, v250, v13
	v_add_f32_e32 v239, v10, v20
	v_add_f32_e32 v249, v11, v21
	v_pk_add_f32 v[20:21], v[10:11], v[20:21] op_sel:[0,0] op_sel_hi:[1,1] neg_lo:[0,1] neg_hi:[0,1]
	v_mul_f32_e32 v10, s71, v247
	v_mul_f32_e32 v11, s72, v247
	s_nop 1
	v_sub_f32_e32 v16, v16, v252
	s_nop 0
	v_sub_f32_e32 v252, v12, v13
	v_add_f32_e32 v12, v12, v13
	ds_write_b64 v27, v[24:25]
	ds_write_b64 v26, v[8:9] offset:4096
	v_xor_b32_e32 v211, 0x80000000, v38
	v_pk_mul_f32 v[8:9], v[220:221], v[210:211] op_sel:[1,0] op_sel_hi:[1,1]
	v_fma_f32 v13, -v248, s72, v10
	v_fma_f32 v11, v248, s71, v11
	v_mul_f32_e32 v36, v210, v210
	v_add_f32_e32 v250, v17, v16
	s_nop 0
	v_pk_fma_f32 v[8:9], v[224:225], v[210:211], v[8:9] op_sel:[0,1,0] op_sel_hi:[0,0,1] neg_lo:[1,0,0] neg_hi:[0,0,0]
	v_mul_f32_e32 v10, v13, v210
	v_mul_f32_e32 v13, v13, v211
	v_fma_f32 v208, -v211, v211, v36
	v_mul_f32_e32 v36, v210, v211
	v_sub_f32_e32 v16, v17, v16
	s_lshl_b64 s[28:29], s[44:45], 14
	v_fma_f32 v10, -v11, v211, v10
	v_fma_f32 v11, v11, v210, v13
	ds_write_b64 v27, v[8:9] offset:8704
	ds_write_b64 v26, v[10:11] offset:12800
	v_mul_f32_e32 v10, s65, v245
	v_mul_f32_e32 v11, s66, v245
	v_fma_f32 v209, v211, v210, v36
	v_mul_f32_e32 v36, v208, v210
	s_add_u32 s44, s14, s28
	v_pk_mul_f32 v[8:9], v[222:223], v[208:209] op_sel:[1,0] op_sel_hi:[1,1]
	v_fma_f32 v13, -v251, s66, v10
	v_fma_f32 v11, v251, s65, v11
	v_fma_f32 v198, -v209, v211, v36
	v_mul_f32_e32 v36, v208, v211
	s_nop 0
	v_pk_fma_f32 v[8:9], v[228:229], v[208:209], v[8:9] op_sel:[1,1,0] op_sel_hi:[1,0,1] neg_lo:[1,0,0] neg_hi:[0,0,0]
	v_mul_f32_e32 v10, v13, v208
	v_mul_f32_e32 v13, v13, v209
	s_addc_u32 s45, s15, s29
	v_fma_f32 v10, -v11, v209, v10
	v_fma_f32 v11, v11, v208, v13
	ds_write_b64 v27, v[8:9] offset:17408
	ds_write_b64 v26, v[10:11] offset:21504
	v_mul_f32_e32 v10, s73, v239
	v_mul_f32_e32 v11, s74, v239
	v_fma_f32 v201, v209, v210, v36
	v_mul_f32_e32 v8, v233, v198
	v_mul_f32_e32 v36, v208, v208
	s_nop 0
	v_mul_f32_e32 v9, v233, v201
	v_fma_f32 v13, -v249, s74, v10
	v_fma_f32 v11, v249, s73, v11
	v_fma_f32 v8, -v234, v201, v8
	v_fma_f32 v196, -v209, v209, v36
	v_mul_f32_e32 v36, v208, v209
	s_nop 0
	v_fma_f32 v9, v234, v198, v9
	v_mul_f32_e32 v10, v13, v198
	v_mul_f32_e32 v13, v13, v201
	s_nop 0
	v_fma_f32 v10, -v11, v201, v10
	v_fma_f32 v11, v11, v198, v13
	ds_write_b64 v27, v[8:9] offset:26112
	ds_write_b64 v26, v[10:11] offset:30208
	v_mul_f32_e32 v10, s67, v222
	v_mul_f32_e32 v11, s68, v222
	v_fma_f32 v197, v209, v208, v36
	v_mul_f32_e32 v36, v196, v210
	s_nop 0
	v_pk_mul_f32 v[8:9], v[242:243], v[196:197] op_sel:[0,0] op_sel_hi:[0,1]
	v_fma_f32 v13, -v226, s68, v10
	v_fma_f32 v11, v226, s67, v11
	v_fma_f32 v132, -v197, v211, v36
	v_mul_f32_e32 v36, v196, v211
	s_nop 0
	v_pk_fma_f32 v[8:9], v[242:243], v[196:197], v[8:9] op_sel:[1,1,0] op_sel_hi:[1,0,1] neg_lo:[1,0,0] neg_hi:[0,0,0]
	v_mul_f32_e32 v10, v13, v196
	v_mul_f32_e32 v13, v13, v197
	s_nop 0
	v_fma_f32 v10, -v11, v197, v10
	v_fma_f32 v11, v11, v196, v13
	ds_write_b64 v27, v[8:9] offset:34816
	ds_write_b64 v26, v[10:11] offset:38912
	v_mul_f32_e32 v10, s75, v241
	v_mul_f32_e32 v11, s76, v241
	v_fma_f32 v134, v197, v210, v36
	v_mul_f32_e32 v8, v225, v132
	v_mul_f32_e32 v36, v198, v198
	s_nop 0
	v_mul_f32_e32 v9, v225, v134
	v_fma_f32 v13, -v244, s76, v10
	v_fma_f32 v11, v244, s75, v11
	v_fma_f32 v8, -v228, v134, v8
	v_fma_f32 v128, -v201, v201, v36
	v_mul_f32_e32 v36, v198, v201
	s_nop 0
	v_fma_f32 v9, v228, v132, v9
	v_mul_f32_e32 v10, v13, v132
	v_mul_f32_e32 v13, v13, v134
	s_nop 0
	v_fma_f32 v10, -v11, v134, v10
	v_fma_f32 v11, v11, v132, v13
	ds_write_b64 v27, v[8:9] offset:43520
	ds_write_b64 v26, v[10:11] offset:47616
	v_mul_f32_e32 v10, s69, v253
	v_mul_f32_e32 v11, s70, v253
	v_fma_f32 v130, v201, v198, v36
	v_mul_f32_e32 v8, v230, v128
	v_mul_f32_e32 v36, v196, v198
	s_nop 0
	v_mul_f32_e32 v9, v230, v130
	v_fma_f32 v13, -v254, s70, v10
	v_fma_f32 v11, v254, s69, v11
	v_fma_f32 v8, -v231, v130, v8
	v_fma_f32 v124, -v197, v201, v36
	v_mul_f32_e32 v36, v196, v201
	s_nop 0
	v_fma_f32 v9, v231, v128, v9
	v_mul_f32_e32 v10, v13, v128
	v_mul_f32_e32 v13, v13, v130
	s_nop 0
	v_fma_f32 v10, -v11, v130, v10
	v_fma_f32 v11, v11, v128, v13
	ds_write_b64 v27, v[8:9] offset:52224
	ds_write_b64 v26, v[10:11] offset:56320
	v_mul_f32_e32 v10, s77, v250
	v_mul_f32_e32 v11, s78, v250
	v_fma_f32 v126, v197, v198, v36
	v_mul_f32_e32 v8, v227, v124
	v_mul_f32_e32 v36, v196, v196
	s_nop 0
	v_mul_f32_e32 v9, v227, v126
	v_fma_f32 v13, -v252, s78, v10
	v_fma_f32 v11, v252, s77, v11
	v_fma_f32 v8, -v235, v126, v8
	v_fma_f32 v120, -v197, v197, v36
	v_mul_f32_e32 v36, v196, v197
	s_nop 0
	v_fma_f32 v9, v235, v124, v9
	v_mul_f32_e32 v10, v13, v124
	v_mul_f32_e32 v13, v13, v126
	s_nop 0
	v_fma_f32 v10, -v11, v126, v10
	v_fma_f32 v11, v11, v124, v13
	ds_write_b64 v27, v[8:9] offset:60928
	ds_write_b64 v26, v[10:11] offset:65024
	v_mul_f32_e32 v10, s59, v22
	v_mul_f32_e32 v11, s79, v22
	v_fma_f32 v122, v197, v196, v36
	v_mul_f32_e32 v8, v213, v120
	v_mul_f32_e32 v36, v120, v210
	v_mul_f32_e32 v37, v120, v126
	s_nop 0
	v_fma_f32 v13, -v23, s79, v10
	v_fma_f32 v11, v23, s59, v11
	v_mul_f32_e32 v9, v213, v122
	v_fma_f32 v8, -v214, v122, v8
	v_fma_f32 v48, -v122, v211, v36
	v_mul_f32_e32 v36, v120, v211
	s_nop 0
	v_mul_f32_e32 v10, v13, v120
	v_mul_f32_e32 v13, v13, v122
	v_fma_f32 v9, v214, v120, v9
	v_fma_f32 v37, v122, v124, v37
	s_nop 0
	v_fma_f32 v10, -v11, v122, v10
	v_fma_f32 v11, v11, v120, v13
	v_add_u32_e32 v13, 0x11000, v27
	ds_write_b64 v13, v[8:9]
	v_add_u32_e32 v8, 0x12000, v26
	ds_write_b64 v8, v[10:11]
	v_mul_f32_e32 v10, s72, v18
	v_mul_f32_e32 v11, s78, v18
	v_fma_f32 v49, v122, v210, v36
	v_pk_mul_f32 v[8:9], v[214:215], v[48:49] op_sel:[1,0] op_sel_hi:[1,1]
	v_mul_f32_e32 v36, v132, v132
	s_nop 0
	v_fma_f32 v13, -v19, s78, v10
	v_fma_f32 v11, v19, s72, v11
	v_fma_f32 v46, -v134, v134, v36
	v_mul_f32_e32 v36, v132, v134
	s_nop 0
	v_mul_f32_e32 v10, v13, v48
	v_mul_f32_e32 v13, v13, v49
	s_nop 0
	v_fma_f32 v10, -v11, v49, v10
	v_fma_f32 v11, v11, v48, v13
	v_add_u32_e32 v13, 0x13200, v27
	v_pk_fma_f32 v[8:9], v[216:217], v[48:49], v[8:9] op_sel:[0,1,0] op_sel_hi:[0,0,1] neg_lo:[1,0,0] neg_hi:[0,0,0]
	ds_write_b64 v13, v[8:9]
	v_add_u32_e32 v8, 0x14200, v26
	ds_write_b64 v8, v[10:11]
	v_mul_f32_e32 v10, s66, v240
	v_mul_f32_e32 v11, s70, v240
	v_fma_f32 v47, v134, v132, v36
	v_pk_mul_f32 v[8:9], v[216:217], v[46:47] op_sel:[1,0] op_sel_hi:[1,1]
	v_mul_f32_e32 v36, v120, v198
	s_nop 0
	v_fma_f32 v13, -v246, s70, v10
	v_fma_f32 v11, v246, s66, v11
	v_fma_f32 v44, -v122, v201, v36
	v_mul_f32_e32 v36, v120, v201
	s_nop 0
	v_mul_f32_e32 v10, v13, v46
	v_mul_f32_e32 v13, v13, v47
	v_mov_b32_e32 v217, v140
	v_fma_f32 v10, -v11, v47, v10
	v_fma_f32 v11, v11, v46, v13
	v_add_u32_e32 v13, 0x15400, v27
	v_pk_fma_f32 v[8:9], v[218:219], v[46:47], v[8:9] op_sel:[0,1,0] op_sel_hi:[0,0,1] neg_lo:[1,0,0] neg_hi:[0,0,0]
	ds_write_b64 v13, v[8:9]
	v_add_u32_e32 v8, 0x16400, v26
	ds_write_b64 v8, v[10:11]
	v_mul_f32_e32 v10, s74, v20
	v_mul_f32_e32 v11, s76, v20
	v_fma_f32 v45, v122, v198, v36
	v_pk_mul_f32 v[8:9], v[218:219], v[44:45] op_sel:[1,0] op_sel_hi:[1,1]
	v_mul_f32_e32 v36, v128, v128
	s_nop 0
	v_fma_f32 v13, -v21, s76, v10
	v_fma_f32 v11, v21, s74, v11
	v_fma_f32 v42, -v130, v130, v36
	v_mul_f32_e32 v36, v128, v130
	s_nop 0
	v_mul_f32_e32 v10, v13, v44
	v_mul_f32_e32 v13, v13, v45
	s_nop 0
	v_fma_f32 v10, -v11, v45, v10
	v_fma_f32 v11, v11, v44, v13
	v_add_u32_e32 v13, 0x17600, v27
	v_pk_fma_f32 v[8:9], v[220:221], v[44:45], v[8:9] op_sel:[0,1,0] op_sel_hi:[0,0,1] neg_lo:[1,0,0] neg_hi:[0,0,0]
	ds_write_b64 v13, v[8:9]
	v_add_u32_e32 v8, 0x18600, v26
	ds_write_b64 v8, v[10:11]
	v_mul_f32_e32 v10, s68, v15
	v_fma_f32 v43, v130, v128, v36
	v_pk_mul_f32 v[8:9], v[198:199], v[42:43] op_sel:[1,0] op_sel_hi:[1,1]
	v_mul_f32_e32 v36, v120, v132
	s_nop 0
	v_fma_f32 v11, -v14, s68, v10
	v_fma_f32 v13, v14, s68, v10
	v_fma_f32 v40, -v122, v134, v36
	v_mul_f32_e32 v36, v120, v134
	s_nop 0
	v_pk_mul_f32 v[10:11], v[10:11], v[42:43] op_sel:[1,0] op_sel_hi:[1,1]
	s_nop 0
	v_pk_fma_f32 v[10:11], v[12:13], v[42:43], v[10:11] op_sel:[1,1,0] op_sel_hi:[1,0,1] neg_lo:[1,0,0] neg_hi:[0,0,0]
	v_add_u32_e32 v13, 0x19800, v27
	v_pk_fma_f32 v[8:9], v[200:201], v[42:43], v[8:9] op_sel:[0,1,0] op_sel_hi:[0,0,1] neg_lo:[1,0,0] neg_hi:[0,0,0]
	ds_write_b64 v13, v[8:9]
	v_add_u32_e32 v8, 0x1a800, v26
	ds_write_b64 v8, v[10:11]
	v_mul_f32_e32 v10, s76, v237
	v_mul_f32_e32 v11, s74, v237
	v_fma_f32 v41, v122, v132, v36
	v_pk_mul_f32 v[8:9], v[202:203], v[40:41] op_sel:[0,0] op_sel_hi:[0,1]
	v_mul_f32_e32 v36, v124, v124
	s_nop 0
	v_fma_f32 v13, -v238, s74, v10
	v_fma_f32 v11, v238, s76, v11
	v_fma_f32 v38, -v126, v126, v36
	v_mul_f32_e32 v36, v124, v126
	s_nop 0
	v_mul_f32_e32 v10, v13, v40
	v_mul_f32_e32 v13, v13, v41
	s_nop 0
	v_fma_f32 v10, -v11, v41, v10
	v_fma_f32 v11, v11, v40, v13
	v_add_u32_e32 v13, 0x1ba00, v27
	v_pk_fma_f32 v[8:9], v[202:203], v[40:41], v[8:9] op_sel:[1,1,0] op_sel_hi:[1,0,1] neg_lo:[1,0,0] neg_hi:[0,0,0]
	ds_write_b64 v13, v[8:9]
	v_add_u32_e32 v8, 0x1ca00, v26
	ds_write_b64 v8, v[10:11]
	v_mul_f32_e32 v10, s70, v232
	v_mul_f32_e32 v11, s66, v232
	v_fma_f32 v39, v126, v124, v36
	v_pk_mul_f32 v[8:9], v[204:205], v[38:39] op_sel:[0,0] op_sel_hi:[0,1]
	v_mul_f32_e32 v36, v120, v124
	v_mov_b32_e32 v120, v139
	v_fma_f32 v13, -v236, s66, v10
	v_fma_f32 v11, v236, s70, v11
	v_fma_f32 v36, -v122, v126, v36
	s_nop 0
	v_mul_f32_e32 v10, v13, v38
	v_mul_f32_e32 v13, v13, v39
	v_pk_fma_f32 v[8:9], v[204:205], v[38:39], v[8:9] op_sel:[1,1,0] op_sel_hi:[1,0,1] neg_lo:[1,0,0] neg_hi:[0,0,0]
	s_nop 0
	v_fma_f32 v10, -v11, v39, v10
	v_fma_f32 v11, v11, v38, v13
	v_add_u32_e32 v13, 0x1dc00, v27
	ds_write_b64 v13, v[8:9]
	v_add_u32_e32 v8, 0x1ec00, v26
	ds_write_b64 v8, v[10:11]
	v_mul_f32_e32 v10, s78, v16
	v_mul_f32_e32 v11, s72, v16
	v_pk_mul_f32 v[8:9], v[206:207], v[36:37] op_sel:[0,0] op_sel_hi:[0,1]
	s_nop 0
	v_fma_f32 v13, -v12, s72, v10
	v_fma_f32 v11, v12, s78, v11
	v_pk_fma_f32 v[8:9], v[206:207], v[36:37], v[8:9] op_sel:[1,1,0] op_sel_hi:[1,0,1] neg_lo:[1,0,0] neg_hi:[0,0,0]
	s_nop 0
	v_mul_f32_e32 v10, v13, v36
	v_mul_f32_e32 v12, v13, v37
	s_nop 0
	v_fma_f32 v10, -v11, v37, v10
	v_fma_f32 v11, v11, v36, v12
	v_add_u32_e32 v12, 0x1fe00, v27
	ds_write_b64 v12, v[8:9]
	v_add_u32_e32 v8, 0x20e00, v26
	ds_write_b64 v8, v[10:11]
	s_waitcnt lgkmcnt(0)
	s_barrier
	ds_read_b64 v[44:45], v136
	ds_read_b64 v[38:39], v137 offset:4096
	ds_read_b64 v[220:221], v136 offset:544
	ds_read_b64 v[22:23], v137 offset:4640
	ds_read_b64 v[222:223], v136 offset:1088
	ds_read_b64 v[14:15], v137 offset:5184
	ds_read_b64 v[224:225], v136 offset:1632
	ds_read_b64 v[8:9], v137 offset:5728
	ds_read_b64 v[226:227], v136 offset:2176
	ds_read_b64 v[42:43], v137 offset:6272
	ds_read_b64 v[228:229], v136 offset:2720
	ds_read_b64 v[26:27], v137 offset:6816
	ds_read_b64 v[230:231], v136 offset:3264
	ds_read_b64 v[18:19], v137 offset:7360
	ds_read_b64 v[232:233], v136 offset:3808
	ds_read_b64 v[10:11], v137 offset:7904
	ds_read_b64 v[234:235], v136 offset:4352
	ds_read_b64 v[46:47], v137 offset:8448
	ds_read_b64 v[236:237], v136 offset:4896
	ds_read_b64 v[36:37], v137 offset:8992
	ds_read_b64 v[238:239], v136 offset:5440
	ds_read_b64 v[20:21], v137 offset:9536
	ds_read_b64 v[240:241], v136 offset:5984
	ds_read_b64 v[12:13], v137 offset:10080
	ds_read_b64 v[242:243], v136 offset:6528
	ds_read_b64 v[48:49], v137 offset:10624
	ds_read_b64 v[244:245], v136 offset:7072
	ds_read_b64 v[40:41], v137 offset:11168
	ds_read_b64 v[246:247], v136 offset:7616
	ds_read_b64 v[24:25], v137 offset:11712
	ds_read_b64 v[248:249], v136 offset:8160
	ds_read_b64 v[16:17], v137 offset:12256
	s_waitcnt lgkmcnt(0)
	v_add_f32_e32 v219, v44, v234
	v_add_f32_e32 v250, v45, v235
	v_pk_add_f32 v[44:45], v[44:45], v[234:235] op_sel:[0,0] op_sel_hi:[1,1] neg_lo:[0,1] neg_hi:[0,1]
	v_pk_add_f32 v[234:235], v[226:227], v[242:243] op_sel:[0,0] op_sel_hi:[1,1]
	v_pk_add_f32 v[226:227], v[226:227], v[242:243] op_sel:[0,0] op_sel_hi:[1,1] neg_lo:[0,1] neg_hi:[0,1]
	s_nop 1
	s_nop 0
	v_add_f32_e32 v242, v219, v234
	v_add_f32_e32 v243, v250, v235
	v_sub_f32_e32 v234, v219, v234
	v_sub_f32_e32 v235, v250, v235
	v_pk_add_f32 v[250:251], v[44:45], v[226:227] op_sel:[0,1] op_sel_hi:[1,0] neg_lo:[0,0] neg_hi:[0,1]
	v_sub_f32_e32 v252, v44, v227
	v_add_f32_e32 v226, v45, v226
	v_pk_add_f32 v[44:45], v[220:221], v[236:237] op_sel:[0,0] op_sel_hi:[1,1]
	v_sub_f32_e32 v219, v220, v236
	v_sub_f32_e32 v220, v221, v237
	v_add_f32_e32 v221, v228, v244
	v_add_f32_e32 v227, v229, v245
	v_pk_add_f32 v[228:229], v[228:229], v[244:245] op_sel:[0,0] op_sel_hi:[1,1] neg_lo:[0,1] neg_hi:[0,1]
	v_xor_b32_e32 v218, 0x80000000, v120
	v_add_f32_e32 v236, v44, v221
	v_add_f32_e32 v237, v45, v227
	v_sub_f32_e32 v44, v44, v221
	v_sub_f32_e32 v45, v45, v227
	v_add_f32_e32 v221, v219, v229
	v_sub_f32_e32 v227, v220, v228
	v_sub_f32_e32 v219, v219, v229
	v_add_f32_e32 v220, v220, v228
	v_pk_add_f32 v[228:229], v[222:223], v[238:239] op_sel:[0,0] op_sel_hi:[1,1]
	v_pk_add_f32 v[222:223], v[222:223], v[238:239] op_sel:[0,0] op_sel_hi:[1,1] neg_lo:[0,1] neg_hi:[0,1]
	v_pk_add_f32 v[238:239], v[230:231], v[246:247] op_sel:[0,0] op_sel_hi:[1,1]
	v_pk_add_f32 v[230:231], v[230:231], v[246:247] op_sel:[0,0] op_sel_hi:[1,1] neg_lo:[0,1] neg_hi:[0,1]
	v_mul_f32_e32 v120, v217, v217
	s_nop 0
	v_pk_add_f32 v[244:245], v[228:229], v[238:239] op_sel:[0,0] op_sel_hi:[1,1]
	v_sub_f32_e32 v228, v228, v238
	v_sub_f32_e32 v238, v229, v239
	v_add_f32_e32 v229, v222, v231
	v_sub_f32_e32 v239, v223, v230
	v_pk_add_f32 v[222:223], v[222:223], v[230:231] op_sel:[0,1] op_sel_hi:[1,0] neg_lo:[0,1] neg_hi:[0,0]
	v_pk_add_f32 v[230:231], v[224:225], v[240:241] op_sel:[0,0] op_sel_hi:[1,1]
	v_pk_add_f32 v[224:225], v[224:225], v[240:241] op_sel:[0,0] op_sel_hi:[1,1] neg_lo:[0,1] neg_hi:[0,1]
	v_pk_add_f32 v[240:241], v[232:233], v[248:249] op_sel:[0,0] op_sel_hi:[1,1]
	v_pk_add_f32 v[232:233], v[232:233], v[248:249] op_sel:[0,0] op_sel_hi:[1,1] neg_lo:[0,1] neg_hi:[0,1]
	s_nop 0
	v_xor_b32_e32 v249, 0x80000000, v228
	v_pk_add_f32 v[246:247], v[230:231], v[240:241] op_sel:[0,0] op_sel_hi:[1,1]
	v_pk_add_f32 v[230:231], v[230:231], v[240:241] op_sel:[0,0] op_sel_hi:[1,1] neg_lo:[0,1] neg_hi:[0,1]
	v_pk_add_f32 v[240:241], v[224:225], v[232:233] op_sel:[0,1] op_sel_hi:[1,0] neg_lo:[0,0] neg_hi:[0,1]
	v_pk_add_f32 v[224:225], v[224:225], v[232:233] op_sel:[0,1] op_sel_hi:[1,0] neg_lo:[0,1] neg_hi:[0,0]
	v_mul_f32_e32 v232, v221, v152
	v_mul_f32_e32 v221, v221, v153
	s_nop 0
	v_fma_f32 v232, -v227, v153, v232
	v_fma_f32 v221, v227, v152, v221
	v_mul_f32_e32 v227, v229, v154
	v_add_f32_e32 v228, v237, v247
	v_fma_f32 v215, -v218, v218, v120
	v_mul_f32_e32 v120, v217, v218
	s_nop 0
	v_fma_f32 v233, -v239, v155, v227
	v_mul_f32_e32 v227, v229, v155
	v_fma_f32 v216, v218, v217, v120
	v_mul_f32_e32 v120, v215, v217
	s_nop 0
	v_fma_f32 v229, v239, v154, v227
	v_mul_f32_e32 v227, v240, v156
	v_fma_f32 v213, -v216, v218, v120
	v_mul_f32_e32 v120, v215, v218
	s_nop 0
	v_fma_f32 v239, -v241, v157, v227
	v_mul_f32_e32 v227, v240, v157
	v_fma_f32 v214, v216, v217, v120
	v_mul_f32_e32 v120, v215, v215
	s_nop 0
	v_fma_f32 v240, v241, v156, v227
	v_mul_f32_e32 v227, v44, v154
	v_mul_f32_e32 v44, v44, v155
	v_fma_f32 v210, -v216, v216, v120
	v_mul_f32_e32 v120, v215, v216
	s_nop 0
	v_fma_f32 v248, v45, v154, v44
	v_mul_f32_e32 v44, v230, v155
	v_sub_f32_e32 v230, v236, v246
	v_fma_f32 v241, -v45, v155, v227
	v_fma_f32 v211, v216, v215, v120
	v_mul_f32_e32 v120, v210, v217
	s_nop 0
	v_fma_f32 v253, -v231, v155, v44
	v_fma_f32 v231, v231, v155, v44
	v_mul_f32_e32 v44, v219, v156
	v_fma_f32 v208, -v211, v218, v120
	v_mul_f32_e32 v120, v210, v218
	s_nop 0
	v_fma_f32 v254, -v220, v157, v44
	v_mul_f32_e32 v44, v219, v157
	v_add_f32_e32 v219, v242, v244
	v_fma_f32 v209, v211, v217, v120
	v_mul_f32_e32 v120, v213, v213
	s_nop 0
	v_fma_f32 v212, v220, v156, v44
	v_mul_f32_e32 v44, v222, v155
	v_add_f32_e32 v220, v243, v245
	v_fma_f32 v206, -v214, v214, v120
	v_mul_f32_e32 v120, v213, v214
	s_nop 0
	v_fma_f32 v151, -v223, v155, v44
	v_fma_f32 v170, v223, v155, v44
	v_mul_f32_e32 v44, v224, v157
	v_pk_add_f32 v[222:223], v[242:243], v[244:245] op_sel:[0,0] op_sel_hi:[1,1] neg_lo:[0,1] neg_hi:[0,1]
	v_add_f32_e32 v45, v220, v228
	v_sub_f32_e32 v228, v220, v228
	v_fma_f32 v207, v214, v213, v120
	v_mul_f32_e32 v120, v210, v213
	s_nop 0
	v_fma_f32 v171, -v225, v156, v44
	v_mul_f32_e32 v44, v224, v156
	v_add_f32_e32 v224, v236, v246
	v_sub_f32_e32 v236, v237, v247
	v_sub_f32_e32 v242, v223, v230
	v_add_f32_e32 v220, v223, v230
	v_add_f32_e32 v223, v251, v229
	s_nop 0
	v_fma_f32 v225, v225, v157, v44
	v_add_f32_e32 v44, v219, v224
	v_sub_f32_e32 v227, v219, v224
	v_add_f32_e32 v237, v222, v236
	v_sub_f32_e32 v219, v222, v236
	v_add_f32_e32 v222, v250, v233
	v_sub_f32_e32 v224, v250, v233
	v_sub_f32_e32 v233, v251, v229
	v_add_f32_e32 v229, v232, v239
	v_add_f32_e32 v230, v221, v240
	v_sub_f32_e32 v232, v232, v239
	v_sub_f32_e32 v221, v221, v240
	v_fma_f32 v204, -v211, v214, v120
	v_mul_f32_e32 v120, v210, v214
	s_nop 0
	v_add_f32_e32 v236, v222, v229
	v_add_f32_e32 v239, v223, v230
	v_sub_f32_e32 v229, v222, v229
	v_sub_f32_e32 v230, v223, v230
	v_add_f32_e32 v240, v224, v221
	v_sub_f32_e32 v243, v233, v232
	v_sub_f32_e32 v221, v224, v221
	v_add_f32_e32 v222, v233, v232
	v_add_f32_e32 v223, v234, v238
	v_add_f32_e32 v224, v235, v249
	v_sub_f32_e32 v233, v234, v238
	v_sub_f32_e32 v234, v235, v249
	v_add_f32_e32 v232, v241, v253
	v_add_f32_e32 v235, v248, v231
	v_sub_f32_e32 v238, v241, v253
	v_sub_f32_e32 v241, v248, v231
	v_fma_f32 v205, v211, v213, v120
	v_mul_f32_e32 v120, v210, v210
	s_nop 0
	v_add_f32_e32 v244, v223, v232
	v_add_f32_e32 v245, v224, v235
	v_sub_f32_e32 v231, v223, v232
	v_sub_f32_e32 v232, v224, v235
	v_add_f32_e32 v235, v233, v241
	v_sub_f32_e32 v246, v234, v238
	v_sub_f32_e32 v223, v233, v241
	v_add_f32_e32 v224, v234, v238
	v_add_f32_e32 v233, v252, v151
	v_add_f32_e32 v234, v226, v170
	v_sub_f32_e32 v151, v252, v151
	v_sub_f32_e32 v170, v226, v170
	v_add_f32_e32 v226, v254, v171
	v_add_f32_e32 v238, v212, v225
	v_sub_f32_e32 v171, v254, v171
	v_sub_f32_e32 v212, v212, v225
	v_fma_f32 v202, -v211, v211, v120
	v_mul_f32_e32 v120, v210, v211
	s_nop 0
	v_add_f32_e32 v241, v233, v226
	v_add_f32_e32 v247, v234, v238
	v_sub_f32_e32 v233, v233, v226
	v_sub_f32_e32 v234, v234, v238
	v_add_f32_e32 v238, v151, v212
	v_sub_f32_e32 v248, v170, v171
	v_sub_f32_e32 v225, v151, v212
	v_add_f32_e32 v226, v170, v171
	v_add_f32_e32 v151, v38, v46
	v_add_f32_e32 v170, v39, v47
	v_pk_add_f32 v[38:39], v[38:39], v[46:47] op_sel:[0,0] op_sel_hi:[1,1] neg_lo:[0,1] neg_hi:[0,1]
	v_pk_add_f32 v[46:47], v[42:43], v[48:49] op_sel:[0,0] op_sel_hi:[1,1]
	v_pk_add_f32 v[42:43], v[42:43], v[48:49] op_sel:[0,0] op_sel_hi:[1,1] neg_lo:[0,1] neg_hi:[0,1]
	v_fma_f32 v203, v211, v210, v120
	v_mul_f32_e32 v120, v202, v217
	s_nop 0
	v_add_f32_e32 v48, v151, v46
	v_add_f32_e32 v49, v170, v47
	v_sub_f32_e32 v46, v151, v46
	v_sub_f32_e32 v47, v170, v47
	v_add_f32_e32 v151, v38, v43
	v_sub_f32_e32 v170, v39, v42
	v_pk_add_f32 v[38:39], v[38:39], v[42:43] op_sel:[0,1] op_sel_hi:[1,0] neg_lo:[0,1] neg_hi:[0,0]
	v_pk_add_f32 v[42:43], v[22:23], v[36:37] op_sel:[0,0] op_sel_hi:[1,1]
	v_pk_add_f32 v[22:23], v[22:23], v[36:37] op_sel:[0,0] op_sel_hi:[1,1] neg_lo:[0,1] neg_hi:[0,1]
	v_pk_add_f32 v[36:37], v[26:27], v[40:41] op_sel:[0,0] op_sel_hi:[1,1]
	v_pk_add_f32 v[26:27], v[26:27], v[40:41] op_sel:[0,0] op_sel_hi:[1,1] neg_lo:[0,1] neg_hi:[0,1]
	v_fma_f32 v200, -v203, v218, v120
	v_mul_f32_e32 v120, v202, v218
	s_nop 0
	v_pk_add_f32 v[40:41], v[42:43], v[36:37] op_sel:[0,0] op_sel_hi:[1,1]
	v_pk_add_f32 v[36:37], v[42:43], v[36:37] op_sel:[0,0] op_sel_hi:[1,1] neg_lo:[0,1] neg_hi:[0,1]
	v_pk_add_f32 v[42:43], v[22:23], v[26:27] op_sel:[0,1] op_sel_hi:[1,0] neg_lo:[0,0] neg_hi:[0,1]
	v_pk_add_f32 v[22:23], v[22:23], v[26:27] op_sel:[0,1] op_sel_hi:[1,0] neg_lo:[0,1] neg_hi:[0,0]
	v_pk_add_f32 v[26:27], v[14:15], v[20:21] op_sel:[0,0] op_sel_hi:[1,1]
	v_pk_add_f32 v[14:15], v[14:15], v[20:21] op_sel:[0,0] op_sel_hi:[1,1] neg_lo:[0,1] neg_hi:[0,1]
	v_pk_add_f32 v[20:21], v[18:19], v[24:25] op_sel:[0,0] op_sel_hi:[1,1]
	v_pk_add_f32 v[18:19], v[18:19], v[24:25] op_sel:[0,0] op_sel_hi:[1,1] neg_lo:[0,1] neg_hi:[0,1]
	v_fma_f32 v201, v203, v217, v120
	v_mul_f32_e32 v120, v208, v208
	s_nop 0
	v_pk_add_f32 v[24:25], v[26:27], v[20:21] op_sel:[0,0] op_sel_hi:[1,1]
	v_pk_add_f32 v[20:21], v[26:27], v[20:21] op_sel:[0,0] op_sel_hi:[1,1] neg_lo:[0,1] neg_hi:[0,1]
	v_pk_add_f32 v[26:27], v[14:15], v[18:19] op_sel:[0,1] op_sel_hi:[1,0] neg_lo:[0,0] neg_hi:[0,1]
	v_pk_add_f32 v[14:15], v[14:15], v[18:19] op_sel:[0,1] op_sel_hi:[1,0] neg_lo:[0,1] neg_hi:[0,0]
	v_pk_add_f32 v[18:19], v[8:9], v[12:13] op_sel:[0,0] op_sel_hi:[1,1]
	v_pk_add_f32 v[8:9], v[8:9], v[12:13] op_sel:[0,0] op_sel_hi:[1,1] neg_lo:[0,1] neg_hi:[0,1]
	v_pk_add_f32 v[12:13], v[10:11], v[16:17] op_sel:[0,0] op_sel_hi:[1,1]
	v_pk_add_f32 v[10:11], v[10:11], v[16:17] op_sel:[0,0] op_sel_hi:[1,1] neg_lo:[0,1] neg_hi:[0,1]
	s_nop 0
	v_mul_f32_e32 v14, v14, v155
	v_add_f32_e32 v171, v48, v24
	v_pk_add_f32 v[16:17], v[18:19], v[12:13] op_sel:[0,0] op_sel_hi:[1,1]
	v_pk_add_f32 v[12:13], v[18:19], v[12:13] op_sel:[0,0] op_sel_hi:[1,1] neg_lo:[0,1] neg_hi:[0,1]
	v_pk_add_f32 v[18:19], v[8:9], v[10:11] op_sel:[0,1] op_sel_hi:[1,0] neg_lo:[0,0] neg_hi:[0,1]
	v_pk_add_f32 v[8:9], v[8:9], v[10:11] op_sel:[0,1] op_sel_hi:[1,0] neg_lo:[0,1] neg_hi:[0,0]
	v_pk_mul_f32 v[10:11], v[42:43], v[152:153] op_sel:[0,0] op_sel_hi:[0,1]
	v_mul_f32_e32 v42, v26, v154
	v_mul_f32_e32 v26, v26, v155
	s_nop 0
	v_mul_f32_e32 v12, v12, v155
	v_add_f32_e32 v212, v49, v25
	v_pk_fma_f32 v[10:11], v[42:43], v[152:153], v[10:11] op_sel:[1,1,0] op_sel_hi:[1,0,1] neg_lo:[1,0,0] neg_hi:[0,0,0]
	v_fma_f32 v42, -v27, v155, v42
	v_fma_f32 v26, v27, v154, v26
	v_mul_f32_e32 v27, v18, v156
	v_mul_f32_e32 v18, v18, v157
	v_pk_add_f32 v[24:25], v[48:49], v[24:25] op_sel:[0,0] op_sel_hi:[1,1] neg_lo:[0,1] neg_hi:[0,1]
	v_pk_add_f32 v[48:49], v[40:41], v[16:17] op_sel:[0,0] op_sel_hi:[1,1]
	s_nop 0
	v_fma_f32 v27, -v19, v157, v27
	v_fma_f32 v18, v19, v156, v18
	v_mul_f32_e32 v19, v36, v154
	v_mul_f32_e32 v36, v36, v155
	v_pk_add_f32 v[16:17], v[40:41], v[16:17] op_sel:[0,0] op_sel_hi:[1,1] neg_lo:[0,1] neg_hi:[0,1]
	v_xor_b32_e32 v20, 0x80000000, v20
	v_fma_f32 v19, -v37, v155, v19
	v_fma_f32 v36, v37, v154, v36
	v_fma_f32 v37, -v13, v155, v12
	v_fma_f32 v12, v13, v155, v12
	v_mul_f32_e32 v13, v22, v156
	v_mul_f32_e32 v22, v22, v157
	v_sub_f32_e32 v40, v171, v48
	v_sub_f32_e32 v41, v212, v49
	v_fma_f32 v198, -v209, v209, v120
	v_mul_f32_e32 v120, v208, v209
	s_nop 0
	v_fma_f32 v13, -v23, v157, v13
	v_fma_f32 v22, v23, v156, v22
	v_fma_f32 v23, -v15, v155, v14
	v_fma_f32 v14, v15, v155, v14
	v_mul_f32_e32 v15, v8, v157
	v_mul_f32_e32 v8, v8, v156
	v_fma_f32 v199, v209, v208, v120
	v_mul_f32_e32 v120, v202, v213
	v_mul_f32_e32 v122, v202, v205
	s_nop 0
	v_fma_f32 v15, -v9, v156, v15
	v_fma_f32 v43, v9, v157, v8
	v_add_f32_e32 v8, v171, v48
	v_add_f32_e32 v9, v212, v49
	v_pk_add_f32 v[48:49], v[24:25], v[16:17] op_sel:[0,1] op_sel_hi:[1,0] neg_lo:[0,0] neg_hi:[0,1]
	v_pk_add_f32 v[16:17], v[24:25], v[16:17] op_sel:[1,0] op_sel_hi:[0,1] neg_lo:[0,0] neg_hi:[0,1]
	v_add_f32_e32 v24, v151, v42
	v_add_f32_e32 v25, v170, v26
	v_sub_f32_e32 v42, v151, v42
	v_sub_f32_e32 v26, v170, v26
	v_add_f32_e32 v151, v10, v27
	v_add_f32_e32 v170, v11, v18
	v_sub_f32_e32 v10, v10, v27
	v_sub_f32_e32 v11, v11, v18
	ds_write_b64 v138, v[44:45]
	ds_write_b64 v137, v[8:9] offset:4096
	v_add_f32_e32 v18, v24, v151
	v_add_f32_e32 v27, v25, v170
	v_sub_f32_e32 v24, v24, v151
	v_sub_f32_e32 v25, v25, v170
	v_add_f32_e32 v151, v42, v11
	v_sub_f32_e32 v170, v26, v10
	v_sub_f32_e32 v42, v42, v11
	v_add_f32_e32 v26, v26, v10
	v_pk_add_f32 v[10:11], v[46:47], v[20:21] op_sel:[0,1] op_sel_hi:[1,0]
	v_pk_add_f32 v[20:21], v[46:47], v[20:21] op_sel:[1,0] op_sel_hi:[0,1] neg_lo:[0,1] neg_hi:[0,1]
	v_add_f32_e32 v46, v19, v37
	v_add_f32_e32 v47, v36, v12
	v_sub_f32_e32 v19, v19, v37
	v_sub_f32_e32 v12, v36, v12
	v_mul_f32_e32 v8, v236, v217
	v_mul_f32_e32 v9, v236, v218
	s_nop 0
	v_pk_add_f32 v[36:37], v[10:11], v[46:47] op_sel:[0,0] op_sel_hi:[1,1]
	v_pk_add_f32 v[46:47], v[10:11], v[46:47] op_sel:[0,0] op_sel_hi:[1,1] neg_lo:[0,1] neg_hi:[0,1]
	v_add_f32_e32 v171, v21, v12
	v_sub_f32_e32 v212, v20, v19
	v_sub_f32_e32 v12, v21, v12
	v_add_f32_e32 v19, v20, v19
	v_add_f32_e32 v10, v38, v23
	v_add_f32_e32 v11, v39, v14
	v_sub_f32_e32 v20, v38, v23
	v_add_f32_e32 v21, v13, v15
	v_add_f32_e32 v23, v22, v43
	v_sub_f32_e32 v13, v13, v15
	v_sub_f32_e32 v15, v22, v43
	v_fma_f32 v8, -v239, v218, v8
	v_fma_f32 v9, v239, v217, v9
	s_nop 0
	v_add_f32_e32 v22, v10, v21
	v_add_f32_e32 v38, v11, v23
	v_sub_f32_e32 v21, v10, v21
	v_sub_f32_e32 v23, v11, v23
	v_mul_f32_e32 v10, v18, v217
	v_mul_f32_e32 v11, v18, v218
	v_sub_f32_e32 v14, v39, v14
	v_add_f32_e32 v39, v20, v15
	v_fma_f32 v196, -v203, v214, v120
	v_mul_f32_e32 v120, v202, v214
	s_nop 0
	v_fma_f32 v10, -v27, v218, v10
	v_fma_f32 v11, v27, v217, v11
	ds_write_b64 v138, v[8:9] offset:544
	ds_write_b64 v137, v[10:11] offset:4640
	v_mul_f32_e32 v8, v244, v215
	v_mul_f32_e32 v9, v244, v216
	v_mul_f32_e32 v10, v36, v215
	v_mul_f32_e32 v11, v36, v216
	v_sub_f32_e32 v43, v14, v13
	v_fma_f32 v197, v203, v213, v120
	s_nop 0
	v_fma_f32 v8, -v245, v216, v8
	v_fma_f32 v9, v245, v215, v9
	v_fma_f32 v10, -v37, v216, v10
	v_fma_f32 v11, v37, v215, v11
	ds_write_b64 v138, v[8:9] offset:1088
	ds_write_b64 v137, v[10:11] offset:5184
	v_mul_f32_e32 v8, v241, v213
	v_mul_f32_e32 v9, v241, v214
	v_mul_f32_e32 v10, v22, v213
	v_mul_f32_e32 v11, v22, v214
	v_mul_f32_e32 v120, v206, v206
	v_fma_f32 v122, v203, v204, v122
	s_nop 0
	v_fma_f32 v8, -v247, v214, v8
	v_fma_f32 v9, v247, v213, v9
	v_fma_f32 v10, -v38, v214, v10
	v_fma_f32 v11, v38, v213, v11
	ds_write_b64 v138, v[8:9] offset:1632
	ds_write_b64 v137, v[10:11] offset:5728
	v_pk_mul_f32 v[8:9], v[236:237], v[210:211] op_sel:[1,0] op_sel_hi:[1,1]
	v_pk_mul_f32 v[10:11], v[48:49], v[210:211] op_sel:[0,0] op_sel_hi:[0,1]
	v_fma_f32 v132, -v207, v207, v120
	v_mul_f32_e32 v120, v206, v207
	s_nop 0
	v_pk_fma_f32 v[8:9], v[242:243], v[210:211], v[8:9] op_sel:[0,1,0] op_sel_hi:[0,0,1] neg_lo:[1,0,0] neg_hi:[0,0,0]
	v_pk_fma_f32 v[10:11], v[48:49], v[210:211], v[10:11] op_sel:[1,1,0] op_sel_hi:[1,0,1] neg_lo:[1,0,0] neg_hi:[0,0,0]
	ds_write_b64 v138, v[8:9] offset:2176
	ds_write_b64 v137, v[10:11] offset:6272
	v_pk_mul_f32 v[8:9], v[240:241], v[208:209] op_sel:[0,0] op_sel_hi:[0,1]
	v_pk_mul_f32 v[10:11], v[150:151], v[208:209] op_sel:[1,0] op_sel_hi:[1,1]
	v_fma_f32 v134, v207, v206, v120
	v_mul_f32_e32 v120, v202, v208
	s_nop 0
	v_pk_fma_f32 v[8:9], v[242:243], v[208:209], v[8:9] op_sel:[1,1,0] op_sel_hi:[1,0,1] neg_lo:[1,0,0] neg_hi:[0,0,0]
	v_pk_fma_f32 v[10:11], v[170:171], v[208:209], v[10:11] op_sel:[0,1,0] op_sel_hi:[0,0,1] neg_lo:[1,0,0] neg_hi:[0,0,0]
	ds_write_b64 v138, v[8:9] offset:2720
	ds_write_b64 v137, v[10:11] offset:6816
	v_pk_mul_f32 v[8:9], v[234:235], v[206:207] op_sel:[1,0] op_sel_hi:[1,1]
	v_pk_mul_f32 v[10:11], v[170:171], v[206:207] op_sel:[1,0] op_sel_hi:[1,1]
	v_fma_f32 v128, -v203, v209, v120
	v_mul_f32_e32 v120, v202, v209
	s_nop 0
	v_pk_fma_f32 v[8:9], v[246:247], v[206:207], v[8:9] op_sel:[0,1,0] op_sel_hi:[0,0,1] neg_lo:[1,0,0] neg_hi:[0,0,0]
	v_pk_fma_f32 v[10:11], v[212:213], v[206:207], v[10:11] op_sel:[0,1,0] op_sel_hi:[0,0,1] neg_lo:[1,0,0] neg_hi:[0,0,0]
	ds_write_b64 v138, v[8:9] offset:3264
	ds_write_b64 v137, v[10:11] offset:7360
	v_pk_mul_f32 v[8:9], v[238:239], v[204:205] op_sel:[0,0] op_sel_hi:[0,1]
	v_pk_mul_f32 v[10:11], v[38:39], v[204:205] op_sel:[1,0] op_sel_hi:[1,1]
	v_fma_f32 v130, v203, v208, v120
	v_mul_f32_e32 v120, v204, v204
	s_nop 0
	v_pk_fma_f32 v[8:9], v[248:249], v[204:205], v[8:9] op_sel:[0,1,0] op_sel_hi:[0,0,1] neg_lo:[1,0,0] neg_hi:[0,0,0]
	v_pk_fma_f32 v[10:11], v[42:43], v[204:205], v[10:11] op_sel:[1,1,0] op_sel_hi:[1,0,1] neg_lo:[1,0,0] neg_hi:[0,0,0]
	ds_write_b64 v138, v[8:9] offset:3808
	ds_write_b64 v137, v[10:11] offset:7904
	v_pk_mul_f32 v[8:9], v[226:227], v[202:203] op_sel:[1,0] op_sel_hi:[1,1]
	v_pk_mul_f32 v[10:11], v[40:41], v[202:203] op_sel:[0,0] op_sel_hi:[0,1]
	v_fma_f32 v124, -v205, v205, v120
	v_mul_f32_e32 v120, v204, v205
	s_nop 0
	v_pk_fma_f32 v[8:9], v[228:229], v[202:203], v[8:9] op_sel:[0,1,0] op_sel_hi:[0,0,1] neg_lo:[1,0,0] neg_hi:[0,0,0]
	v_pk_fma_f32 v[10:11], v[40:41], v[202:203], v[10:11] op_sel:[1,1,0] op_sel_hi:[1,0,1] neg_lo:[1,0,0] neg_hi:[0,0,0]
	ds_write_b64 v138, v[8:9] offset:4352
	ds_write_b64 v137, v[10:11] offset:8448
	v_pk_mul_f32 v[8:9], v[228:229], v[200:201] op_sel:[1,0] op_sel_hi:[1,1]
	v_pk_mul_f32 v[10:11], v[24:25], v[200:201] op_sel:[0,0] op_sel_hi:[0,1]
	v_fma_f32 v126, v205, v204, v120
	v_mul_f32_e32 v120, v202, v204
	s_nop 0
	v_pk_fma_f32 v[8:9], v[230:231], v[200:201], v[8:9] op_sel:[0,1,0] op_sel_hi:[0,0,1] neg_lo:[1,0,0] neg_hi:[0,0,0]
	v_pk_fma_f32 v[10:11], v[24:25], v[200:201], v[10:11] op_sel:[1,1,0] op_sel_hi:[1,0,1] neg_lo:[1,0,0] neg_hi:[0,0,0]
	ds_write_b64 v138, v[8:9] offset:4896
	ds_write_b64 v137, v[10:11] offset:8992
	v_pk_mul_f32 v[8:9], v[230:231], v[198:199] op_sel:[1,0] op_sel_hi:[1,1]
	v_pk_mul_f32 v[10:11], v[46:47], v[198:199] op_sel:[0,0] op_sel_hi:[0,1]
	v_fma_f32 v120, -v203, v205, v120
	v_sub_f32_e32 v15, v20, v15
	s_nop 0
	v_pk_fma_f32 v[8:9], v[232:233], v[198:199], v[8:9] op_sel:[0,1,0] op_sel_hi:[0,0,1] neg_lo:[1,0,0] neg_hi:[0,0,0]
	v_pk_fma_f32 v[10:11], v[46:47], v[198:199], v[10:11] op_sel:[1,1,0] op_sel_hi:[1,0,1] neg_lo:[1,0,0] neg_hi:[0,0,0]
	ds_write_b64 v138, v[8:9] offset:5440
	ds_write_b64 v137, v[10:11] offset:9536
	v_pk_mul_f32 v[8:9], v[232:233], v[196:197] op_sel:[1,0] op_sel_hi:[1,1]
	v_pk_mul_f32 v[10:11], v[20:21], v[196:197] op_sel:[1,0] op_sel_hi:[1,1]
	v_add_f32_e32 v13, v14, v13
	v_mov_b32_e32 v217, v144
	v_pk_fma_f32 v[8:9], v[234:235], v[196:197], v[8:9] op_sel:[0,1,0] op_sel_hi:[0,0,1] neg_lo:[1,0,0] neg_hi:[0,0,0]
	v_pk_fma_f32 v[10:11], v[22:23], v[196:197], v[10:11] op_sel:[1,1,0] op_sel_hi:[1,0,1] neg_lo:[1,0,0] neg_hi:[0,0,0]
	ds_write_b64 v138, v[8:9] offset:5984
	ds_write_b64 v137, v[10:11] offset:10080
	v_mul_f32_e32 v8, v219, v132
	v_mul_f32_e32 v9, v219, v134
	v_mul_f32_e32 v10, v17, v132
	v_mul_f32_e32 v11, v17, v134
	s_nop 0
	v_fma_f32 v8, -v220, v134, v8
	v_fma_f32 v9, v220, v132, v9
	v_fma_f32 v10, -v16, v134, v10
	v_fma_f32 v11, v16, v132, v11
	ds_write_b64 v138, v[8:9] offset:6528
	ds_write_b64 v137, v[10:11] offset:10624
	v_mul_f32_e32 v8, v221, v128
	v_mul_f32_e32 v9, v221, v130
	v_mul_f32_e32 v10, v42, v128
	v_mul_f32_e32 v11, v42, v130
	s_nop 0
	v_fma_f32 v8, -v222, v130, v8
	v_fma_f32 v9, v222, v128, v9
	v_fma_f32 v10, -v26, v130, v10
	v_fma_f32 v11, v26, v128, v11
	ds_write_b64 v138, v[8:9] offset:7072
	ds_write_b64 v137, v[10:11] offset:11168
	v_mul_f32_e32 v8, v223, v124
	v_mul_f32_e32 v9, v223, v126
	v_mul_f32_e32 v10, v12, v124
	v_mul_f32_e32 v11, v12, v126
	s_nop 0
	v_fma_f32 v8, -v224, v126, v8
	v_fma_f32 v9, v224, v124, v9
	v_fma_f32 v10, -v19, v126, v10
	v_fma_f32 v11, v19, v124, v11
	ds_write_b64 v138, v[8:9] offset:7616
	ds_write_b64 v137, v[10:11] offset:11712
	v_mul_f32_e32 v8, v225, v120
	v_mul_f32_e32 v9, v225, v122
	v_mul_f32_e32 v10, v15, v120
	v_mul_f32_e32 v11, v15, v122
	s_nop 0
	v_fma_f32 v8, -v226, v122, v8
	v_fma_f32 v9, v226, v120, v9
	v_fma_f32 v10, -v13, v122, v10
	v_fma_f32 v11, v13, v120, v11
	ds_write_b64 v138, v[8:9] offset:8160
	ds_write_b64 v137, v[10:11] offset:12256
	ds_read_b64 v[44:45], v93
	ds_read_b64 v[38:39], v141 offset:4096
	ds_read_b64 v[220:221], v93 offset:32
	ds_read_b64 v[22:23], v141 offset:4128
	ds_read_b64 v[222:223], v93 offset:64
	ds_read_b64 v[14:15], v141 offset:4160
	ds_read_b64 v[224:225], v93 offset:96
	ds_read_b64 v[8:9], v141 offset:4192
	ds_read_b64 v[226:227], v93 offset:128
	ds_read_b64 v[42:43], v141 offset:4224
	ds_read_b64 v[228:229], v93 offset:160
	ds_read_b64 v[26:27], v141 offset:4256
	ds_read_b64 v[230:231], v93 offset:192
	ds_read_b64 v[18:19], v141 offset:4288
	ds_read_b64 v[232:233], v93 offset:224
	ds_read_b64 v[10:11], v141 offset:4320
	ds_read_b64 v[234:235], v93 offset:256
	ds_read_b64 v[46:47], v141 offset:4352
	ds_read_b64 v[236:237], v93 offset:288
	ds_read_b64 v[36:37], v141 offset:4384
	ds_read_b64 v[238:239], v93 offset:320
	ds_read_b64 v[20:21], v141 offset:4416
	ds_read_b64 v[240:241], v93 offset:352
	ds_read_b64 v[12:13], v141 offset:4448
	ds_read_b64 v[242:243], v93 offset:384
	ds_read_b64 v[48:49], v141 offset:4480
	ds_read_b64 v[244:245], v93 offset:416
	ds_read_b64 v[40:41], v141 offset:4512
	ds_read_b64 v[246:247], v93 offset:448
	ds_read_b64 v[24:25], v141 offset:4544
	ds_read_b64 v[248:249], v93 offset:480
	ds_read_b64 v[16:17], v141 offset:4576
	s_waitcnt lgkmcnt(0)
	v_add_f32_e32 v151, v44, v234
	v_add_f32_e32 v170, v45, v235
	v_pk_add_f32 v[44:45], v[44:45], v[234:235] op_sel:[0,0] op_sel_hi:[1,1] neg_lo:[0,1] neg_hi:[0,1]
	v_add_f32_e32 v171, v226, v242
	v_add_f32_e32 v212, v227, v243
	v_sub_f32_e32 v219, v226, v242
	v_sub_f32_e32 v226, v227, v243
	v_mov_b32_e32 v120, v143
	v_add_f32_e32 v227, v151, v171
	v_add_f32_e32 v234, v170, v212
	v_sub_f32_e32 v151, v151, v171
	v_sub_f32_e32 v170, v170, v212
	v_add_f32_e32 v171, v44, v226
	v_sub_f32_e32 v212, v45, v219
	v_sub_f32_e32 v226, v44, v226
	v_add_f32_e32 v235, v45, v219
	v_pk_add_f32 v[44:45], v[220:221], v[236:237] op_sel:[0,0] op_sel_hi:[1,1]
	v_sub_f32_e32 v219, v220, v236
	v_sub_f32_e32 v220, v221, v237
	v_add_f32_e32 v221, v228, v244
	v_add_f32_e32 v236, v229, v245
	v_pk_add_f32 v[228:229], v[228:229], v[244:245] op_sel:[0,0] op_sel_hi:[1,1] neg_lo:[0,1] neg_hi:[0,1]
	s_nop 1
	s_nop 0
	v_add_f32_e32 v237, v44, v221
	v_add_f32_e32 v242, v45, v236
	v_sub_f32_e32 v44, v44, v221
	v_sub_f32_e32 v45, v45, v236
	v_add_f32_e32 v221, v219, v229
	v_sub_f32_e32 v236, v220, v228
	v_sub_f32_e32 v219, v219, v229
	v_add_f32_e32 v220, v220, v228
	v_pk_add_f32 v[228:229], v[222:223], v[238:239] op_sel:[0,0] op_sel_hi:[1,1]
	v_pk_add_f32 v[222:223], v[222:223], v[238:239] op_sel:[0,0] op_sel_hi:[1,1] neg_lo:[0,1] neg_hi:[0,1]
	v_pk_add_f32 v[238:239], v[230:231], v[246:247] op_sel:[0,0] op_sel_hi:[1,1]
	v_pk_add_f32 v[230:231], v[230:231], v[246:247] op_sel:[0,0] op_sel_hi:[1,1] neg_lo:[0,1] neg_hi:[0,1]
	v_xor_b32_e32 v218, 0x80000000, v120
	v_add_f32_e32 v243, v228, v238
	v_add_f32_e32 v244, v229, v239
	v_sub_f32_e32 v228, v228, v238
	v_sub_f32_e32 v238, v229, v239
	v_add_f32_e32 v229, v222, v231
	v_sub_f32_e32 v239, v223, v230
	v_pk_add_f32 v[222:223], v[222:223], v[230:231] op_sel:[0,1] op_sel_hi:[1,0] neg_lo:[0,1] neg_hi:[0,0]
	v_pk_add_f32 v[230:231], v[224:225], v[240:241] op_sel:[0,0] op_sel_hi:[1,1]
	v_pk_add_f32 v[224:225], v[224:225], v[240:241] op_sel:[0,0] op_sel_hi:[1,1] neg_lo:[0,1] neg_hi:[0,1]
	v_pk_add_f32 v[240:241], v[232:233], v[248:249] op_sel:[0,0] op_sel_hi:[1,1]
	v_pk_add_f32 v[232:233], v[232:233], v[248:249] op_sel:[0,0] op_sel_hi:[1,1] neg_lo:[0,1] neg_hi:[0,1]
	s_nop 0
	v_xor_b32_e32 v247, 0x80000000, v228
	v_add_f32_e32 v245, v230, v240
	v_add_f32_e32 v246, v231, v241
	v_pk_add_f32 v[230:231], v[230:231], v[240:241] op_sel:[0,0] op_sel_hi:[1,1] neg_lo:[0,1] neg_hi:[0,1]
	v_pk_add_f32 v[240:241], v[224:225], v[232:233] op_sel:[0,1] op_sel_hi:[1,0] neg_lo:[0,0] neg_hi:[0,1]
	v_pk_add_f32 v[224:225], v[224:225], v[232:233] op_sel:[0,1] op_sel_hi:[1,0] neg_lo:[0,1] neg_hi:[0,0]
	v_mul_f32_e32 v232, v221, v152
	v_mul_f32_e32 v221, v221, v153
	v_mul_f32_e32 v233, v229, v154
	v_mul_f32_e32 v229, v229, v155
	s_nop 0
	v_add_f32_e32 v228, v242, v246
	v_mul_f32_e32 v120, v217, v217
	v_fma_f32 v232, -v236, v153, v232
	v_fma_f32 v221, v236, v152, v221
	v_fma_f32 v233, -v239, v155, v233
	v_fma_f32 v229, v239, v154, v229
	v_mul_f32_e32 v236, v240, v156
	v_mul_f32_e32 v239, v240, v157
	v_mul_f32_e32 v240, v44, v154
	v_mul_f32_e32 v44, v44, v155
	s_nop 0
	v_fma_f32 v215, -v218, v218, v120
	v_mul_f32_e32 v120, v217, v218
	v_fma_f32 v236, -v241, v157, v236
	v_fma_f32 v239, v241, v156, v239
	v_fma_f32 v240, -v45, v155, v240
	v_fma_f32 v241, v45, v154, v44
	v_mul_f32_e32 v44, v230, v155
	v_sub_f32_e32 v230, v237, v245
	s_nop 0
	v_fma_f32 v216, v218, v217, v120
	v_mul_f32_e32 v120, v215, v217
	v_fma_f32 v248, -v231, v155, v44
	v_fma_f32 v231, v231, v155, v44
	v_mul_f32_e32 v44, v219, v156
	s_nop 0
	v_fma_f32 v213, -v216, v218, v120
	v_mul_f32_e32 v120, v215, v218
	v_fma_f32 v249, -v220, v157, v44
	v_mul_f32_e32 v44, v219, v157
	v_add_f32_e32 v219, v227, v243
	s_nop 0
	v_fma_f32 v214, v216, v217, v120
	v_mul_f32_e32 v120, v215, v215
	v_fma_f32 v250, v220, v156, v44
	v_mul_f32_e32 v44, v222, v155
	v_add_f32_e32 v220, v234, v244
	v_sub_f32_e32 v222, v227, v243
	s_nop 0
	v_fma_f32 v210, -v216, v216, v120
	v_mul_f32_e32 v120, v215, v216
	v_fma_f32 v251, -v223, v155, v44
	v_fma_f32 v252, v223, v155, v44
	v_mul_f32_e32 v44, v224, v157
	v_sub_f32_e32 v223, v234, v244
	v_sub_f32_e32 v234, v242, v246
	v_add_f32_e32 v45, v220, v228
	v_sub_f32_e32 v228, v220, v228
	s_nop 0
	v_fma_f32 v211, v216, v215, v120
	v_fma_f32 v253, -v225, v156, v44
	v_mul_f32_e32 v44, v224, v156
	v_add_f32_e32 v224, v237, v245
	v_add_f32_e32 v237, v222, v234
	v_sub_f32_e32 v242, v223, v230
	v_add_f32_e32 v220, v223, v230
	v_add_f32_e32 v223, v212, v229
	s_nop 0
	v_fma_f32 v225, v225, v157, v44
	v_add_f32_e32 v44, v219, v224
	v_sub_f32_e32 v227, v219, v224
	v_sub_f32_e32 v219, v222, v234
	v_add_f32_e32 v222, v171, v233
	v_sub_f32_e32 v171, v171, v233
	v_sub_f32_e32 v212, v212, v229
	v_add_f32_e32 v224, v232, v236
	v_add_f32_e32 v230, v221, v239
	v_sub_f32_e32 v221, v221, v239
	v_sub_f32_e32 v232, v232, v236
	v_sub_f32_e32 v233, v240, v248
	v_sub_f32_e32 v234, v241, v231
	s_nop 0
	v_add_f32_e32 v236, v222, v224
	v_add_f32_e32 v239, v223, v230
	v_sub_f32_e32 v229, v222, v224
	v_sub_f32_e32 v230, v223, v230
	v_add_f32_e32 v243, v171, v221
	v_sub_f32_e32 v244, v212, v232
	v_sub_f32_e32 v221, v171, v221
	v_add_f32_e32 v222, v212, v232
	v_add_f32_e32 v171, v151, v238
	v_add_f32_e32 v212, v170, v247
	v_sub_f32_e32 v151, v151, v238
	v_sub_f32_e32 v170, v170, v247
	v_add_f32_e32 v223, v240, v248
	v_add_f32_e32 v224, v241, v231
	v_sub_f32_e32 v241, v249, v253
	v_mul_f32_e32 v120, v210, v217
	s_nop 0
	v_add_f32_e32 v238, v171, v223
	v_add_f32_e32 v240, v212, v224
	v_sub_f32_e32 v231, v171, v223
	v_sub_f32_e32 v232, v212, v224
	v_add_f32_e32 v171, v151, v234
	v_sub_f32_e32 v212, v170, v233
	v_sub_f32_e32 v223, v151, v234
	v_add_f32_e32 v224, v170, v233
	v_add_f32_e32 v151, v226, v251
	v_add_f32_e32 v170, v235, v252
	v_sub_f32_e32 v226, v226, v251
	v_sub_f32_e32 v235, v235, v252
	v_add_f32_e32 v233, v249, v253
	v_add_f32_e32 v234, v250, v225
	v_sub_f32_e32 v225, v250, v225
	v_fma_f32 v208, -v211, v218, v120
	v_mul_f32_e32 v120, v210, v218
	s_nop 0
	v_add_f32_e32 v245, v151, v233
	v_add_f32_e32 v246, v170, v234
	v_sub_f32_e32 v233, v151, v233
	v_sub_f32_e32 v234, v170, v234
	v_add_f32_e32 v151, v226, v225
	v_sub_f32_e32 v170, v235, v241
	v_sub_f32_e32 v225, v226, v225
	v_add_f32_e32 v226, v235, v241
	v_add_f32_e32 v235, v38, v46
	v_add_f32_e32 v241, v39, v47
	v_pk_add_f32 v[38:39], v[38:39], v[46:47] op_sel:[0,0] op_sel_hi:[1,1] neg_lo:[0,1] neg_hi:[0,1]
	v_pk_add_f32 v[46:47], v[42:43], v[48:49] op_sel:[0,0] op_sel_hi:[1,1]
	v_pk_add_f32 v[42:43], v[42:43], v[48:49] op_sel:[0,0] op_sel_hi:[1,1] neg_lo:[0,1] neg_hi:[0,1]
	v_fma_f32 v209, v211, v217, v120
	v_mul_f32_e32 v120, v213, v213
	s_nop 0
	v_add_f32_e32 v48, v235, v46
	v_add_f32_e32 v49, v241, v47
	v_sub_f32_e32 v46, v235, v46
	v_sub_f32_e32 v47, v241, v47
	v_add_f32_e32 v235, v38, v43
	v_sub_f32_e32 v241, v39, v42
	v_pk_add_f32 v[38:39], v[38:39], v[42:43] op_sel:[0,1] op_sel_hi:[1,0] neg_lo:[0,1] neg_hi:[0,0]
	v_pk_add_f32 v[42:43], v[22:23], v[36:37] op_sel:[0,0] op_sel_hi:[1,1]
	v_pk_add_f32 v[22:23], v[22:23], v[36:37] op_sel:[0,0] op_sel_hi:[1,1] neg_lo:[0,1] neg_hi:[0,1]
	v_pk_add_f32 v[36:37], v[26:27], v[40:41] op_sel:[0,0] op_sel_hi:[1,1]
	v_pk_add_f32 v[26:27], v[26:27], v[40:41] op_sel:[0,0] op_sel_hi:[1,1] neg_lo:[0,1] neg_hi:[0,1]
	v_fma_f32 v206, -v214, v214, v120
	v_mul_f32_e32 v120, v213, v214
	s_nop 0
	v_pk_add_f32 v[40:41], v[42:43], v[36:37] op_sel:[0,0] op_sel_hi:[1,1]
	v_pk_add_f32 v[36:37], v[42:43], v[36:37] op_sel:[0,0] op_sel_hi:[1,1] neg_lo:[0,1] neg_hi:[0,1]
	v_pk_add_f32 v[42:43], v[22:23], v[26:27] op_sel:[0,1] op_sel_hi:[1,0] neg_lo:[0,0] neg_hi:[0,1]
	v_pk_add_f32 v[22:23], v[22:23], v[26:27] op_sel:[0,1] op_sel_hi:[1,0] neg_lo:[0,1] neg_hi:[0,0]
	v_pk_add_f32 v[26:27], v[14:15], v[20:21] op_sel:[0,0] op_sel_hi:[1,1]
	v_pk_add_f32 v[14:15], v[14:15], v[20:21] op_sel:[0,0] op_sel_hi:[1,1] neg_lo:[0,1] neg_hi:[0,1]
	v_pk_add_f32 v[20:21], v[18:19], v[24:25] op_sel:[0,0] op_sel_hi:[1,1]
	v_pk_add_f32 v[18:19], v[18:19], v[24:25] op_sel:[0,0] op_sel_hi:[1,1] neg_lo:[0,1] neg_hi:[0,1]
	v_fma_f32 v207, v214, v213, v120
	v_mul_f32_e32 v120, v210, v213
	s_nop 0
	v_pk_add_f32 v[24:25], v[26:27], v[20:21] op_sel:[0,0] op_sel_hi:[1,1]
	v_pk_add_f32 v[20:21], v[26:27], v[20:21] op_sel:[0,0] op_sel_hi:[1,1] neg_lo:[0,1] neg_hi:[0,1]
	v_pk_add_f32 v[26:27], v[14:15], v[18:19] op_sel:[0,1] op_sel_hi:[1,0] neg_lo:[0,0] neg_hi:[0,1]
	v_pk_add_f32 v[14:15], v[14:15], v[18:19] op_sel:[0,1] op_sel_hi:[1,0] neg_lo:[0,1] neg_hi:[0,0]
	v_pk_add_f32 v[18:19], v[8:9], v[12:13] op_sel:[0,0] op_sel_hi:[1,1]
	v_pk_add_f32 v[8:9], v[8:9], v[12:13] op_sel:[0,0] op_sel_hi:[1,1] neg_lo:[0,1] neg_hi:[0,1]
	v_pk_add_f32 v[12:13], v[10:11], v[16:17] op_sel:[0,0] op_sel_hi:[1,1]
	v_pk_add_f32 v[10:11], v[10:11], v[16:17] op_sel:[0,0] op_sel_hi:[1,1] neg_lo:[0,1] neg_hi:[0,1]
	s_nop 0
	v_mul_f32_e32 v14, v14, v155
	v_add_f32_e32 v247, v48, v24
	v_pk_add_f32 v[16:17], v[18:19], v[12:13] op_sel:[0,0] op_sel_hi:[1,1]
	v_pk_add_f32 v[12:13], v[18:19], v[12:13] op_sel:[0,0] op_sel_hi:[1,1] neg_lo:[0,1] neg_hi:[0,1]
	v_pk_add_f32 v[18:19], v[8:9], v[10:11] op_sel:[0,1] op_sel_hi:[1,0] neg_lo:[0,0] neg_hi:[0,1]
	v_pk_add_f32 v[8:9], v[8:9], v[10:11] op_sel:[0,1] op_sel_hi:[1,0] neg_lo:[0,1] neg_hi:[0,0]
	v_pk_mul_f32 v[10:11], v[42:43], v[152:153] op_sel:[0,0] op_sel_hi:[0,1]
	v_mul_f32_e32 v42, v26, v154
	v_mul_f32_e32 v26, v26, v155
	s_nop 0
	v_mul_f32_e32 v12, v12, v155
	v_add_f32_e32 v248, v49, v25
	v_pk_fma_f32 v[10:11], v[42:43], v[152:153], v[10:11] op_sel:[1,1,0] op_sel_hi:[1,0,1] neg_lo:[1,0,0] neg_hi:[0,0,0]
	v_fma_f32 v42, -v27, v155, v42
	v_fma_f32 v26, v27, v154, v26
	v_mul_f32_e32 v27, v18, v156
	v_mul_f32_e32 v18, v18, v157
	v_pk_add_f32 v[24:25], v[48:49], v[24:25] op_sel:[0,0] op_sel_hi:[1,1] neg_lo:[0,1] neg_hi:[0,1]
	v_pk_add_f32 v[48:49], v[40:41], v[16:17] op_sel:[0,0] op_sel_hi:[1,1]
	s_nop 0
	v_fma_f32 v27, -v19, v157, v27
	v_fma_f32 v18, v19, v156, v18
	v_mul_f32_e32 v19, v36, v154
	v_mul_f32_e32 v36, v36, v155
	v_pk_add_f32 v[16:17], v[40:41], v[16:17] op_sel:[0,0] op_sel_hi:[1,1] neg_lo:[0,1] neg_hi:[0,1]
	v_xor_b32_e32 v20, 0x80000000, v20
	v_fma_f32 v19, -v37, v155, v19
	v_fma_f32 v36, v37, v154, v36
	v_fma_f32 v37, -v13, v155, v12
	v_fma_f32 v12, v13, v155, v12
	v_mul_f32_e32 v13, v22, v156
	v_mul_f32_e32 v22, v22, v157
	v_sub_f32_e32 v40, v247, v48
	v_sub_f32_e32 v41, v248, v49
	v_fma_f32 v204, -v211, v214, v120
	v_mul_f32_e32 v120, v210, v214
	s_nop 0
	v_fma_f32 v13, -v23, v157, v13
	v_fma_f32 v22, v23, v156, v22
	v_fma_f32 v23, -v15, v155, v14
	v_fma_f32 v14, v15, v155, v14
	v_mul_f32_e32 v15, v8, v157
	v_mul_f32_e32 v8, v8, v156
	v_fma_f32 v205, v211, v213, v120
	v_mul_f32_e32 v120, v210, v210
	s_nop 0
	v_fma_f32 v15, -v9, v156, v15
	v_fma_f32 v43, v9, v157, v8
	v_add_f32_e32 v8, v247, v48
	v_add_f32_e32 v9, v248, v49
	v_pk_add_f32 v[48:49], v[24:25], v[16:17] op_sel:[0,1] op_sel_hi:[1,0] neg_lo:[0,0] neg_hi:[0,1]
	v_pk_add_f32 v[16:17], v[24:25], v[16:17] op_sel:[1,0] op_sel_hi:[0,1] neg_lo:[0,0] neg_hi:[0,1]
	v_add_f32_e32 v24, v235, v42
	v_add_f32_e32 v25, v241, v26
	v_sub_f32_e32 v42, v235, v42
	v_sub_f32_e32 v26, v241, v26
	v_add_f32_e32 v235, v10, v27
	v_add_f32_e32 v241, v11, v18
	v_sub_f32_e32 v10, v10, v27
	v_sub_f32_e32 v11, v11, v18
	ds_write_b64 v142, v[44:45]
	ds_write_b64 v141, v[8:9] offset:4096
	v_add_f32_e32 v18, v24, v235
	v_add_f32_e32 v27, v25, v241
	v_sub_f32_e32 v24, v24, v235
	v_sub_f32_e32 v25, v25, v241
	v_add_f32_e32 v235, v42, v11
	v_sub_f32_e32 v241, v26, v10
	v_sub_f32_e32 v42, v42, v11
	v_add_f32_e32 v26, v26, v10
	v_pk_add_f32 v[10:11], v[46:47], v[20:21] op_sel:[0,1] op_sel_hi:[1,0]
	v_pk_add_f32 v[20:21], v[46:47], v[20:21] op_sel:[1,0] op_sel_hi:[0,1] neg_lo:[0,1] neg_hi:[0,1]
	v_add_f32_e32 v46, v19, v37
	v_add_f32_e32 v47, v36, v12
	v_sub_f32_e32 v19, v19, v37
	v_sub_f32_e32 v12, v36, v12
	v_mul_f32_e32 v8, v236, v217
	v_mul_f32_e32 v9, v236, v218
	s_nop 0
	v_pk_add_f32 v[36:37], v[10:11], v[46:47] op_sel:[0,0] op_sel_hi:[1,1]
	v_pk_add_f32 v[46:47], v[10:11], v[46:47] op_sel:[0,0] op_sel_hi:[1,1] neg_lo:[0,1] neg_hi:[0,1]
	v_add_f32_e32 v247, v21, v12
	v_sub_f32_e32 v248, v20, v19
	v_sub_f32_e32 v12, v21, v12
	v_add_f32_e32 v19, v20, v19
	v_add_f32_e32 v10, v38, v23
	v_add_f32_e32 v11, v39, v14
	v_sub_f32_e32 v20, v38, v23
	v_add_f32_e32 v21, v13, v15
	v_add_f32_e32 v23, v22, v43
	v_sub_f32_e32 v13, v13, v15
	v_sub_f32_e32 v15, v22, v43
	v_fma_f32 v8, -v239, v218, v8
	v_fma_f32 v9, v239, v217, v9
	s_nop 0
	v_add_f32_e32 v22, v10, v21
	v_add_f32_e32 v38, v11, v23
	v_sub_f32_e32 v21, v10, v21
	v_sub_f32_e32 v23, v11, v23
	v_mul_f32_e32 v10, v18, v217
	v_mul_f32_e32 v11, v18, v218
	v_sub_f32_e32 v14, v39, v14
	v_add_f32_e32 v39, v20, v15
	v_fma_f32 v202, -v211, v211, v120
	v_mul_f32_e32 v120, v210, v211
	s_nop 0
	v_fma_f32 v10, -v27, v218, v10
	v_fma_f32 v11, v27, v217, v11
	ds_write_b64 v142, v[8:9] offset:32
	ds_write_b64 v141, v[10:11] offset:4128
	v_mul_f32_e32 v8, v238, v215
	v_mul_f32_e32 v9, v238, v216
	v_mul_f32_e32 v10, v36, v215
	v_mul_f32_e32 v11, v36, v216
	v_fma_f32 v203, v211, v210, v120
	v_sub_f32_e32 v43, v14, v13
	s_nop 0
	v_fma_f32 v8, -v240, v216, v8
	v_fma_f32 v9, v240, v215, v9
	v_fma_f32 v10, -v37, v216, v10
	v_fma_f32 v11, v37, v215, v11
	ds_write_b64 v142, v[8:9] offset:64
	ds_write_b64 v141, v[10:11] offset:4160
	v_mul_f32_e32 v8, v245, v213
	v_mul_f32_e32 v9, v245, v214
	v_mul_f32_e32 v10, v22, v213
	v_mul_f32_e32 v11, v22, v214
	v_mul_f32_e32 v120, v202, v217
	v_mul_f32_e32 v122, v202, v205
	s_nop 0
	v_fma_f32 v8, -v246, v214, v8
	v_fma_f32 v9, v246, v213, v9
	v_fma_f32 v10, -v38, v214, v10
	v_fma_f32 v11, v38, v213, v11
	ds_write_b64 v142, v[8:9] offset:96
	ds_write_b64 v141, v[10:11] offset:4192
	v_pk_mul_f32 v[8:9], v[236:237], v[210:211] op_sel:[1,0] op_sel_hi:[1,1]
	v_pk_mul_f32 v[10:11], v[48:49], v[210:211] op_sel:[0,0] op_sel_hi:[0,1]
	v_fma_f32 v200, -v203, v218, v120
	v_mul_f32_e32 v120, v202, v218
	s_nop 0
	v_pk_fma_f32 v[8:9], v[242:243], v[210:211], v[8:9] op_sel:[0,1,0] op_sel_hi:[0,0,1] neg_lo:[1,0,0] neg_hi:[0,0,0]
	v_pk_fma_f32 v[10:11], v[48:49], v[210:211], v[10:11] op_sel:[1,1,0] op_sel_hi:[1,0,1] neg_lo:[1,0,0] neg_hi:[0,0,0]
	ds_write_b64 v142, v[8:9] offset:128
	ds_write_b64 v141, v[10:11] offset:4224
	v_pk_mul_f32 v[8:9], v[242:243], v[208:209] op_sel:[1,0] op_sel_hi:[1,1]
	v_pk_mul_f32 v[10:11], v[234:235], v[208:209] op_sel:[1,0] op_sel_hi:[1,1]
	v_fma_f32 v201, v203, v217, v120
	v_mul_f32_e32 v120, v208, v208
	s_nop 0
	v_pk_fma_f32 v[8:9], v[244:245], v[208:209], v[8:9] op_sel:[0,1,0] op_sel_hi:[0,0,1] neg_lo:[1,0,0] neg_hi:[0,0,0]
	v_pk_fma_f32 v[10:11], v[240:241], v[208:209], v[10:11] op_sel:[1,1,0] op_sel_hi:[1,0,1] neg_lo:[1,0,0] neg_hi:[0,0,0]
	ds_write_b64 v142, v[8:9] offset:160
	ds_write_b64 v141, v[10:11] offset:4256
	v_pk_mul_f32 v[8:9], v[170:171], v[206:207] op_sel:[1,0] op_sel_hi:[1,1]
	v_pk_mul_f32 v[10:11], v[246:247], v[206:207] op_sel:[1,0] op_sel_hi:[1,1]
	v_fma_f32 v198, -v209, v209, v120
	v_mul_f32_e32 v120, v208, v209
	s_nop 0
	v_pk_fma_f32 v[8:9], v[212:213], v[206:207], v[8:9] op_sel:[0,1,0] op_sel_hi:[0,0,1] neg_lo:[1,0,0] neg_hi:[0,0,0]
	v_pk_fma_f32 v[10:11], v[248:249], v[206:207], v[10:11] op_sel:[0,1,0] op_sel_hi:[0,0,1] neg_lo:[1,0,0] neg_hi:[0,0,0]
	ds_write_b64 v142, v[8:9] offset:192
	ds_write_b64 v141, v[10:11] offset:4288
	v_pk_mul_f32 v[8:9], v[150:151], v[204:205] op_sel:[1,0] op_sel_hi:[1,1]
	v_pk_mul_f32 v[10:11], v[38:39], v[204:205] op_sel:[1,0] op_sel_hi:[1,1]
	v_fma_f32 v199, v209, v208, v120
	v_mul_f32_e32 v120, v202, v213
	s_nop 0
	v_pk_fma_f32 v[8:9], v[170:171], v[204:205], v[8:9] op_sel:[0,1,0] op_sel_hi:[0,0,1] neg_lo:[1,0,0] neg_hi:[0,0,0]
	v_pk_fma_f32 v[10:11], v[42:43], v[204:205], v[10:11] op_sel:[1,1,0] op_sel_hi:[1,0,1] neg_lo:[1,0,0] neg_hi:[0,0,0]
	ds_write_b64 v142, v[8:9] offset:224
	ds_write_b64 v141, v[10:11] offset:4320
	v_pk_mul_f32 v[8:9], v[226:227], v[202:203] op_sel:[1,0] op_sel_hi:[1,1]
	v_pk_mul_f32 v[10:11], v[40:41], v[202:203] op_sel:[0,0] op_sel_hi:[0,1]
	v_fma_f32 v196, -v203, v214, v120
	v_mul_f32_e32 v120, v202, v214
	s_nop 0
	v_pk_fma_f32 v[8:9], v[228:229], v[202:203], v[8:9] op_sel:[0,1,0] op_sel_hi:[0,0,1] neg_lo:[1,0,0] neg_hi:[0,0,0]
	v_pk_fma_f32 v[10:11], v[40:41], v[202:203], v[10:11] op_sel:[1,1,0] op_sel_hi:[1,0,1] neg_lo:[1,0,0] neg_hi:[0,0,0]
	ds_write_b64 v142, v[8:9] offset:256
	ds_write_b64 v141, v[10:11] offset:4352
	v_pk_mul_f32 v[8:9], v[228:229], v[200:201] op_sel:[1,0] op_sel_hi:[1,1]
	v_pk_mul_f32 v[10:11], v[24:25], v[200:201] op_sel:[0,0] op_sel_hi:[0,1]
	v_fma_f32 v197, v203, v213, v120
	v_mul_f32_e32 v120, v206, v206
	s_nop 0
	v_pk_fma_f32 v[8:9], v[230:231], v[200:201], v[8:9] op_sel:[0,1,0] op_sel_hi:[0,0,1] neg_lo:[1,0,0] neg_hi:[0,0,0]
	v_pk_fma_f32 v[10:11], v[24:25], v[200:201], v[10:11] op_sel:[1,1,0] op_sel_hi:[1,0,1] neg_lo:[1,0,0] neg_hi:[0,0,0]
	ds_write_b64 v142, v[8:9] offset:288
	ds_write_b64 v141, v[10:11] offset:4384
	v_pk_mul_f32 v[8:9], v[230:231], v[198:199] op_sel:[1,0] op_sel_hi:[1,1]
	v_pk_mul_f32 v[10:11], v[46:47], v[198:199] op_sel:[0,0] op_sel_hi:[0,1]
	v_fma_f32 v132, -v207, v207, v120
	v_mul_f32_e32 v120, v206, v207
	s_nop 0
	v_pk_fma_f32 v[8:9], v[232:233], v[198:199], v[8:9] op_sel:[0,1,0] op_sel_hi:[0,0,1] neg_lo:[1,0,0] neg_hi:[0,0,0]
	v_pk_fma_f32 v[10:11], v[46:47], v[198:199], v[10:11] op_sel:[1,1,0] op_sel_hi:[1,0,1] neg_lo:[1,0,0] neg_hi:[0,0,0]
	ds_write_b64 v142, v[8:9] offset:320
	ds_write_b64 v141, v[10:11] offset:4416
	v_pk_mul_f32 v[8:9], v[232:233], v[196:197] op_sel:[1,0] op_sel_hi:[1,1]
	v_pk_mul_f32 v[10:11], v[20:21], v[196:197] op_sel:[1,0] op_sel_hi:[1,1]
	v_fma_f32 v134, v207, v206, v120
	v_mul_f32_e32 v120, v202, v208
	s_nop 0
	v_pk_fma_f32 v[8:9], v[234:235], v[196:197], v[8:9] op_sel:[0,1,0] op_sel_hi:[0,0,1] neg_lo:[1,0,0] neg_hi:[0,0,0]
	v_pk_fma_f32 v[10:11], v[22:23], v[196:197], v[10:11] op_sel:[1,1,0] op_sel_hi:[1,0,1] neg_lo:[1,0,0] neg_hi:[0,0,0]
	ds_write_b64 v142, v[8:9] offset:352
	ds_write_b64 v141, v[10:11] offset:4448
	v_mul_f32_e32 v8, v219, v132
	v_mul_f32_e32 v9, v219, v134
	v_mul_f32_e32 v10, v17, v132
	v_mul_f32_e32 v11, v17, v134
	v_fma_f32 v128, -v203, v209, v120
	v_mul_f32_e32 v120, v202, v209
	s_nop 0
	v_fma_f32 v8, -v220, v134, v8
	v_fma_f32 v9, v220, v132, v9
	v_fma_f32 v10, -v16, v134, v10
	v_fma_f32 v11, v16, v132, v11
	ds_write_b64 v142, v[8:9] offset:384
	ds_write_b64 v141, v[10:11] offset:4480
	v_fma_f32 v130, v203, v208, v120
	v_mul_f32_e32 v8, v221, v128
	v_mul_f32_e32 v120, v204, v204
	v_mul_f32_e32 v10, v42, v128
	v_fma_f32 v122, v203, v204, v122
	v_sub_f32_e32 v15, v20, v15
	s_nop 0
	v_mul_f32_e32 v9, v221, v130
	v_fma_f32 v8, -v222, v130, v8
	v_mul_f32_e32 v11, v42, v130
	v_fma_f32 v124, -v205, v205, v120
	v_mul_f32_e32 v120, v204, v205
	v_fma_f32 v10, -v26, v130, v10
	s_nop 0
	v_fma_f32 v9, v222, v128, v9
	v_add_f32_e32 v13, v14, v13
	v_fma_f32 v11, v26, v128, v11
	ds_write_b64 v142, v[8:9] offset:416
	ds_write_b64 v141, v[10:11] offset:4512
	v_fma_f32 v126, v205, v204, v120
	v_mul_f32_e32 v8, v223, v124
	v_mul_f32_e32 v120, v202, v204
	v_mul_f32_e32 v10, v12, v124
	v_cvt_f32_f16_e32 v21, v193
	v_mul_f32_e32 v9, v223, v126
	v_fma_f32 v8, -v224, v126, v8
	v_mul_f32_e32 v11, v12, v126
	v_fma_f32 v120, -v203, v205, v120
	v_fma_f32 v10, -v19, v126, v10
	v_cvt_f32_f16_e32 v20, v190
	v_fma_f32 v9, v224, v124, v9
	v_fma_f32 v11, v19, v124, v11
	ds_write_b64 v142, v[8:9] offset:448
	ds_write_b64 v141, v[10:11] offset:4544
	v_mul_f32_e32 v8, v225, v120
	v_mul_f32_e32 v9, v225, v122
	v_mul_f32_e32 v10, v15, v120
	v_mul_f32_e32 v11, v15, v122
	v_pk_mul_f32 v[18:19], v[82:83], v[34:35] op_sel_hi:[0,1]
	v_fma_f32 v8, -v226, v122, v8
	v_fma_f32 v9, v226, v120, v9
	v_fma_f32 v10, -v13, v122, v10
	v_fma_f32 v11, v13, v120, v11
	ds_write_b64 v142, v[8:9] offset:480
	ds_write_b64 v141, v[10:11] offset:4576
	ds_read_b128 v[10:13], v162
	ds_read_b128 v[14:17], v162 offset:16
	v_pk_mul_f32 v[8:9], v[82:83], v[32:33] op_sel_hi:[0,1]
	v_cvt_pk_f16_f32 v9, v8, v9
	v_cvt_pk_f16_f32 v8, v18, v19
	s_waitcnt lgkmcnt(0)
	v_pk_add_f32 v[18:19], v[10:11], v[14:15] op_sel:[0,0] op_sel_hi:[1,1]
	v_pk_add_f32 v[10:11], v[10:11], v[14:15] op_sel:[0,0] op_sel_hi:[1,1] neg_lo:[0,1] neg_hi:[0,1]
	v_pk_add_f32 v[14:15], v[12:13], v[16:17] op_sel:[0,0] op_sel_hi:[1,1]
	v_pk_add_f32 v[12:13], v[12:13], v[16:17] op_sel:[0,0] op_sel_hi:[1,1] neg_lo:[0,1] neg_hi:[0,1]
	v_cvt_f32_f16_e32 v24, v195
	v_pk_add_f32 v[16:17], v[18:19], v[14:15] op_sel:[0,0] op_sel_hi:[1,1]
	v_pk_add_f32 v[14:15], v[18:19], v[14:15] op_sel:[0,0] op_sel_hi:[1,1] neg_lo:[0,1] neg_hi:[0,1]
	v_pk_add_f32 v[18:19], v[10:11], v[12:13] op_sel:[0,1] op_sel_hi:[1,0] neg_lo:[0,0] neg_hi:[0,1]
	v_pk_add_f32 v[10:11], v[10:11], v[12:13] op_sel:[0,1] op_sel_hi:[1,0] neg_lo:[0,1] neg_hi:[0,0]
	v_cvt_f32_f16_sdwa v13, v193 dst_sel:DWORD dst_unused:UNUSED_PAD src0_sel:WORD_1
	v_cvt_f32_f16_sdwa v12, v190 dst_sel:DWORD dst_unused:UNUSED_PAD src0_sel:WORD_1
	v_cvt_f32_f16_sdwa v23, v195 dst_sel:DWORD dst_unused:UNUSED_PAD src0_sel:WORD_1
	v_cvt_f32_f16_e32 v25, v192
	v_cvt_f32_f16_sdwa v22, v192 dst_sel:DWORD dst_unused:UNUSED_PAD src0_sel:WORD_1
	v_pk_add_f32 v[20:21], v[176:177], v[20:21] op_sel:[1,0] op_sel_hi:[1,1]
	v_mul_f32_e32 v13, v13, v17
	v_mul_f32_e32 v17, v21, v17
	v_fma_f32 v13, v21, v16, -v13
	v_fma_mix_f32 v16, v193, v16, v17 op_sel:[1,0,0] op_sel_hi:[1,0,0]
	v_mul_f32_e32 v12, v12, v19
	v_mul_f32_e32 v17, v20, v19
	v_pk_add_f32 v[24:25], v[176:177], v[24:25] op_sel:[1,0] op_sel_hi:[1,1]
	v_fma_f32 v12, v20, v18, -v12
	v_fma_mix_f32 v17, v190, v18, v17 op_sel:[1,0,0] op_sel_hi:[1,0,0]
	v_mul_f32_e32 v18, v23, v15
	v_mul_f32_e32 v15, v24, v15
	v_fma_f32 v18, v24, v14, -v18
	v_fma_mix_f32 v14, v195, v14, v15 op_sel:[1,0,0] op_sel_hi:[1,0,0]
	v_mul_f32_e32 v15, v22, v11
	v_mul_f32_e32 v11, v25, v11
	v_mul_f32_e32 v13, 0x38800000, v13
	v_mul_f32_e32 v18, 0x38800000, v18
	v_fma_f32 v15, v25, v10, -v15
	v_fma_mix_f32 v10, v192, v10, v11 op_sel:[1,0,0] op_sel_hi:[1,0,0]
	v_mul_f32_e32 v16, 0x38800000, v16
	v_mul_f32_e32 v12, 0x38800000, v12
	v_mul_f32_e32 v17, 0x38800000, v17
	v_mul_f32_e32 v14, 0x38800000, v14
	v_mul_f32_e32 v15, 0x38800000, v15
	v_mul_f32_e32 v10, 0x38800000, v10
	v_pk_add_f32 v[18:19], v[12:13], v[18:19] op_sel:[1,0] op_sel_hi:[1,0] neg_lo:[0,1] neg_hi:[0,0]
	v_add_f32_e32 v13, v12, v15
	v_pk_add_f32 v[20:21], v[16:17], v[14:15] op_sel:[0,0] op_sel_hi:[0,0] neg_lo:[0,0] neg_hi:[0,1]
	v_sub_f32_e32 v22, v12, v15
	v_pk_add_f32 v[16:17], v[16:17], v[10:11] op_sel:[1,0] op_sel_hi:[1,0] neg_lo:[0,0] neg_hi:[0,1]
	s_nop 0
	v_add_f32_e32 v10, v19, v13
	v_sub_f32_e32 v14, v19, v13
	v_cvt_f32_f16_e32 v23, v188
	v_add_f32_e32 v11, v20, v16
	v_sub_f32_e32 v12, v18, v17
	v_add_f32_e32 v13, v21, v22
	v_sub_f32_e32 v15, v20, v16
	v_add_f32_e32 v16, v18, v17
	v_sub_f32_e32 v17, v21, v22
	ds_write_b128 v162, v[10:13]
	ds_write_b128 v162, v[14:17] offset:16
	ds_read_b128 v[12:15], v163
	ds_read_b128 v[16:19], v163 offset:16
	v_pk_mul_f32 v[20:21], v[82:83], v[30:31] op_sel_hi:[0,1]
	v_pk_mul_f32 v[10:11], v[82:83], v[28:29] op_sel_hi:[0,1]
	v_cvt_pk_f16_f32 v11, v10, v11
	v_cvt_pk_f16_f32 v10, v20, v21
	s_waitcnt lgkmcnt(0)
	v_pk_add_f32 v[20:21], v[12:13], v[16:17] op_sel:[0,0] op_sel_hi:[1,1]
	v_pk_add_f32 v[12:13], v[12:13], v[16:17] op_sel:[0,0] op_sel_hi:[1,1] neg_lo:[0,1] neg_hi:[0,1]
	v_pk_add_f32 v[16:17], v[14:15], v[18:19] op_sel:[0,0] op_sel_hi:[1,1]
	v_pk_add_f32 v[14:15], v[14:15], v[18:19] op_sel:[0,0] op_sel_hi:[1,1] neg_lo:[0,1] neg_hi:[0,1]
	v_cvt_f32_f16_e32 v22, v186
	v_pk_add_f32 v[18:19], v[20:21], v[16:17] op_sel:[0,0] op_sel_hi:[1,1]
	v_pk_add_f32 v[16:17], v[20:21], v[16:17] op_sel:[0,0] op_sel_hi:[1,1] neg_lo:[0,1] neg_hi:[0,1]
	v_pk_add_f32 v[20:21], v[12:13], v[14:15] op_sel:[0,1] op_sel_hi:[1,0] neg_lo:[0,0] neg_hi:[0,1]
	v_pk_add_f32 v[12:13], v[12:13], v[14:15] op_sel:[0,1] op_sel_hi:[1,0] neg_lo:[0,1] neg_hi:[0,0]
	v_cvt_f32_f16_sdwa v15, v188 dst_sel:DWORD dst_unused:UNUSED_PAD src0_sel:WORD_1
	v_cvt_f32_f16_sdwa v14, v186 dst_sel:DWORD dst_unused:UNUSED_PAD src0_sel:WORD_1
	v_cvt_f32_f16_e32 v26, v189
	v_cvt_f32_f16_sdwa v25, v189 dst_sel:DWORD dst_unused:UNUSED_PAD src0_sel:WORD_1
	v_cvt_f32_f16_e32 v27, v187
	v_cvt_f32_f16_sdwa v24, v187 dst_sel:DWORD dst_unused:UNUSED_PAD src0_sel:WORD_1
	v_pk_add_f32 v[22:23], v[176:177], v[22:23] op_sel:[1,0] op_sel_hi:[1,1]
	v_mul_f32_e32 v15, v15, v19
	v_mul_f32_e32 v19, v23, v19
	v_fma_f32 v15, v23, v18, -v15
	v_fma_mix_f32 v18, v188, v18, v19 op_sel:[1,0,0] op_sel_hi:[1,0,0]
	v_mul_f32_e32 v14, v14, v21
	v_mul_f32_e32 v19, v22, v21
	v_pk_add_f32 v[26:27], v[176:177], v[26:27] op_sel:[1,0] op_sel_hi:[1,1]
	v_fma_f32 v14, v22, v20, -v14
	v_fma_mix_f32 v19, v186, v20, v19 op_sel:[1,0,0] op_sel_hi:[1,0,0]
	v_mul_f32_e32 v20, v25, v17
	v_mul_f32_e32 v17, v26, v17
	v_fma_f32 v20, v26, v16, -v20
	v_fma_mix_f32 v16, v189, v16, v17 op_sel:[1,0,0] op_sel_hi:[1,0,0]
	v_mul_f32_e32 v17, v24, v13
	v_mul_f32_e32 v13, v27, v13
	v_mul_f32_e32 v15, 0x38800000, v15
	v_mul_f32_e32 v20, 0x38800000, v20
	v_fma_f32 v17, v27, v12, -v17
	v_fma_mix_f32 v12, v187, v12, v13 op_sel:[1,0,0] op_sel_hi:[1,0,0]
	v_mul_f32_e32 v18, 0x38800000, v18
	v_mul_f32_e32 v14, 0x38800000, v14
	v_mul_f32_e32 v19, 0x38800000, v19
	v_mul_f32_e32 v16, 0x38800000, v16
	v_mul_f32_e32 v17, 0x38800000, v17
	v_mul_f32_e32 v12, 0x38800000, v12
	v_pk_add_f32 v[20:21], v[14:15], v[20:21] op_sel:[1,0] op_sel_hi:[1,0] neg_lo:[0,1] neg_hi:[0,0]
	v_add_f32_e32 v15, v14, v17
	v_pk_add_f32 v[22:23], v[18:19], v[16:17] op_sel:[0,0] op_sel_hi:[0,0] neg_lo:[0,0] neg_hi:[0,1]
	v_sub_f32_e32 v24, v14, v17
	v_pk_add_f32 v[18:19], v[18:19], v[12:13] op_sel:[1,0] op_sel_hi:[1,0] neg_lo:[0,0] neg_hi:[0,1]
	s_nop 0
	v_add_f32_e32 v12, v21, v15
	v_sub_f32_e32 v16, v21, v15
	v_add_f32_e32 v13, v22, v18
	v_add_f32_e32 v15, v23, v24
	v_sub_f32_e32 v14, v20, v19
	v_sub_f32_e32 v17, v22, v18
	v_add_f32_e32 v18, v20, v19
	v_sub_f32_e32 v19, v23, v24
	ds_write_b128 v163, v[12:15]
	ds_write_b128 v163, v[16:19] offset:16
	ds_read_b128 v[12:15], v164
	ds_read_b128 v[16:19], v164 offset:16
	v_pk_add_f32 v[20:21], v[0:1], v[4:5] op_sel:[0,0] op_sel_hi:[1,1]
	v_pk_add_f32 v[22:23], v[0:1], v[4:5] op_sel:[0,0] op_sel_hi:[1,1] neg_lo:[0,1] neg_hi:[0,1]
	s_waitcnt lgkmcnt(0)
	v_pk_add_f32 v[0:1], v[12:13], v[16:17] op_sel:[0,0] op_sel_hi:[1,1]
	v_pk_add_f32 v[4:5], v[12:13], v[16:17] op_sel:[0,0] op_sel_hi:[1,1] neg_lo:[0,1] neg_hi:[0,1]
	v_pk_add_f32 v[12:13], v[14:15], v[18:19] op_sel:[0,0] op_sel_hi:[1,1]
	v_pk_add_f32 v[14:15], v[14:15], v[18:19] op_sel:[0,0] op_sel_hi:[1,1] neg_lo:[0,1] neg_hi:[0,1]
	v_cvt_f32_f16_e32 v18, v182
	v_pk_add_f32 v[16:17], v[0:1], v[12:13] op_sel:[0,0] op_sel_hi:[1,1]
	v_pk_add_f32 v[0:1], v[0:1], v[12:13] op_sel:[0,0] op_sel_hi:[1,1] neg_lo:[0,1] neg_hi:[0,1]
	v_pk_add_f32 v[12:13], v[4:5], v[14:15] op_sel:[0,1] op_sel_hi:[1,0] neg_lo:[0,0] neg_hi:[0,1]
	v_pk_add_f32 v[4:5], v[4:5], v[14:15] op_sel:[0,1] op_sel_hi:[1,0] neg_lo:[0,1] neg_hi:[0,0]
	v_cvt_f32_f16_sdwa v14, v182 dst_sel:DWORD dst_unused:UNUSED_PAD src0_sel:WORD_1
	v_cvt_f32_f16_e32 v26, v185
	v_cvt_f32_f16_sdwa v15, v184 dst_sel:DWORD dst_unused:UNUSED_PAD src0_sel:WORD_1
	v_cvt_f32_f16_e32 v19, v184
	v_cvt_f32_f16_sdwa v25, v185 dst_sel:DWORD dst_unused:UNUSED_PAD src0_sel:WORD_1
	v_cvt_f32_f16_e32 v27, v183
	v_cvt_f32_f16_sdwa v24, v183 dst_sel:DWORD dst_unused:UNUSED_PAD src0_sel:WORD_1
	v_pk_add_f32 v[18:19], v[176:177], v[18:19] op_sel:[1,0] op_sel_hi:[1,1]
	v_mul_f32_e32 v14, v14, v13
	v_mul_f32_e32 v13, v18, v13
	v_pk_add_f32 v[26:27], v[176:177], v[26:27] op_sel:[1,0] op_sel_hi:[1,1]
	v_mul_f32_e32 v15, v15, v17
	v_fma_f32 v14, v18, v12, -v14
	v_fma_mix_f32 v12, v182, v12, v13 op_sel:[1,0,0] op_sel_hi:[1,0,0]
	v_mul_f32_e32 v13, v25, v1
	v_mul_f32_e32 v1, v26, v1
	v_fma_f32 v15, v19, v16, -v15
	v_mul_f32_e32 v17, v19, v17
	v_fma_f32 v13, v26, v0, -v13
	v_fma_mix_f32 v0, v185, v0, v1 op_sel:[1,0,0] op_sel_hi:[1,0,0]
	v_mul_f32_e32 v1, v24, v5
	v_mul_f32_e32 v5, v27, v5
	v_mul_f32_e32 v15, 0x38800000, v15
	v_fma_mix_f32 v16, v184, v16, v17 op_sel:[1,0,0] op_sel_hi:[1,0,0]
	v_fma_f32 v1, v27, v4, -v1
	v_fma_mix_f32 v4, v183, v4, v5 op_sel:[1,0,0] op_sel_hi:[1,0,0]
	v_mul_f32_e32 v16, 0x38800000, v16
	v_mul_f32_e32 v14, 0x38800000, v14
	v_mul_f32_e32 v12, 0x38800000, v12
	v_mul_f32_e32 v13, 0x38800000, v13
	v_mul_f32_e32 v0, 0x38800000, v0
	v_mul_f32_e32 v1, 0x38800000, v1
	v_mul_f32_e32 v4, 0x38800000, v4
	v_add_f32_e32 v5, v15, v13
	v_sub_f32_e32 v18, v15, v13
	v_add_f32_e32 v15, v14, v1
	v_add_f32_e32 v17, v16, v0
	v_sub_f32_e32 v0, v16, v0
	v_add_f32_e32 v19, v12, v4
	v_sub_f32_e32 v1, v14, v1
	v_sub_f32_e32 v4, v12, v4
	s_nop 0
	v_add_f32_e32 v12, v5, v15
	v_sub_f32_e32 v16, v5, v15
	v_add_f32_e32 v13, v17, v19
	v_add_f32_e32 v15, v0, v1
	v_sub_f32_e32 v14, v18, v4
	v_sub_f32_e32 v17, v17, v19
	v_add_f32_e32 v18, v18, v4
	v_sub_f32_e32 v19, v0, v1
	ds_write_b128 v164, v[12:15]
	ds_write_b128 v164, v[16:19] offset:16
	ds_read_b128 v[12:15], v165
	ds_read_b128 v[16:19], v165 offset:16
	v_pk_add_f32 v[24:25], v[2:3], v[6:7] op_sel:[0,0] op_sel_hi:[1,1]
	v_pk_add_f32 v[26:27], v[2:3], v[6:7] op_sel:[0,0] op_sel_hi:[1,1] neg_lo:[0,1] neg_hi:[0,1]
	s_waitcnt lgkmcnt(0)
	v_add_f32_e32 v1, v13, v17
	v_sub_f32_e32 v3, v13, v17
	v_pk_add_f32 v[4:5], v[14:15], v[18:19] op_sel:[0,0] op_sel_hi:[1,1]
	v_pk_add_f32 v[6:7], v[14:15], v[18:19] op_sel:[0,0] op_sel_hi:[1,1] neg_lo:[0,1] neg_hi:[0,1]
	v_cvt_f32_f16_e32 v14, v178
	v_add_f32_e32 v13, v1, v5
	v_sub_f32_e32 v1, v1, v5
	v_sub_f32_e32 v5, v3, v6
	v_add_f32_e32 v3, v3, v6
	v_cvt_f32_f16_sdwa v6, v178 dst_sel:DWORD dst_unused:UNUSED_PAD src0_sel:WORD_1
	v_cvt_f32_f16_e32 v18, v181
	v_add_f32_e32 v0, v12, v16
	v_sub_f32_e32 v2, v12, v16
	v_cvt_f32_f16_e32 v15, v180
	v_cvt_f32_f16_sdwa v17, v181 dst_sel:DWORD dst_unused:UNUSED_PAD src0_sel:WORD_1
	v_cvt_f32_f16_e32 v19, v179
	v_add_f32_e32 v12, v0, v4
	v_sub_f32_e32 v0, v0, v4
	v_add_f32_e32 v4, v2, v7
	v_sub_f32_e32 v2, v2, v7
	v_cvt_f32_f16_sdwa v7, v180 dst_sel:DWORD dst_unused:UNUSED_PAD src0_sel:WORD_1
	v_cvt_f32_f16_sdwa v16, v179 dst_sel:DWORD dst_unused:UNUSED_PAD src0_sel:WORD_1
	v_pk_add_f32 v[14:15], v[176:177], v[14:15] op_sel:[1,0] op_sel_hi:[1,1]
	v_mul_f32_e32 v6, v6, v5
	v_mul_f32_e32 v5, v14, v5
	v_pk_add_f32 v[18:19], v[176:177], v[18:19] op_sel:[1,0] op_sel_hi:[1,1]
	v_fma_f32 v6, v14, v4, -v6
	v_fma_mix_f32 v4, v178, v4, v5 op_sel:[1,0,0] op_sel_hi:[1,0,0]
	v_mul_f32_e32 v5, v17, v1
	v_mul_f32_e32 v1, v18, v1
	v_mul_f32_e32 v7, v7, v13
	v_mul_f32_e32 v13, v15, v13
	v_fma_f32 v5, v18, v0, -v5
	v_fma_mix_f32 v0, v181, v0, v1 op_sel:[1,0,0] op_sel_hi:[1,0,0]
	v_mul_f32_e32 v1, v16, v3
	v_mul_f32_e32 v3, v19, v3
	v_fma_f32 v7, v15, v12, -v7
	v_fma_mix_f32 v12, v180, v12, v13 op_sel:[1,0,0] op_sel_hi:[1,0,0]
	v_fma_f32 v1, v19, v2, -v1
	v_fma_mix_f32 v2, v179, v2, v3 op_sel:[1,0,0] op_sel_hi:[1,0,0]
	v_mul_f32_e32 v7, 0x38800000, v7
	v_mul_f32_e32 v12, 0x38800000, v12
	v_mul_f32_e32 v6, 0x38800000, v6
	v_mul_f32_e32 v4, 0x38800000, v4
	v_mul_f32_e32 v5, 0x38800000, v5
	v_mul_f32_e32 v0, 0x38800000, v0
	v_mul_f32_e32 v1, 0x38800000, v1
	v_mul_f32_e32 v2, 0x38800000, v2
	v_add_f32_e32 v3, v7, v5
	v_sub_f32_e32 v7, v7, v5
	v_pk_add_f32 v[12:13], v[12:13], v[0:1] op_sel:[0,0] op_sel_hi:[0,0] neg_lo:[0,1] neg_hi:[0,0]
	v_add_f32_e32 v5, v6, v1
	v_add_f32_e32 v14, v4, v2
	v_sub_f32_e32 v15, v6, v1
	v_sub_f32_e32 v6, v4, v2
	v_cvt_f32_f16_e32 v19, v194
	v_add_f32_e32 v0, v3, v5
	v_add_f32_e32 v1, v13, v14
	v_sub_f32_e32 v4, v3, v5
	v_sub_f32_e32 v2, v7, v6
	v_add_f32_e32 v3, v12, v15
	v_sub_f32_e32 v5, v13, v14
	v_add_f32_e32 v6, v7, v6
	v_sub_f32_e32 v7, v12, v15
	ds_write_b128 v165, v[0:3]
	ds_write_b128 v165, v[4:7] offset:16
	ds_read_b128 v[2:5], v166
	ds_read_b128 v[12:15], v166 offset:16
	s_waitcnt lgkmcnt(0)
	v_pk_add_f32 v[16:17], v[2:3], v[12:13] op_sel:[0,0] op_sel_hi:[1,1]
	v_pk_add_f32 v[2:3], v[2:3], v[12:13] op_sel:[0,0] op_sel_hi:[1,1] neg_lo:[0,1] neg_hi:[0,1]
	v_pk_add_f32 v[12:13], v[4:5], v[14:15] op_sel:[0,0] op_sel_hi:[1,1]
	v_pk_add_f32 v[4:5], v[4:5], v[14:15] op_sel:[0,0] op_sel_hi:[1,1] neg_lo:[0,1] neg_hi:[0,1]
	v_cvt_f32_f16_e32 v18, v191
	v_pk_add_f32 v[14:15], v[16:17], v[12:13] op_sel:[0,0] op_sel_hi:[1,1]
	v_pk_add_f32 v[12:13], v[16:17], v[12:13] op_sel:[0,0] op_sel_hi:[1,1] neg_lo:[0,1] neg_hi:[0,1]
	v_pk_add_f32 v[16:17], v[2:3], v[4:5] op_sel:[0,1] op_sel_hi:[1,0] neg_lo:[0,0] neg_hi:[0,1]
	v_pk_add_f32 v[2:3], v[2:3], v[4:5] op_sel:[0,1] op_sel_hi:[1,0] neg_lo:[0,1] neg_hi:[0,0]
	v_cvt_f32_f16_sdwa v5, v194 dst_sel:DWORD dst_unused:UNUSED_PAD src0_sel:WORD_1
	v_pk_add_f32 v[6:7], v[20:21], v[24:25] op_sel:[0,0] op_sel_hi:[1,1]
	v_pk_add_f32 v[0:1], v[20:21], v[24:25] op_sel:[0,0] op_sel_hi:[1,1] neg_lo:[0,1] neg_hi:[0,1]
	v_cvt_f32_f16_sdwa v4, v191 dst_sel:DWORD dst_unused:UNUSED_PAD src0_sel:WORD_1
	v_cvt_f32_f16_e32 v24, v131
	v_cvt_f32_f16_sdwa v21, v131 dst_sel:DWORD dst_unused:UNUSED_PAD src0_sel:WORD_1
	v_cvt_f32_f16_e32 v25, v129
	v_cvt_f32_f16_sdwa v20, v129 dst_sel:DWORD dst_unused:UNUSED_PAD src0_sel:WORD_1
	v_pk_add_f32 v[18:19], v[176:177], v[18:19] op_sel:[1,0] op_sel_hi:[1,1]
	v_mul_f32_e32 v5, v5, v15
	v_mul_f32_e32 v15, v19, v15
	v_fma_f32 v5, v19, v14, -v5
	v_fma_mix_f32 v14, v194, v14, v15 op_sel:[1,0,0] op_sel_hi:[1,0,0]
	v_mul_f32_e32 v4, v4, v17
	v_mul_f32_e32 v15, v18, v17
	v_pk_add_f32 v[24:25], v[176:177], v[24:25] op_sel:[1,0] op_sel_hi:[1,1]
	v_fma_f32 v4, v18, v16, -v4
	v_fma_mix_f32 v15, v191, v16, v15 op_sel:[1,0,0] op_sel_hi:[1,0,0]
	v_mul_f32_e32 v16, v21, v13
	v_mul_f32_e32 v13, v24, v13
	v_fma_f32 v16, v24, v12, -v16
	v_fma_mix_f32 v12, v131, v12, v13 op_sel:[1,0,0] op_sel_hi:[1,0,0]
	v_mul_f32_e32 v13, v20, v3
	v_mul_f32_e32 v3, v25, v3
	v_mul_f32_e32 v5, 0x38800000, v5
	v_mul_f32_e32 v16, 0x38800000, v16
	v_fma_f32 v13, v25, v2, -v13
	v_fma_mix_f32 v2, v129, v2, v3 op_sel:[1,0,0] op_sel_hi:[1,0,0]
	v_mul_f32_e32 v14, 0x38800000, v14
	v_mul_f32_e32 v4, 0x38800000, v4
	v_mul_f32_e32 v15, 0x38800000, v15
	v_mul_f32_e32 v12, 0x38800000, v12
	v_mul_f32_e32 v13, 0x38800000, v13
	v_mul_f32_e32 v2, 0x38800000, v2
	v_pk_add_f32 v[16:17], v[4:5], v[16:17] op_sel:[1,0] op_sel_hi:[1,0] neg_lo:[0,1] neg_hi:[0,0]
	v_add_f32_e32 v5, v4, v13
	v_pk_add_f32 v[18:19], v[14:15], v[12:13] op_sel:[0,0] op_sel_hi:[0,0] neg_lo:[0,0] neg_hi:[0,1]
	v_sub_f32_e32 v20, v4, v13
	v_pk_add_f32 v[14:15], v[14:15], v[2:3] op_sel:[1,0] op_sel_hi:[1,0] neg_lo:[0,0] neg_hi:[0,1]
	s_nop 0
	v_add_f32_e32 v2, v17, v5
	v_sub_f32_e32 v12, v17, v5
	v_sub_f32_e32 v17, v23, v26
	v_add_f32_e32 v3, v18, v14
	v_add_f32_e32 v5, v19, v20
	v_sub_f32_e32 v4, v16, v15
	v_sub_f32_e32 v13, v18, v14
	v_add_f32_e32 v14, v16, v15
	v_sub_f32_e32 v15, v19, v20
	ds_write_b128 v166, v[2:5]
	ds_write_b128 v166, v[12:15] offset:16
	ds_read_b128 v[2:5], v167
	ds_read_b128 v[12:15], v167 offset:16
	v_add_f32_e32 v19, v23, v26
	s_waitcnt lgkmcnt(0)
	v_pk_add_f32 v[20:21], v[2:3], v[12:13] op_sel:[0,0] op_sel_hi:[1,1]
	v_pk_add_f32 v[2:3], v[2:3], v[12:13] op_sel:[0,0] op_sel_hi:[1,1] neg_lo:[0,1] neg_hi:[0,1]
	v_pk_add_f32 v[12:13], v[4:5], v[14:15] op_sel:[0,0] op_sel_hi:[1,1]
	v_cvt_f32_f16_e32 v23, v127
	v_add_f32_e32 v16, v22, v27
	v_sub_f32_e32 v18, v22, v27
	v_pk_add_f32 v[4:5], v[4:5], v[14:15] op_sel:[0,0] op_sel_hi:[1,1] neg_lo:[0,1] neg_hi:[0,1]
	v_pk_add_f32 v[14:15], v[20:21], v[12:13] op_sel:[0,0] op_sel_hi:[1,1]
	v_pk_add_f32 v[12:13], v[20:21], v[12:13] op_sel:[0,0] op_sel_hi:[1,1] neg_lo:[0,1] neg_hi:[0,1]
	v_pk_add_f32 v[20:21], v[2:3], v[4:5] op_sel:[0,1] op_sel_hi:[1,0] neg_lo:[0,0] neg_hi:[0,1]
	v_pk_add_f32 v[2:3], v[2:3], v[4:5] op_sel:[0,1] op_sel_hi:[1,0] neg_lo:[0,1] neg_hi:[0,0]
	v_cvt_f32_f16_sdwa v5, v127 dst_sel:DWORD dst_unused:UNUSED_PAD src0_sel:WORD_1
	v_cvt_f32_f16_e32 v22, v125
	v_cvt_f32_f16_sdwa v4, v125 dst_sel:DWORD dst_unused:UNUSED_PAD src0_sel:WORD_1
	v_cvt_f32_f16_e32 v26, v123
	v_cvt_f32_f16_sdwa v25, v123 dst_sel:DWORD dst_unused:UNUSED_PAD src0_sel:WORD_1
	v_cvt_f32_f16_e32 v27, v121
	v_cvt_f32_f16_sdwa v24, v121 dst_sel:DWORD dst_unused:UNUSED_PAD src0_sel:WORD_1
	v_pk_add_f32 v[22:23], v[176:177], v[22:23] op_sel:[1,0] op_sel_hi:[1,1]
	v_mul_f32_e32 v5, v5, v15
	v_mul_f32_e32 v15, v23, v15
	v_fma_f32 v5, v23, v14, -v5
	v_fma_mix_f32 v14, v127, v14, v15 op_sel:[1,0,0] op_sel_hi:[1,0,0]
	v_mul_f32_e32 v4, v4, v21
	v_mul_f32_e32 v15, v22, v21
	v_pk_add_f32 v[26:27], v[176:177], v[26:27] op_sel:[1,0] op_sel_hi:[1,1]
	v_fma_f32 v4, v22, v20, -v4
	v_fma_mix_f32 v15, v125, v20, v15 op_sel:[1,0,0] op_sel_hi:[1,0,0]
	v_mul_f32_e32 v20, v25, v13
	v_mul_f32_e32 v13, v26, v13
	v_fma_f32 v20, v26, v12, -v20
	v_fma_mix_f32 v12, v123, v12, v13 op_sel:[1,0,0] op_sel_hi:[1,0,0]
	v_mul_f32_e32 v13, v24, v3
	v_mul_f32_e32 v3, v27, v3
	v_mul_f32_e32 v5, 0x38800000, v5
	v_mul_f32_e32 v20, 0x38800000, v20
	v_fma_f32 v13, v27, v2, -v13
	v_fma_mix_f32 v2, v121, v2, v3 op_sel:[1,0,0] op_sel_hi:[1,0,0]
	v_mul_f32_e32 v14, 0x38800000, v14
	v_mul_f32_e32 v4, 0x38800000, v4
	v_mul_f32_e32 v15, 0x38800000, v15
	v_mul_f32_e32 v12, 0x38800000, v12
	v_mul_f32_e32 v13, 0x38800000, v13
	v_mul_f32_e32 v2, 0x38800000, v2
	v_pk_add_f32 v[20:21], v[4:5], v[20:21] op_sel:[1,0] op_sel_hi:[1,0] neg_lo:[0,1] neg_hi:[0,0]
	v_add_f32_e32 v5, v4, v13
	v_pk_add_f32 v[22:23], v[14:15], v[12:13] op_sel:[0,0] op_sel_hi:[0,0] neg_lo:[0,0] neg_hi:[0,1]
	v_sub_f32_e32 v24, v4, v13
	v_pk_add_f32 v[14:15], v[14:15], v[2:3] op_sel:[1,0] op_sel_hi:[1,0] neg_lo:[0,0] neg_hi:[0,1]
	s_nop 0
	v_add_f32_e32 v2, v21, v5
	v_sub_f32_e32 v12, v21, v5
	v_pk_mul_f32 v[16:17], v[82:83], v[16:17] op_sel_hi:[0,1]
	v_add_f32_e32 v3, v22, v14
	v_sub_f32_e32 v4, v20, v15
	v_add_f32_e32 v5, v23, v24
	v_sub_f32_e32 v13, v22, v14
	v_add_f32_e32 v14, v20, v15
	v_sub_f32_e32 v15, v23, v24
	ds_write_b128 v167, v[2:5]
	ds_write_b128 v167, v[12:15] offset:16
	ds_read_b128 v[2:5], v168
	ds_read_b128 v[12:15], v168 offset:16
	v_pk_mul_f32 v[6:7], v[82:83], v[6:7] op_sel_hi:[0,1]
	v_cvt_pk_f16_f32 v20, v6, v7
	v_cvt_pk_f16_f32 v16, v16, v17
	s_waitcnt lgkmcnt(0)
	v_pk_add_f32 v[6:7], v[2:3], v[12:13] op_sel:[0,0] op_sel_hi:[1,1]
	v_pk_add_f32 v[2:3], v[2:3], v[12:13] op_sel:[0,0] op_sel_hi:[1,1] neg_lo:[0,1] neg_hi:[0,1]
	v_pk_add_f32 v[12:13], v[4:5], v[14:15] op_sel:[0,0] op_sel_hi:[1,1]
	v_cvt_f32_f16_e32 v17, v8
	v_pk_add_f32 v[4:5], v[4:5], v[14:15] op_sel:[0,0] op_sel_hi:[1,1] neg_lo:[0,1] neg_hi:[0,1]
	v_pk_add_f32 v[14:15], v[6:7], v[12:13] op_sel:[0,0] op_sel_hi:[1,1]
	v_pk_add_f32 v[6:7], v[6:7], v[12:13] op_sel:[0,0] op_sel_hi:[1,1] neg_lo:[0,1] neg_hi:[0,1]
	v_pk_add_f32 v[12:13], v[2:3], v[4:5] op_sel:[0,1] op_sel_hi:[1,0] neg_lo:[0,0] neg_hi:[0,1]
	v_pk_add_f32 v[2:3], v[2:3], v[4:5] op_sel:[0,1] op_sel_hi:[1,0] neg_lo:[0,1] neg_hi:[0,0]
	v_cvt_f32_f16_sdwa v4, v8 dst_sel:DWORD dst_unused:UNUSED_PAD src0_sel:WORD_1
	v_cvt_f32_f16_e32 v24, v11
	v_cvt_f32_f16_sdwa v5, v9 dst_sel:DWORD dst_unused:UNUSED_PAD src0_sel:WORD_1
	v_cvt_f32_f16_e32 v21, v9
	v_cvt_f32_f16_sdwa v23, v11 dst_sel:DWORD dst_unused:UNUSED_PAD src0_sel:WORD_1
	v_cvt_f32_f16_e32 v25, v10
	v_cvt_f32_f16_sdwa v22, v10 dst_sel:DWORD dst_unused:UNUSED_PAD src0_sel:WORD_1
	v_add_f32_e32 v17, v177, v17
	v_mul_f32_e32 v4, v4, v13
	v_mul_f32_e32 v13, v17, v13
	v_add_f32_e32 v21, v177, v21
	v_pk_add_f32 v[24:25], v[176:177], v[24:25] op_sel:[1,0] op_sel_hi:[1,1]
	v_mul_f32_e32 v5, v5, v15
	v_fma_f32 v4, v17, v12, -v4
	v_fma_mix_f32 v8, v8, v12, v13 op_sel:[1,0,0] op_sel_hi:[1,0,0]
	v_mul_f32_e32 v12, v23, v7
	v_mul_f32_e32 v7, v24, v7
	v_fma_f32 v5, v21, v14, -v5
	v_mul_f32_e32 v15, v21, v15
	v_fma_f32 v12, v24, v6, -v12
	v_fma_mix_f32 v6, v11, v6, v7 op_sel:[1,0,0] op_sel_hi:[1,0,0]
	v_mul_f32_e32 v7, v22, v3
	v_mul_f32_e32 v3, v25, v3
	v_mul_f32_e32 v5, 0x38800000, v5
	v_fma_mix_f32 v9, v9, v14, v15 op_sel:[1,0,0] op_sel_hi:[1,0,0]
	v_mul_f32_e32 v12, 0x38800000, v12
	v_fma_f32 v7, v25, v2, -v7
	v_fma_mix_f32 v2, v10, v2, v3 op_sel:[1,0,0] op_sel_hi:[1,0,0]
	v_mul_f32_e32 v9, 0x38800000, v9
	v_mul_f32_e32 v4, 0x38800000, v4
	v_mul_f32_e32 v8, 0x38800000, v8
	v_mul_f32_e32 v6, 0x38800000, v6
	v_mul_f32_e32 v7, 0x38800000, v7
	v_mul_f32_e32 v2, 0x38800000, v2
	v_add_f32_e32 v10, v5, v12
	v_sub_f32_e32 v12, v5, v12
	v_add_f32_e32 v5, v4, v7
	v_add_f32_e32 v11, v9, v6
	v_sub_f32_e32 v9, v9, v6
	v_add_f32_e32 v13, v8, v2
	v_sub_f32_e32 v14, v4, v7
	v_sub_f32_e32 v8, v8, v2
	s_nop 0
	v_add_f32_e32 v2, v10, v5
	v_sub_f32_e32 v6, v10, v5
	v_pk_mul_f32 v[0:1], v[82:83], v[0:1] op_sel_hi:[0,1]
	v_add_f32_e32 v3, v11, v13
	v_sub_f32_e32 v4, v12, v8
	v_add_f32_e32 v5, v9, v14
	v_sub_f32_e32 v7, v11, v13
	v_add_f32_e32 v8, v12, v8
	v_sub_f32_e32 v9, v9, v14
	ds_write_b128 v168, v[2:5]
	ds_write_b128 v168, v[6:9] offset:16
	ds_read_b128 v[2:5], v169
	ds_read_b128 v[6:9], v169 offset:16
	v_pk_mul_f32 v[10:11], v[82:83], v[18:19] op_sel_hi:[0,1]
	v_cvt_pk_f16_f32 v0, v0, v1
	v_cvt_pk_f16_f32 v1, v10, v11
	s_waitcnt lgkmcnt(0)
	v_pk_add_f32 v[10:11], v[2:3], v[6:7] op_sel:[0,0] op_sel_hi:[1,1]
	v_pk_add_f32 v[2:3], v[2:3], v[6:7] op_sel:[0,0] op_sel_hi:[1,1] neg_lo:[0,1] neg_hi:[0,1]
	v_pk_add_f32 v[6:7], v[4:5], v[8:9] op_sel:[0,0] op_sel_hi:[1,1]
	v_cvt_f32_f16_e32 v13, v20
	v_pk_add_f32 v[4:5], v[4:5], v[8:9] op_sel:[0,0] op_sel_hi:[1,1] neg_lo:[0,1] neg_hi:[0,1]
	v_pk_add_f32 v[8:9], v[10:11], v[6:7] op_sel:[0,0] op_sel_hi:[1,1]
	v_pk_add_f32 v[6:7], v[10:11], v[6:7] op_sel:[0,0] op_sel_hi:[1,1] neg_lo:[0,1] neg_hi:[0,1]
	v_pk_add_f32 v[10:11], v[2:3], v[4:5] op_sel:[0,1] op_sel_hi:[1,0] neg_lo:[0,0] neg_hi:[0,1]
	v_pk_add_f32 v[2:3], v[2:3], v[4:5] op_sel:[0,1] op_sel_hi:[1,0] neg_lo:[0,1] neg_hi:[0,0]
	v_cvt_f32_f16_sdwa v5, v20 dst_sel:DWORD dst_unused:UNUSED_PAD src0_sel:WORD_1
	v_cvt_f32_f16_e32 v12, v16
	v_cvt_f32_f16_sdwa v4, v16 dst_sel:DWORD dst_unused:UNUSED_PAD src0_sel:WORD_1
	v_cvt_f32_f16_e32 v17, v0
	v_cvt_f32_f16_sdwa v15, v0 dst_sel:DWORD dst_unused:UNUSED_PAD src0_sel:WORD_1
	v_cvt_f32_f16_e32 v18, v1
	v_cvt_f32_f16_sdwa v14, v1 dst_sel:DWORD dst_unused:UNUSED_PAD src0_sel:WORD_1
	v_pk_add_f32 v[12:13], v[176:177], v[12:13] op_sel:[1,0] op_sel_hi:[1,1]
	v_mul_f32_e32 v5, v5, v9
	v_mul_f32_e32 v9, v13, v9
	v_add_f32_e32 v17, v177, v17
	v_fma_f32 v5, v13, v8, -v5
	v_fma_mix_f32 v8, v20, v8, v9 op_sel:[1,0,0] op_sel_hi:[1,0,0]
	v_mul_f32_e32 v4, v4, v11
	v_mul_f32_e32 v9, v12, v11
	v_add_f32_e32 v18, v177, v18
	v_fma_f32 v4, v12, v10, -v4
	v_fma_mix_f32 v9, v16, v10, v9 op_sel:[1,0,0] op_sel_hi:[1,0,0]
	v_mul_f32_e32 v10, v15, v7
	v_mul_f32_e32 v7, v17, v7
	v_fma_f32 v10, v17, v6, -v10
	v_fma_mix_f32 v0, v0, v6, v7 op_sel:[1,0,0] op_sel_hi:[1,0,0]
	v_mul_f32_e32 v6, v14, v3
	v_mul_f32_e32 v3, v18, v3
	v_mul_f32_e32 v5, 0x38800000, v5
	v_fma_f32 v6, v18, v2, -v6
	v_fma_mix_f32 v1, v1, v2, v3 op_sel:[1,0,0] op_sel_hi:[1,0,0]
	v_mul_f32_e32 v8, 0x38800000, v8
	v_mul_f32_e32 v4, 0x38800000, v4
	v_mul_f32_e32 v10, 0x38800000, v10
	v_mul_f32_e32 v0, 0x38800000, v0
	v_mul_f32_e32 v6, 0x38800000, v6
	v_mul_f32_e32 v1, 0x38800000, v1
	v_add_f32_e32 v2, v5, v10
	v_add_f32_e32 v3, v8, v0
	v_sub_f32_e32 v7, v5, v10
	v_add_f32_e32 v5, v4, v6
	v_mul_f32_e32 v9, 0x38800000, v9
	v_sub_f32_e32 v8, v8, v0
	v_add_f32_e32 v10, v9, v1
	v_sub_f32_e32 v11, v4, v6
	v_sub_f32_e32 v6, v9, v1
	v_add_f32_e32 v0, v2, v5
	v_sub_f32_e32 v4, v2, v5
	v_mov_b32_e32 v34, v143
	v_add_f32_e32 v1, v3, v10
	v_sub_f32_e32 v5, v3, v10
	v_sub_f32_e32 v2, v7, v6
	v_add_f32_e32 v3, v8, v11
	v_add_f32_e32 v6, v7, v6
	v_sub_f32_e32 v7, v8, v11
	ds_write_b128 v169, v[0:3]
	ds_write_b128 v169, v[4:7] offset:16
	v_mov_b32_e32 v35, v144
	ds_read_b64 v[2:3], v142
	ds_read_b64 v[0:1], v141 offset:4096
	ds_read_b64 v[20:21], v142 offset:32
	ds_read_b64 v[22:23], v141 offset:4128
	ds_read_b64 v[24:25], v142 offset:64
	ds_read_b64 v[26:27], v141 offset:4160
	ds_read_b64 v[28:29], v142 offset:96
	ds_read_b64 v[30:31], v141 offset:4192
	ds_read_b64 v[32:33], v142 offset:128
	ds_read_b64 v[40:41], v141 offset:4224
	ds_read_b64 v[42:43], v142 offset:160
	ds_read_b64 v[44:45], v141 offset:4256
	ds_read_b64 v[46:47], v142 offset:192
	ds_read_b64 v[48:49], v141 offset:4288
	ds_read_b64 v[120:121], v142 offset:224
	ds_read_b64 v[122:123], v141 offset:4320
	ds_read_b64 v[124:125], v142 offset:256
	ds_read_b64 v[126:127], v141 offset:4352
	ds_read_b64 v[128:129], v142 offset:288
	ds_read_b64 v[130:131], v141 offset:4384
	ds_read_b64 v[178:179], v142 offset:320
	ds_read_b64 v[180:181], v141 offset:4416
	ds_read_b64 v[182:183], v142 offset:352
	ds_read_b64 v[184:185], v141 offset:4448
	ds_read_b64 v[18:19], v142 offset:384
	ds_read_b64 v[16:17], v141 offset:4480
	ds_read_b64 v[14:15], v142 offset:416
	ds_read_b64 v[12:13], v141 offset:4512
	ds_read_b64 v[10:11], v142 offset:448
	ds_read_b64 v[8:9], v141 offset:4544
	ds_read_b64 v[6:7], v142 offset:480
	ds_read_b64 v[4:5], v141 offset:4576
	s_nop 1
	s_nop 0
	v_mul_f32_e32 v36, v35, v35
	s_nop 0
	v_fma_f32 v37, -v34, v34, v36
	v_mul_f32_e32 v36, v35, v34
	s_nop 0
	v_fma_f32 v82, v34, v35, v36
	v_mul_f32_e32 v36, v37, v35
	s_nop 0
	v_fma_f32 v132, -v82, v34, v36
	v_mul_f32_e32 v36, v37, v34
	s_nop 0
	v_fma_f32 v134, v82, v35, v36
	v_mul_f32_e32 v36, v37, v37
	s_nop 0
	v_fma_f32 v151, -v82, v82, v36
	v_mul_f32_e32 v36, v37, v82
	s_nop 0
	v_fma_f32 v170, v82, v37, v36
	v_mul_f32_e32 v36, v151, v35
	s_nop 0
	v_fma_f32 v171, -v170, v34, v36
	v_mul_f32_e32 v36, v151, v34
	s_nop 0
	v_fma_f32 v177, v170, v35, v36
	v_mul_f32_e32 v36, v132, v132
	s_nop 0
	v_fma_f32 v186, -v134, v134, v36
	v_mul_f32_e32 v36, v132, v134
	s_nop 0
	v_fma_f32 v187, v134, v132, v36
	v_mul_f32_e32 v36, v151, v132
	s_nop 0
	v_fma_f32 v188, -v170, v134, v36
	v_mul_f32_e32 v36, v151, v134
	s_nop 0
	v_fma_f32 v189, v170, v132, v36
	v_mul_f32_e32 v36, v151, v151
	s_nop 0
	v_fma_f32 v190, -v170, v170, v36
	v_mul_f32_e32 v36, v151, v170
	s_nop 0
	v_fma_f32 v191, v170, v151, v36
	v_mul_f32_e32 v36, v190, v35
	s_nop 0
	v_fma_f32 v192, -v191, v34, v36
	v_mul_f32_e32 v36, v190, v34
	s_nop 0
	v_fma_f32 v193, v191, v35, v36
	v_mul_f32_e32 v36, v171, v171
	s_nop 0
	v_fma_f32 v194, -v177, v177, v36
	v_mul_f32_e32 v36, v171, v177
	s_nop 0
	v_fma_f32 v195, v177, v171, v36
	v_mul_f32_e32 v36, v190, v132
	s_nop 0
	v_fma_f32 v196, -v191, v134, v36
	v_mul_f32_e32 v36, v190, v134
	s_nop 0
	v_fma_f32 v197, v191, v132, v36
	v_mul_f32_e32 v36, v186, v186
	s_nop 0
	v_fma_f32 v198, -v187, v187, v36
	v_mul_f32_e32 v36, v186, v187
	s_nop 0
	v_fma_f32 v199, v187, v186, v36
	v_mul_f32_e32 v36, v190, v171
	s_nop 0
	v_fma_f32 v200, -v191, v177, v36
	v_mul_f32_e32 v36, v190, v177
	s_nop 0
	v_fma_f32 v201, v191, v171, v36
	v_mul_f32_e32 v36, v188, v188
	s_nop 0
	v_fma_f32 v202, -v189, v189, v36
	v_mul_f32_e32 v36, v188, v189
	s_nop 0
	v_fma_f32 v203, v189, v188, v36
	v_mul_f32_e32 v36, v190, v188
	s_nop 0
	v_fma_f32 v204, -v191, v189, v36
	v_mul_f32_e32 v36, v190, v189
	s_nop 0
	v_fma_f32 v205, v191, v188, v36
	s_waitcnt lgkmcnt(0)
	v_mul_f32_e32 v36, v20, v35
	v_mul_f32_e32 v20, v20, v34
	s_nop 0
	v_fma_f32 v206, -v21, v34, v36
	v_fma_f32 v20, v21, v35, v20
	v_mul_f32_e32 v21, v22, v35
	s_nop 0
	v_fma_f32 v38, -v23, v34, v21
	v_mul_f32_e32 v21, v22, v34
	v_mul_f32_e32 v22, v24, v82
	s_nop 0
	v_fma_f32 v39, v23, v35, v21
	v_mul_f32_e32 v21, v24, v37
	v_mul_f32_e32 v23, v26, v37
	v_fma_f32 v22, v25, v37, v22
	v_mul_f32_e32 v24, v28, v134
	s_nop 0
	v_fma_f32 v21, -v25, v82, v21
	v_fma_f32 v36, -v27, v82, v23
	v_mul_f32_e32 v23, v26, v82
	v_mul_f32_e32 v25, v30, v132
	v_fma_f32 v24, v29, v132, v24
	v_mul_f32_e32 v26, v32, v170
	s_nop 0
	v_fma_f32 v37, v27, v37, v23
	v_mul_f32_e32 v27, v40, v151
	v_fma_f32 v34, -v31, v134, v25
	v_mul_f32_e32 v25, v30, v134
	v_mul_f32_e32 v23, v28, v132
	v_mul_f32_e32 v28, v42, v177
	v_fma_f32 v26, v33, v151, v26
	s_nop 0
	v_fma_f32 v82, -v41, v170, v27
	v_mul_f32_e32 v27, v40, v170
	v_fma_f32 v35, v31, v132, v25
	v_mul_f32_e32 v31, v48, v186
	v_mul_f32_e32 v25, v32, v151
	v_fma_f32 v28, v43, v171, v28
	v_mul_f32_e32 v32, v120, v189
	s_nop 0
	v_fma_f32 v132, v41, v151, v27
	v_mul_f32_e32 v27, v42, v171
	v_fma_f32 v42, -v49, v187, v31
	v_mul_f32_e32 v31, v48, v187
	v_fma_f32 v23, -v29, v134, v23
	v_fma_f32 v32, v121, v188, v32
	v_mul_f32_e32 v29, v44, v171
	s_nop 0
	v_fma_f32 v27, -v43, v177, v27
	v_fma_f32 v25, -v33, v170, v25
	v_fma_f32 v43, v49, v186, v31
	v_mul_f32_e32 v31, v120, v188
	v_fma_f32 v134, -v45, v177, v29
	v_mul_f32_e32 v29, v44, v177
	v_mul_f32_e32 v33, v122, v188
	v_mul_f32_e32 v48, v128, v192
	s_nop 0
	v_fma_f32 v31, -v121, v189, v31
	v_pk_mul_f32 v[120:121], v[130:131], v[192:193] op_sel:[0,0] op_sel_hi:[0,1]
	v_mul_f32_e32 v130, v18, v198
	v_mul_f32_e32 v18, v18, v199
	v_fma_f32 v44, v45, v171, v29
	v_fma_f32 v40, -v123, v189, v33
	v_mul_f32_e32 v33, v122, v189
	s_nop 0
	v_fma_f32 v130, -v19, v199, v130
	v_fma_f32 v18, v19, v198, v18
	v_mul_f32_e32 v19, v16, v198
	v_mul_f32_e32 v16, v16, v199
	v_fma_f32 v41, v123, v188, v33
	v_pk_mul_f32 v[122:123], v[178:179], v[194:195] op_sel:[0,0] op_sel_hi:[0,1]
	v_mul_f32_e32 v33, v124, v190
	v_mul_f32_e32 v45, v124, v191
	v_mul_f32_e32 v49, v128, v193
	s_nop 0
	v_fma_f32 v151, v17, v198, v16
	v_mul_f32_e32 v16, v14, v200
	v_mul_f32_e32 v14, v14, v201
	v_fma_f32 v33, -v125, v191, v33
	v_fma_f32 v45, v125, v190, v45
	v_pk_fma_f32 v[122:123], v[178:179], v[194:195], v[122:123] op_sel:[1,1,0] op_sel_hi:[1,0,1] neg_lo:[1,0,0] neg_hi:[0,0,0]
	s_nop 0
	v_fma_f32 v16, -v15, v201, v16
	v_fma_f32 v14, v15, v200, v14
	v_mul_f32_e32 v15, v12, v200
	v_mul_f32_e32 v12, v12, v201
	v_pk_mul_f32 v[124:125], v[180:181], v[194:195] op_sel:[0,0] op_sel_hi:[0,1]
	v_mul_f32_e32 v29, v46, v186
	v_mul_f32_e32 v30, v46, v187
	s_nop 0
	v_fma_f32 v170, -v13, v201, v15
	v_fma_f32 v171, v13, v200, v12
	v_mul_f32_e32 v12, v10, v202
	v_mul_f32_e32 v10, v10, v203
	v_sub_f32_e32 v13, v26, v18
	v_pk_fma_f32 v[48:49], v[128:129], v[192:193], v[48:49] op_sel:[1,1,0] op_sel_hi:[1,0,1] neg_lo:[1,0,0] neg_hi:[0,0,0]
	s_nop 0
	v_fma_f32 v12, -v11, v203, v12
	v_fma_f32 v10, v11, v202, v10
	v_mul_f32_e32 v11, v8, v202
	v_mul_f32_e32 v8, v8, v203
	v_pk_fma_f32 v[120:121], v[130:131], v[192:193], v[120:121] op_sel:[1,1,0] op_sel_hi:[1,0,1] neg_lo:[1,0,0] neg_hi:[0,0,0]
	v_fma_f32 v131, -v17, v199, v19
	v_fma_f32 v29, -v47, v187, v29
	v_fma_f32 v30, v47, v186, v30
	s_nop 0
	v_fma_f32 v177, -v9, v203, v11
	v_fma_f32 v178, v9, v202, v8
	v_mul_f32_e32 v8, v6, v204
	v_mul_f32_e32 v6, v6, v205
	v_add_f32_e32 v9, v26, v18
	v_sub_f32_e32 v11, v25, v130
	v_pk_mul_f32 v[46:47], v[126:127], v[190:191] op_sel:[0,0] op_sel_hi:[0,1]
	s_nop 0
	v_fma_f32 v8, -v7, v205, v8
	v_fma_f32 v6, v7, v204, v6
	v_mul_f32_e32 v7, v4, v204
	v_mul_f32_e32 v4, v4, v205
	v_pk_fma_f32 v[46:47], v[126:127], v[190:191], v[46:47] op_sel:[1,1,0] op_sel_hi:[1,0,1] neg_lo:[1,0,0] neg_hi:[0,0,0]
	v_pk_mul_f32 v[126:127], v[182:183], v[196:197] op_sel:[0,0] op_sel_hi:[0,1]
	s_nop 0
	v_fma_f32 v179, -v5, v205, v7
	v_fma_f32 v180, v5, v204, v4
	v_add_f32_e32 v4, v2, v33
	v_add_f32_e32 v5, v3, v45
	v_sub_f32_e32 v2, v2, v33
	v_sub_f32_e32 v3, v3, v45
	v_add_f32_e32 v7, v25, v130
	v_pk_fma_f32 v[126:127], v[182:183], v[196:197], v[126:127] op_sel:[1,1,0] op_sel_hi:[1,0,1] neg_lo:[1,0,0] neg_hi:[0,0,0]
	s_nop 0
	v_add_f32_e32 v17, v5, v9
	v_sub_f32_e32 v26, v5, v9
	v_add_f32_e32 v9, v3, v11
	v_add_f32_e32 v15, v4, v7
	v_sub_f32_e32 v25, v4, v7
	v_sub_f32_e32 v7, v2, v13
	v_add_f32_e32 v33, v2, v13
	v_sub_f32_e32 v45, v3, v11
	v_add_f32_e32 v2, v206, v48
	v_add_f32_e32 v3, v20, v49
	v_sub_f32_e32 v4, v206, v48
	v_sub_f32_e32 v5, v20, v49
	v_add_f32_e32 v11, v27, v16
	v_add_f32_e32 v13, v28, v14
	v_sub_f32_e32 v16, v27, v16
	v_sub_f32_e32 v14, v28, v14
	v_sub_f32_e32 v20, v21, v122
	v_add_f32_e32 v27, v30, v10
	s_nop 0
	v_add_f32_e32 v18, v2, v11
	v_add_f32_e32 v19, v3, v13
	v_sub_f32_e32 v2, v2, v11
	v_sub_f32_e32 v3, v3, v13
	v_sub_f32_e32 v11, v4, v14
	v_add_f32_e32 v13, v5, v16
	v_add_f32_e32 v4, v4, v14
	v_sub_f32_e32 v5, v5, v16
	v_add_f32_e32 v14, v21, v122
	v_add_f32_e32 v16, v22, v123
	v_sub_f32_e32 v10, v30, v10
	v_sub_f32_e32 v21, v22, v123
	v_add_f32_e32 v22, v29, v12
	v_sub_f32_e32 v12, v29, v12
	v_add_f32_e32 v48, v32, v6
	s_nop 0
	v_add_f32_e32 v29, v16, v27
	v_sub_f32_e32 v6, v32, v6
	v_mul_f32_e32 v2, v2, v154
	v_add_f32_e32 v28, v14, v22
	v_sub_f32_e32 v30, v14, v22
	v_sub_f32_e32 v14, v16, v27
	v_sub_f32_e32 v16, v20, v10
	v_add_f32_e32 v10, v20, v10
	v_add_f32_e32 v20, v23, v126
	v_sub_f32_e32 v23, v23, v126
	v_add_f32_e32 v27, v31, v8
	v_sub_f32_e32 v8, v31, v8
	v_add_f32_e32 v22, v21, v12
	v_sub_f32_e32 v12, v21, v12
	v_add_f32_e32 v21, v24, v127
	v_sub_f32_e32 v24, v24, v127
	s_nop 0
	v_add_f32_e32 v31, v20, v27
	v_sub_f32_e32 v20, v20, v27
	v_sub_f32_e32 v27, v23, v6
	v_add_f32_e32 v6, v23, v6
	v_mul_f32_e32 v23, v11, v152
	v_mul_f32_e32 v11, v11, v156
	v_add_f32_e32 v32, v21, v48
	v_sub_f32_e32 v21, v21, v48
	v_add_f32_e32 v48, v24, v8
	v_sub_f32_e32 v8, v24, v8
	s_nop 0
	v_fma_f32 v23, -v13, v156, v23
	v_fma_f32 v13, v13, v152, v11
	v_mul_f32_e32 v11, v16, v154
	v_fma_f32 v49, v3, v154, v2
	v_pk_fma_f32 v[124:125], v[180:181], v[194:195], v[124:125] op_sel:[1,1,0] op_sel_hi:[1,0,1] neg_lo:[1,0,0] neg_hi:[0,0,0]
	v_xor_b32_e32 v122, 0x80000000, v14
	v_fma_f32 v16, -v22, v154, v11
	v_fma_f32 v22, v22, v154, v11
	v_mul_f32_e32 v11, v27, v156
	v_pk_mul_f32 v[128:129], v[184:185], v[196:197] op_sel:[0,0] op_sel_hi:[0,1]
	s_nop 0
	v_fma_f32 v24, -v48, v152, v11
	v_mul_f32_e32 v11, v27, v152
	v_pk_fma_f32 v[128:129], v[184:185], v[196:197], v[128:129] op_sel:[1,1,0] op_sel_hi:[1,0,1] neg_lo:[1,0,0] neg_hi:[0,0,0]
	s_nop 0
	v_fma_f32 v27, v48, v156, v11
	v_fma_f32 v48, -v3, v154, v2
	v_mul_f32_e32 v2, v20, v155
	v_add_f32_e32 v3, v17, v29
	s_nop 0
	v_fma_f32 v123, -v21, v154, v2
	v_mul_f32_e32 v2, v20, v154
	s_nop 0
	v_fma_f32 v20, v21, v155, v2
	v_mul_f32_e32 v2, v4, v156
	s_nop 0
	v_fma_f32 v21, -v5, v152, v2
	v_mul_f32_e32 v2, v4, v152
	v_add_f32_e32 v4, v18, v31
	s_nop 0
	v_fma_f32 v126, v5, v156, v2
	v_mul_f32_e32 v2, v10, v155
	v_add_f32_e32 v5, v19, v32
	s_nop 0
	v_fma_f32 v127, -v12, v154, v2
	v_mul_f32_e32 v2, v10, v154
	s_nop 0
	v_fma_f32 v130, v12, v155, v2
	v_mul_f32_e32 v2, v6, v157
	v_sub_f32_e32 v12, v18, v31
	s_nop 0
	v_fma_f32 v181, -v8, v153, v2
	v_mul_f32_e32 v2, v6, v153
	v_sub_f32_e32 v6, v15, v28
	s_nop 0
	v_fma_f32 v182, v8, v157, v2
	v_add_f32_e32 v2, v15, v28
	v_sub_f32_e32 v8, v17, v29
	v_sub_f32_e32 v17, v19, v32
	v_pk_add_f32 v[14:15], v[2:3], v[4:5] op_sel:[0,0] op_sel_hi:[1,1]
	s_nop 0
	v_pk_add_f32 v[4:5], v[2:3], v[4:5] op_sel:[0,0] op_sel_hi:[1,1] neg_lo:[0,1] neg_hi:[0,1]
	v_sub_f32_e32 v10, v6, v17
	v_add_f32_e32 v11, v8, v12
	v_add_f32_e32 v2, v6, v17
	v_sub_f32_e32 v3, v8, v12
	v_add_f32_e32 v12, v9, v22
	v_pk_add_f32 v[6:7], v[6:7], v[16:17] op_sel:[1,0] op_sel_hi:[1,0] neg_lo:[0,0] neg_hi:[0,1]
	v_sub_f32_e32 v16, v9, v22
	v_add_f32_e32 v8, v23, v24
	v_add_f32_e32 v9, v13, v27
	v_sub_f32_e32 v17, v23, v24
	v_sub_f32_e32 v13, v13, v27
	v_sub_f32_e32 v24, v25, v122
	s_nop 0
	v_add_f32_e32 v22, v6, v8
	v_add_f32_e32 v23, v12, v9
	v_sub_f32_e32 v8, v6, v8
	v_sub_f32_e32 v9, v12, v9
	v_sub_f32_e32 v18, v7, v13
	v_add_f32_e32 v19, v16, v17
	v_add_f32_e32 v6, v7, v13
	v_sub_f32_e32 v7, v16, v17
	v_add_f32_e32 v12, v25, v122
	v_add_f32_e32 v13, v26, v30
	v_sub_f32_e32 v25, v26, v30
	v_add_f32_e32 v16, v48, v123
	v_add_f32_e32 v17, v49, v20
	v_sub_f32_e32 v30, v48, v123
	v_sub_f32_e32 v20, v49, v20
	v_sub_f32_e32 v48, v33, v127
	v_sub_f32_e32 v49, v126, v182
	s_nop 0
	v_pk_add_f32 v[28:29], v[12:13], v[16:17] op_sel:[0,0] op_sel_hi:[1,1]
	v_pk_add_f32 v[16:17], v[12:13], v[16:17] op_sel:[0,0] op_sel_hi:[1,1] neg_lo:[0,1] neg_hi:[0,1]
	v_sub_f32_e32 v26, v24, v20
	v_add_f32_e32 v27, v25, v30
	v_add_f32_e32 v12, v24, v20
	v_sub_f32_e32 v13, v25, v30
	v_add_f32_e32 v20, v33, v127
	v_add_f32_e32 v25, v45, v130
	v_sub_f32_e32 v45, v45, v130
	v_add_f32_e32 v24, v21, v181
	v_add_f32_e32 v30, v126, v182
	v_sub_f32_e32 v21, v21, v181
	s_nop 0
	v_add_f32_e32 v32, v20, v24
	v_add_f32_e32 v33, v25, v30
	v_sub_f32_e32 v24, v20, v24
	v_sub_f32_e32 v25, v25, v30
	v_sub_f32_e32 v30, v48, v49
	v_add_f32_e32 v31, v45, v21
	v_add_f32_e32 v20, v48, v49
	v_sub_f32_e32 v21, v45, v21
	v_add_f32_e32 v45, v0, v46
	v_add_f32_e32 v48, v1, v47
	v_pk_add_f32 v[0:1], v[0:1], v[46:47] op_sel:[0,0] op_sel_hi:[1,1] neg_lo:[0,1] neg_hi:[0,1]
	v_add_f32_e32 v46, v82, v131
	v_add_f32_e32 v47, v132, v151
	v_sub_f32_e32 v49, v82, v131
	v_sub_f32_e32 v82, v132, v151
	s_nop 0
	v_add_f32_e32 v122, v45, v46
	v_add_f32_e32 v123, v48, v47
	v_sub_f32_e32 v126, v45, v46
	v_sub_f32_e32 v48, v48, v47
	v_sub_f32_e32 v45, v0, v82
	v_add_f32_e32 v46, v1, v49
	v_add_f32_e32 v82, v0, v82
	v_sub_f32_e32 v127, v1, v49
	v_pk_add_f32 v[0:1], v[38:39], v[120:121] op_sel:[0,0] op_sel_hi:[1,1]
	v_pk_add_f32 v[38:39], v[38:39], v[120:121] op_sel:[0,0] op_sel_hi:[1,1] neg_lo:[0,1] neg_hi:[0,1]
	v_add_f32_e32 v47, v134, v170
	v_add_f32_e32 v49, v44, v171
	v_sub_f32_e32 v120, v134, v170
	v_sub_f32_e32 v44, v44, v171
	s_nop 0
	v_add_f32_e32 v121, v0, v47
	v_add_f32_e32 v130, v1, v49
	v_sub_f32_e32 v0, v0, v47
	v_sub_f32_e32 v1, v1, v49
	v_sub_f32_e32 v47, v38, v44
	v_add_f32_e32 v49, v39, v120
	v_add_f32_e32 v38, v38, v44
	v_sub_f32_e32 v39, v39, v120
	v_add_f32_e32 v44, v36, v124
	v_add_f32_e32 v120, v37, v125
	v_pk_add_f32 v[36:37], v[36:37], v[124:125] op_sel:[0,0] op_sel_hi:[1,1] neg_lo:[0,1] neg_hi:[0,1]
	v_add_f32_e32 v124, v42, v177
	v_add_f32_e32 v125, v43, v178
	v_sub_f32_e32 v42, v42, v177
	v_sub_f32_e32 v43, v43, v178
	s_nop 0
	v_mul_f32_e32 v0, v0, v154
	v_add_f32_e32 v131, v44, v124
	v_add_f32_e32 v132, v120, v125
	v_sub_f32_e32 v124, v44, v124
	v_sub_f32_e32 v44, v120, v125
	v_sub_f32_e32 v120, v36, v43
	v_add_f32_e32 v125, v37, v42
	v_pk_add_f32 v[36:37], v[36:37], v[42:43] op_sel:[0,1] op_sel_hi:[1,0] neg_lo:[0,0] neg_hi:[0,1]
	v_pk_add_f32 v[42:43], v[34:35], v[128:129] op_sel:[0,0] op_sel_hi:[1,1]
	v_pk_add_f32 v[34:35], v[34:35], v[128:129] op_sel:[0,0] op_sel_hi:[1,1] neg_lo:[0,1] neg_hi:[0,1]
	v_add_f32_e32 v128, v40, v179
	v_add_f32_e32 v129, v41, v180
	v_sub_f32_e32 v40, v40, v179
	v_sub_f32_e32 v41, v41, v180
	s_nop 0
	v_xor_b32_e32 v170, 0x80000000, v44
	v_add_f32_e32 v134, v42, v128
	v_add_f32_e32 v151, v43, v129
	v_pk_add_f32 v[42:43], v[42:43], v[128:129] op_sel:[0,0] op_sel_hi:[1,1] neg_lo:[0,1] neg_hi:[0,1]
	v_pk_add_f32 v[128:129], v[34:35], v[40:41] op_sel:[0,1] op_sel_hi:[1,0] neg_lo:[0,1] neg_hi:[0,0]
	v_pk_add_f32 v[34:35], v[34:35], v[40:41] op_sel:[0,1] op_sel_hi:[1,0] neg_lo:[0,0] neg_hi:[0,1]
	v_mul_f32_e32 v40, v47, v152
	v_mul_f32_e32 v41, v47, v156
	v_mul_f32_e32 v47, v120, v154
	s_nop 0
	v_mul_f32_e32 v120, v128, v156
	v_fma_f32 v40, -v49, v156, v40
	v_fma_f32 v41, v49, v152, v41
	v_fma_f32 v49, -v125, v154, v47
	v_fma_f32 v47, v125, v154, v47
	v_mul_f32_e32 v125, v128, v152
	s_nop 0
	v_fma_f32 v120, -v129, v152, v120
	v_fma_f32 v125, v129, v156, v125
	v_pk_fma_f32 v[128:129], v[0:1], v[154:155], v[0:1] op_sel:[1,0,0] op_sel_hi:[1,0,0] neg_lo:[1,0,0] neg_hi:[0,0,0]
	v_mul_f32_e32 v0, v42, v155
	s_nop 0
	v_add_f32_e32 v44, v40, v120
	v_sub_f32_e32 v120, v40, v120
	v_fma_f32 v171, -v43, v154, v0
	v_mul_f32_e32 v0, v42, v154
	v_sub_f32_e32 v42, v121, v134
	s_nop 0
	v_fma_f32 v177, v43, v155, v0
	v_mul_f32_e32 v0, v38, v156
	v_sub_f32_e32 v43, v130, v151
	s_nop 0
	v_fma_f32 v178, -v39, v152, v0
	v_mul_f32_e32 v0, v38, v152
	v_sub_f32_e32 v38, v122, v131
	s_nop 0
	v_fma_f32 v179, v39, v156, v0
	v_mul_f32_e32 v0, v36, v155
	v_sub_f32_e32 v39, v123, v132
	s_nop 0
	v_fma_f32 v180, -v37, v154, v0
	v_mul_f32_e32 v0, v36, v154
	v_add_f32_e32 v36, v121, v134
	v_add_f32_e32 v121, v48, v124
	s_nop 0
	v_fma_f32 v181, v37, v155, v0
	v_mul_f32_e32 v0, v34, v157
	v_add_f32_e32 v37, v130, v151
	s_nop 0
	v_fma_f32 v182, -v35, v153, v0
	v_mul_f32_e32 v0, v34, v153
	v_add_f32_e32 v34, v122, v131
	v_add_f32_e32 v122, v128, v171
	v_sub_f32_e32 v128, v128, v171
	s_nop 0
	v_fma_f32 v183, v35, v157, v0
	v_add_f32_e32 v35, v123, v132
	v_pk_add_f32 v[0:1], v[34:35], v[36:37] op_sel:[0,0] op_sel_hi:[1,1]
	v_pk_add_f32 v[34:35], v[34:35], v[36:37] op_sel:[0,0] op_sel_hi:[1,1] neg_lo:[0,1] neg_hi:[0,1]
	v_pk_add_f32 v[36:37], v[38:39], v[42:43] op_sel:[0,1] op_sel_hi:[1,0] neg_lo:[0,1] neg_hi:[0,0]
	v_pk_add_f32 v[38:39], v[38:39], v[42:43] op_sel:[0,1] op_sel_hi:[1,0] neg_lo:[0,0] neg_hi:[0,1]
	v_add_f32_e32 v43, v46, v47
	s_nop 0
	v_add_f32_e32 v42, v45, v49
	v_sub_f32_e32 v49, v45, v49
	v_sub_f32_e32 v47, v46, v47
	v_add_f32_e32 v45, v41, v125
	v_sub_f32_e32 v46, v41, v125
	v_sub_f32_e32 v125, v126, v170
	v_add_f32_e32 v123, v129, v177
	s_nop 0
	v_pk_add_f32 v[40:41], v[42:43], v[44:45] op_sel:[0,0] op_sel_hi:[1,1]
	v_pk_add_f32 v[42:43], v[42:43], v[44:45] op_sel:[0,0] op_sel_hi:[1,1] neg_lo:[0,1] neg_hi:[0,1]
	v_add_f32_e32 v45, v47, v120
	v_sub_f32_e32 v47, v47, v120
	v_add_f32_e32 v120, v126, v170
	v_sub_f32_e32 v126, v48, v124
	v_sub_f32_e32 v124, v129, v177
	v_sub_f32_e32 v44, v49, v46
	v_add_f32_e32 v46, v49, v46
	s_nop 0
	v_pk_add_f32 v[48:49], v[120:121], v[122:123] op_sel:[0,0] op_sel_hi:[1,1]
	v_pk_add_f32 v[120:121], v[120:121], v[122:123] op_sel:[0,0] op_sel_hi:[1,1] neg_lo:[0,1] neg_hi:[0,1]
	v_sub_f32_e32 v122, v125, v124
	v_add_f32_e32 v123, v126, v128
	v_add_f32_e32 v124, v125, v124
	v_sub_f32_e32 v125, v126, v128
	v_add_f32_e32 v128, v82, v180
	v_add_f32_e32 v129, v127, v181
	v_pk_add_f32 v[130:131], v[178:179], v[182:183] op_sel:[0,0] op_sel_hi:[1,1]
	v_sub_f32_e32 v82, v82, v180
	v_sub_f32_e32 v132, v127, v181
	v_sub_f32_e32 v134, v178, v182
	v_sub_f32_e32 v151, v179, v183
	s_nop 0
	v_pk_add_f32 v[126:127], v[128:129], v[130:131] op_sel:[0,0] op_sel_hi:[1,1]
	v_pk_add_f32 v[128:129], v[128:129], v[130:131] op_sel:[0,0] op_sel_hi:[1,1] neg_lo:[0,1] neg_hi:[0,1]
	v_add_f32_e32 v131, v132, v134
	v_sub_f32_e32 v130, v82, v151
	v_add_f32_e32 v178, v82, v151
	v_sub_f32_e32 v179, v132, v134
	ds_write_b64 v142, v[14:15]
	ds_write_b64 v141, v[0:1] offset:4096
	ds_write_b64 v142, v[22:23] offset:32
	ds_write_b64 v141, v[40:41] offset:4128
	ds_write_b64 v142, v[28:29] offset:64
	ds_write_b64 v141, v[48:49] offset:4160
	ds_write_b64 v142, v[32:33] offset:96
	ds_write_b64 v141, v[126:127] offset:4192
	ds_write_b64 v142, v[10:11] offset:128
	ds_write_b64 v141, v[36:37] offset:4224
	ds_write_b64 v142, v[18:19] offset:160
	ds_write_b64 v141, v[44:45] offset:4256
	ds_write_b64 v142, v[26:27] offset:192
	ds_write_b64 v141, v[122:123] offset:4288
	ds_write_b64 v142, v[30:31] offset:224
	ds_write_b64 v141, v[130:131] offset:4320
	ds_write_b64 v142, v[4:5] offset:256
	ds_write_b64 v141, v[34:35] offset:4352
	ds_write_b64 v142, v[8:9] offset:288
	ds_write_b64 v141, v[42:43] offset:4384
	ds_write_b64 v142, v[16:17] offset:320
	ds_write_b64 v141, v[120:121] offset:4416
	ds_write_b64 v142, v[24:25] offset:352
	ds_write_b64 v141, v[128:129] offset:4448
	ds_write_b64 v142, v[2:3] offset:384
	ds_write_b64 v141, v[38:39] offset:4480
	ds_write_b64 v142, v[6:7] offset:416
	ds_write_b64 v141, v[46:47] offset:4512
	ds_write_b64 v142, v[12:13] offset:448
	ds_write_b64 v141, v[124:125] offset:4544
	ds_write_b64 v142, v[20:21] offset:480
	ds_write_b64 v141, v[178:179] offset:4576
	v_mov_b32_e32 v34, v139
	v_mov_b32_e32 v35, v140
	ds_read_b64 v[2:3], v138
	ds_read_b64 v[0:1], v137 offset:4096
	ds_read_b64 v[20:21], v138 offset:544
	ds_read_b64 v[22:23], v137 offset:4640
	ds_read_b64 v[24:25], v138 offset:1088
	ds_read_b64 v[26:27], v137 offset:5184
	ds_read_b64 v[28:29], v138 offset:1632
	ds_read_b64 v[30:31], v137 offset:5728
	ds_read_b64 v[32:33], v138 offset:2176
	ds_read_b64 v[40:41], v137 offset:6272
	ds_read_b64 v[42:43], v138 offset:2720
	ds_read_b64 v[44:45], v137 offset:6816
	ds_read_b64 v[46:47], v138 offset:3264
	ds_read_b64 v[48:49], v137 offset:7360
	ds_read_b64 v[120:121], v138 offset:3808
	ds_read_b64 v[122:123], v137 offset:7904
	ds_read_b64 v[124:125], v138 offset:4352
	ds_read_b64 v[126:127], v137 offset:8448
	ds_read_b64 v[128:129], v138 offset:4896
	ds_read_b64 v[130:131], v137 offset:8992
	ds_read_b64 v[178:179], v138 offset:5440
	ds_read_b64 v[180:181], v137 offset:9536
	ds_read_b64 v[182:183], v138 offset:5984
	ds_read_b64 v[184:185], v137 offset:10080
	ds_read_b64 v[18:19], v138 offset:6528
	ds_read_b64 v[16:17], v137 offset:10624
	ds_read_b64 v[14:15], v138 offset:7072
	ds_read_b64 v[12:13], v137 offset:11168
	ds_read_b64 v[10:11], v138 offset:7616
	ds_read_b64 v[8:9], v137 offset:11712
	ds_read_b64 v[6:7], v138 offset:8160
	ds_read_b64 v[4:5], v137 offset:12256
	s_nop 1
	s_nop 0
	v_mul_f32_e32 v36, v35, v35
	s_nop 0
	v_fma_f32 v37, -v34, v34, v36
	v_mul_f32_e32 v36, v35, v34
	s_nop 0
	v_fma_f32 v82, v34, v35, v36
	v_mul_f32_e32 v36, v37, v35
	s_nop 0
	v_fma_f32 v132, -v82, v34, v36
	v_mul_f32_e32 v36, v37, v34
	s_nop 0
	v_fma_f32 v134, v82, v35, v36
	v_mul_f32_e32 v36, v37, v37
	s_nop 0
	v_fma_f32 v151, -v82, v82, v36
	v_mul_f32_e32 v36, v37, v82
	s_nop 0
	v_fma_f32 v170, v82, v37, v36
	v_mul_f32_e32 v36, v151, v35
	s_nop 0
	v_fma_f32 v171, -v170, v34, v36
	v_mul_f32_e32 v36, v151, v34
	s_nop 0
	v_fma_f32 v177, v170, v35, v36
	v_mul_f32_e32 v36, v132, v132
	s_nop 0
	v_fma_f32 v186, -v134, v134, v36
	v_mul_f32_e32 v36, v132, v134
	s_nop 0
	v_fma_f32 v187, v134, v132, v36
	v_mul_f32_e32 v36, v151, v132
	s_nop 0
	v_fma_f32 v188, -v170, v134, v36
	v_mul_f32_e32 v36, v151, v134
	s_nop 0
	v_fma_f32 v189, v170, v132, v36
	v_mul_f32_e32 v36, v151, v151
	s_nop 0
	v_fma_f32 v190, -v170, v170, v36
	v_mul_f32_e32 v36, v151, v170
	s_nop 0
	v_fma_f32 v191, v170, v151, v36
	v_mul_f32_e32 v36, v190, v35
	s_nop 0
	v_fma_f32 v192, -v191, v34, v36
	v_mul_f32_e32 v36, v190, v34
	s_nop 0
	v_fma_f32 v193, v191, v35, v36
	v_mul_f32_e32 v36, v171, v171
	s_nop 0
	v_fma_f32 v194, -v177, v177, v36
	v_mul_f32_e32 v36, v171, v177
	s_nop 0
	v_fma_f32 v195, v177, v171, v36
	v_mul_f32_e32 v36, v190, v132
	s_nop 0
	v_fma_f32 v196, -v191, v134, v36
	v_mul_f32_e32 v36, v190, v134
	s_nop 0
	v_fma_f32 v197, v191, v132, v36
	v_mul_f32_e32 v36, v186, v186
	s_nop 0
	v_fma_f32 v198, -v187, v187, v36
	v_mul_f32_e32 v36, v186, v187
	s_nop 0
	v_fma_f32 v199, v187, v186, v36
	v_mul_f32_e32 v36, v190, v171
	s_nop 0
	v_fma_f32 v200, -v191, v177, v36
	v_mul_f32_e32 v36, v190, v177
	s_nop 0
	v_fma_f32 v201, v191, v171, v36
	v_mul_f32_e32 v36, v188, v188
	s_nop 0
	v_fma_f32 v202, -v189, v189, v36
	v_mul_f32_e32 v36, v188, v189
	s_nop 0
	v_fma_f32 v203, v189, v188, v36
	v_mul_f32_e32 v36, v190, v188
	s_nop 0
	v_fma_f32 v204, -v191, v189, v36
	v_mul_f32_e32 v36, v190, v189
	s_nop 0
	v_fma_f32 v205, v191, v188, v36
	s_waitcnt lgkmcnt(0)
	v_mul_f32_e32 v36, v20, v35
	v_mul_f32_e32 v20, v20, v34
	s_nop 0
	v_fma_f32 v206, -v21, v34, v36
	v_fma_f32 v20, v21, v35, v20
	v_mul_f32_e32 v21, v22, v35
	s_nop 0
	v_fma_f32 v38, -v23, v34, v21
	v_mul_f32_e32 v21, v22, v34
	v_mul_f32_e32 v22, v24, v82
	s_nop 0
	v_fma_f32 v39, v23, v35, v21
	v_mul_f32_e32 v21, v24, v37
	v_mul_f32_e32 v23, v26, v37
	v_fma_f32 v22, v25, v37, v22
	v_mul_f32_e32 v24, v28, v134
	s_nop 0
	v_fma_f32 v21, -v25, v82, v21
	v_fma_f32 v36, -v27, v82, v23
	v_mul_f32_e32 v23, v26, v82
	v_mul_f32_e32 v25, v30, v132
	v_fma_f32 v24, v29, v132, v24
	v_mul_f32_e32 v26, v32, v170
	s_nop 0
	v_fma_f32 v37, v27, v37, v23
	v_mul_f32_e32 v27, v40, v151
	v_fma_f32 v34, -v31, v134, v25
	v_mul_f32_e32 v25, v30, v134
	v_mul_f32_e32 v23, v28, v132
	v_mul_f32_e32 v28, v42, v177
	v_fma_f32 v26, v33, v151, v26
	s_nop 0
	v_fma_f32 v82, -v41, v170, v27
	v_mul_f32_e32 v27, v40, v170
	v_fma_f32 v35, v31, v132, v25
	v_mul_f32_e32 v31, v48, v186
	v_mul_f32_e32 v25, v32, v151
	v_fma_f32 v28, v43, v171, v28
	v_mul_f32_e32 v32, v120, v189
	s_nop 0
	v_fma_f32 v132, v41, v151, v27
	v_mul_f32_e32 v27, v42, v171
	v_fma_f32 v42, -v49, v187, v31
	v_mul_f32_e32 v31, v48, v187
	v_fma_f32 v23, -v29, v134, v23
	v_fma_f32 v32, v121, v188, v32
	v_mul_f32_e32 v29, v44, v171
	s_nop 0
	v_fma_f32 v27, -v43, v177, v27
	v_fma_f32 v25, -v33, v170, v25
	v_fma_f32 v43, v49, v186, v31
	v_mul_f32_e32 v31, v120, v188
	v_fma_f32 v134, -v45, v177, v29
	v_mul_f32_e32 v29, v44, v177
	v_mul_f32_e32 v33, v122, v188
	v_mul_f32_e32 v48, v128, v192
	s_nop 0
	v_fma_f32 v31, -v121, v189, v31
	v_pk_mul_f32 v[120:121], v[130:131], v[192:193] op_sel:[0,0] op_sel_hi:[0,1]
	v_mul_f32_e32 v130, v18, v198
	v_mul_f32_e32 v18, v18, v199
	v_fma_f32 v44, v45, v171, v29
	v_fma_f32 v40, -v123, v189, v33
	v_mul_f32_e32 v33, v122, v189
	s_nop 0
	v_fma_f32 v130, -v19, v199, v130
	v_fma_f32 v18, v19, v198, v18
	v_mul_f32_e32 v19, v16, v198
	v_mul_f32_e32 v16, v16, v199
	v_fma_f32 v41, v123, v188, v33
	v_pk_mul_f32 v[122:123], v[178:179], v[194:195] op_sel:[0,0] op_sel_hi:[0,1]
	v_mul_f32_e32 v33, v124, v190
	v_mul_f32_e32 v45, v124, v191
	v_mul_f32_e32 v49, v128, v193
	s_nop 0
	v_fma_f32 v151, v17, v198, v16
	v_mul_f32_e32 v16, v14, v200
	v_mul_f32_e32 v14, v14, v201
	v_fma_f32 v33, -v125, v191, v33
	v_fma_f32 v45, v125, v190, v45
	v_pk_fma_f32 v[122:123], v[178:179], v[194:195], v[122:123] op_sel:[1,1,0] op_sel_hi:[1,0,1] neg_lo:[1,0,0] neg_hi:[0,0,0]
	s_nop 0
	v_fma_f32 v16, -v15, v201, v16
	v_fma_f32 v14, v15, v200, v14
	v_mul_f32_e32 v15, v12, v200
	v_mul_f32_e32 v12, v12, v201
	v_pk_mul_f32 v[124:125], v[180:181], v[194:195] op_sel:[0,0] op_sel_hi:[0,1]
	v_mul_f32_e32 v29, v46, v186
	v_mul_f32_e32 v30, v46, v187
	s_nop 0
	v_fma_f32 v170, -v13, v201, v15
	v_fma_f32 v171, v13, v200, v12
	v_mul_f32_e32 v12, v10, v202
	v_mul_f32_e32 v10, v10, v203
	v_sub_f32_e32 v13, v26, v18
	v_pk_fma_f32 v[48:49], v[128:129], v[192:193], v[48:49] op_sel:[1,1,0] op_sel_hi:[1,0,1] neg_lo:[1,0,0] neg_hi:[0,0,0]
	s_nop 0
	v_fma_f32 v12, -v11, v203, v12
	v_fma_f32 v10, v11, v202, v10
	v_mul_f32_e32 v11, v8, v202
	v_mul_f32_e32 v8, v8, v203
	v_pk_fma_f32 v[120:121], v[130:131], v[192:193], v[120:121] op_sel:[1,1,0] op_sel_hi:[1,0,1] neg_lo:[1,0,0] neg_hi:[0,0,0]
	v_fma_f32 v131, -v17, v199, v19
	v_fma_f32 v29, -v47, v187, v29
	v_fma_f32 v30, v47, v186, v30
	s_nop 0
	v_fma_f32 v177, -v9, v203, v11
	v_fma_f32 v178, v9, v202, v8
	v_mul_f32_e32 v8, v6, v204
	v_mul_f32_e32 v6, v6, v205
	v_add_f32_e32 v9, v26, v18
	v_sub_f32_e32 v11, v25, v130
	v_pk_mul_f32 v[46:47], v[126:127], v[190:191] op_sel:[0,0] op_sel_hi:[0,1]
	s_nop 0
	v_fma_f32 v8, -v7, v205, v8
	v_fma_f32 v6, v7, v204, v6
	v_mul_f32_e32 v7, v4, v204
	v_mul_f32_e32 v4, v4, v205
	v_pk_fma_f32 v[46:47], v[126:127], v[190:191], v[46:47] op_sel:[1,1,0] op_sel_hi:[1,0,1] neg_lo:[1,0,0] neg_hi:[0,0,0]
	v_pk_mul_f32 v[126:127], v[182:183], v[196:197] op_sel:[0,0] op_sel_hi:[0,1]
	s_nop 0
	v_fma_f32 v179, -v5, v205, v7
	v_fma_f32 v180, v5, v204, v4
	v_add_f32_e32 v4, v2, v33
	v_add_f32_e32 v5, v3, v45
	v_sub_f32_e32 v2, v2, v33
	v_sub_f32_e32 v3, v3, v45
	v_add_f32_e32 v7, v25, v130
	v_pk_fma_f32 v[126:127], v[182:183], v[196:197], v[126:127] op_sel:[1,1,0] op_sel_hi:[1,0,1] neg_lo:[1,0,0] neg_hi:[0,0,0]
	s_nop 0
	v_add_f32_e32 v17, v5, v9
	v_sub_f32_e32 v26, v5, v9
	v_add_f32_e32 v9, v3, v11
	v_add_f32_e32 v15, v4, v7
	v_sub_f32_e32 v25, v4, v7
	v_sub_f32_e32 v7, v2, v13
	v_add_f32_e32 v33, v2, v13
	v_sub_f32_e32 v45, v3, v11
	v_add_f32_e32 v2, v206, v48
	v_add_f32_e32 v3, v20, v49
	v_sub_f32_e32 v4, v206, v48
	v_sub_f32_e32 v5, v20, v49
	v_add_f32_e32 v11, v27, v16
	v_add_f32_e32 v13, v28, v14
	v_sub_f32_e32 v16, v27, v16
	v_sub_f32_e32 v14, v28, v14
	v_sub_f32_e32 v20, v21, v122
	v_add_f32_e32 v27, v30, v10
	s_nop 0
	v_add_f32_e32 v18, v2, v11
	v_add_f32_e32 v19, v3, v13
	v_sub_f32_e32 v2, v2, v11
	v_sub_f32_e32 v3, v3, v13
	v_sub_f32_e32 v11, v4, v14
	v_add_f32_e32 v13, v5, v16
	v_add_f32_e32 v4, v4, v14
	v_sub_f32_e32 v5, v5, v16
	v_add_f32_e32 v14, v21, v122
	v_add_f32_e32 v16, v22, v123
	v_sub_f32_e32 v10, v30, v10
	v_sub_f32_e32 v21, v22, v123
	v_add_f32_e32 v22, v29, v12
	v_sub_f32_e32 v12, v29, v12
	v_add_f32_e32 v48, v32, v6
	s_nop 0
	v_add_f32_e32 v29, v16, v27
	v_sub_f32_e32 v6, v32, v6
	v_mul_f32_e32 v2, v2, v154
	v_add_f32_e32 v28, v14, v22
	v_sub_f32_e32 v30, v14, v22
	v_sub_f32_e32 v14, v16, v27
	v_sub_f32_e32 v16, v20, v10
	v_add_f32_e32 v10, v20, v10
	v_add_f32_e32 v20, v23, v126
	v_sub_f32_e32 v23, v23, v126
	v_add_f32_e32 v27, v31, v8
	v_sub_f32_e32 v8, v31, v8
	v_add_f32_e32 v22, v21, v12
	v_sub_f32_e32 v12, v21, v12
	v_add_f32_e32 v21, v24, v127
	v_sub_f32_e32 v24, v24, v127
	s_nop 0
	v_add_f32_e32 v31, v20, v27
	v_sub_f32_e32 v20, v20, v27
	v_sub_f32_e32 v27, v23, v6
	v_add_f32_e32 v6, v23, v6
	v_mul_f32_e32 v23, v11, v152
	v_mul_f32_e32 v11, v11, v156
	v_add_f32_e32 v32, v21, v48
	v_sub_f32_e32 v21, v21, v48
	v_add_f32_e32 v48, v24, v8
	v_sub_f32_e32 v8, v24, v8
	s_nop 0
	v_fma_f32 v23, -v13, v156, v23
	v_fma_f32 v13, v13, v152, v11
	v_mul_f32_e32 v11, v16, v154
	v_fma_f32 v49, v3, v154, v2
	v_pk_fma_f32 v[124:125], v[180:181], v[194:195], v[124:125] op_sel:[1,1,0] op_sel_hi:[1,0,1] neg_lo:[1,0,0] neg_hi:[0,0,0]
	v_xor_b32_e32 v122, 0x80000000, v14
	v_fma_f32 v16, -v22, v154, v11
	v_fma_f32 v22, v22, v154, v11
	v_mul_f32_e32 v11, v27, v156
	v_pk_mul_f32 v[128:129], v[184:185], v[196:197] op_sel:[0,0] op_sel_hi:[0,1]
	s_nop 0
	v_fma_f32 v24, -v48, v152, v11
	v_mul_f32_e32 v11, v27, v152
	v_pk_fma_f32 v[128:129], v[184:185], v[196:197], v[128:129] op_sel:[1,1,0] op_sel_hi:[1,0,1] neg_lo:[1,0,0] neg_hi:[0,0,0]
	s_nop 0
	v_fma_f32 v27, v48, v156, v11
	v_fma_f32 v48, -v3, v154, v2
	v_mul_f32_e32 v2, v20, v155
	v_add_f32_e32 v3, v17, v29
	s_nop 0
	v_fma_f32 v123, -v21, v154, v2
	v_mul_f32_e32 v2, v20, v154
	s_nop 0
	v_fma_f32 v20, v21, v155, v2
	v_mul_f32_e32 v2, v4, v156
	s_nop 0
	v_fma_f32 v21, -v5, v152, v2
	v_mul_f32_e32 v2, v4, v152
	v_add_f32_e32 v4, v18, v31
	s_nop 0
	v_fma_f32 v126, v5, v156, v2
	v_mul_f32_e32 v2, v10, v155
	v_add_f32_e32 v5, v19, v32
	s_nop 0
	v_fma_f32 v127, -v12, v154, v2
	v_mul_f32_e32 v2, v10, v154
	s_nop 0
	v_fma_f32 v130, v12, v155, v2
	v_mul_f32_e32 v2, v6, v157
	v_sub_f32_e32 v12, v18, v31
	s_nop 0
	v_fma_f32 v181, -v8, v153, v2
	v_mul_f32_e32 v2, v6, v153
	v_sub_f32_e32 v6, v15, v28
	s_nop 0
	v_fma_f32 v182, v8, v157, v2
	v_add_f32_e32 v2, v15, v28
	v_sub_f32_e32 v8, v17, v29
	v_sub_f32_e32 v17, v19, v32
	v_pk_add_f32 v[14:15], v[2:3], v[4:5] op_sel:[0,0] op_sel_hi:[1,1]
	s_nop 0
	v_pk_add_f32 v[4:5], v[2:3], v[4:5] op_sel:[0,0] op_sel_hi:[1,1] neg_lo:[0,1] neg_hi:[0,1]
	v_sub_f32_e32 v10, v6, v17
	v_add_f32_e32 v11, v8, v12
	v_add_f32_e32 v2, v6, v17
	v_sub_f32_e32 v3, v8, v12
	v_add_f32_e32 v12, v9, v22
	v_pk_add_f32 v[6:7], v[6:7], v[16:17] op_sel:[1,0] op_sel_hi:[1,0] neg_lo:[0,0] neg_hi:[0,1]
	v_sub_f32_e32 v16, v9, v22
	v_add_f32_e32 v8, v23, v24
	v_add_f32_e32 v9, v13, v27
	v_sub_f32_e32 v17, v23, v24
	v_sub_f32_e32 v13, v13, v27
	v_sub_f32_e32 v24, v25, v122
	s_nop 0
	v_add_f32_e32 v22, v6, v8
	v_add_f32_e32 v23, v12, v9
	v_sub_f32_e32 v8, v6, v8
	v_sub_f32_e32 v9, v12, v9
	v_sub_f32_e32 v18, v7, v13
	v_add_f32_e32 v19, v16, v17
	v_add_f32_e32 v6, v7, v13
	v_sub_f32_e32 v7, v16, v17
	v_add_f32_e32 v12, v25, v122
	v_add_f32_e32 v13, v26, v30
	v_sub_f32_e32 v25, v26, v30
	v_add_f32_e32 v16, v48, v123
	v_add_f32_e32 v17, v49, v20
	v_sub_f32_e32 v30, v48, v123
	v_sub_f32_e32 v20, v49, v20
	v_sub_f32_e32 v48, v33, v127
	v_sub_f32_e32 v49, v126, v182
	s_nop 0
	v_pk_add_f32 v[28:29], v[12:13], v[16:17] op_sel:[0,0] op_sel_hi:[1,1]
	v_pk_add_f32 v[16:17], v[12:13], v[16:17] op_sel:[0,0] op_sel_hi:[1,1] neg_lo:[0,1] neg_hi:[0,1]
	v_sub_f32_e32 v26, v24, v20
	v_add_f32_e32 v27, v25, v30
	v_add_f32_e32 v12, v24, v20
	v_sub_f32_e32 v13, v25, v30
	v_add_f32_e32 v20, v33, v127
	v_add_f32_e32 v25, v45, v130
	v_sub_f32_e32 v45, v45, v130
	v_add_f32_e32 v24, v21, v181
	v_add_f32_e32 v30, v126, v182
	v_sub_f32_e32 v21, v21, v181
	s_nop 0
	v_add_f32_e32 v32, v20, v24
	v_add_f32_e32 v33, v25, v30
	v_sub_f32_e32 v24, v20, v24
	v_sub_f32_e32 v25, v25, v30
	v_sub_f32_e32 v30, v48, v49
	v_add_f32_e32 v31, v45, v21
	v_add_f32_e32 v20, v48, v49
	v_sub_f32_e32 v21, v45, v21
	v_add_f32_e32 v45, v0, v46
	v_add_f32_e32 v48, v1, v47
	v_pk_add_f32 v[0:1], v[0:1], v[46:47] op_sel:[0,0] op_sel_hi:[1,1] neg_lo:[0,1] neg_hi:[0,1]
	v_add_f32_e32 v46, v82, v131
	v_add_f32_e32 v47, v132, v151
	v_sub_f32_e32 v49, v82, v131
	v_sub_f32_e32 v82, v132, v151
	s_nop 0
	v_add_f32_e32 v122, v45, v46
	v_add_f32_e32 v123, v48, v47
	v_sub_f32_e32 v126, v45, v46
	v_sub_f32_e32 v48, v48, v47
	v_sub_f32_e32 v45, v0, v82
	v_add_f32_e32 v46, v1, v49
	v_add_f32_e32 v82, v0, v82
	v_sub_f32_e32 v127, v1, v49
	v_pk_add_f32 v[0:1], v[38:39], v[120:121] op_sel:[0,0] op_sel_hi:[1,1]
	v_pk_add_f32 v[38:39], v[38:39], v[120:121] op_sel:[0,0] op_sel_hi:[1,1] neg_lo:[0,1] neg_hi:[0,1]
	v_add_f32_e32 v47, v134, v170
	v_add_f32_e32 v49, v44, v171
	v_sub_f32_e32 v120, v134, v170
	v_sub_f32_e32 v44, v44, v171
	s_nop 0
	v_add_f32_e32 v121, v0, v47
	v_add_f32_e32 v130, v1, v49
	v_sub_f32_e32 v0, v0, v47
	v_sub_f32_e32 v1, v1, v49
	v_sub_f32_e32 v47, v38, v44
	v_add_f32_e32 v49, v39, v120
	v_add_f32_e32 v38, v38, v44
	v_sub_f32_e32 v39, v39, v120
	v_add_f32_e32 v44, v36, v124
	v_add_f32_e32 v120, v37, v125
	v_pk_add_f32 v[36:37], v[36:37], v[124:125] op_sel:[0,0] op_sel_hi:[1,1] neg_lo:[0,1] neg_hi:[0,1]
	v_add_f32_e32 v124, v42, v177
	v_add_f32_e32 v125, v43, v178
	v_sub_f32_e32 v42, v42, v177
	v_sub_f32_e32 v43, v43, v178
	s_nop 0
	v_mul_f32_e32 v0, v0, v154
	v_add_f32_e32 v131, v44, v124
	v_add_f32_e32 v132, v120, v125
	v_sub_f32_e32 v124, v44, v124
	v_sub_f32_e32 v44, v120, v125
	v_sub_f32_e32 v120, v36, v43
	v_add_f32_e32 v125, v37, v42
	v_pk_add_f32 v[36:37], v[36:37], v[42:43] op_sel:[0,1] op_sel_hi:[1,0] neg_lo:[0,0] neg_hi:[0,1]
	v_pk_add_f32 v[42:43], v[34:35], v[128:129] op_sel:[0,0] op_sel_hi:[1,1]
	v_pk_add_f32 v[34:35], v[34:35], v[128:129] op_sel:[0,0] op_sel_hi:[1,1] neg_lo:[0,1] neg_hi:[0,1]
	v_add_f32_e32 v128, v40, v179
	v_add_f32_e32 v129, v41, v180
	v_sub_f32_e32 v40, v40, v179
	v_sub_f32_e32 v41, v41, v180
	s_nop 0
	v_xor_b32_e32 v170, 0x80000000, v44
	v_add_f32_e32 v134, v42, v128
	v_add_f32_e32 v151, v43, v129
	v_pk_add_f32 v[42:43], v[42:43], v[128:129] op_sel:[0,0] op_sel_hi:[1,1] neg_lo:[0,1] neg_hi:[0,1]
	v_pk_add_f32 v[128:129], v[34:35], v[40:41] op_sel:[0,1] op_sel_hi:[1,0] neg_lo:[0,1] neg_hi:[0,0]
	v_pk_add_f32 v[34:35], v[34:35], v[40:41] op_sel:[0,1] op_sel_hi:[1,0] neg_lo:[0,0] neg_hi:[0,1]
	v_mul_f32_e32 v40, v47, v152
	v_mul_f32_e32 v41, v47, v156
	v_mul_f32_e32 v47, v120, v154
	s_nop 0
	v_mul_f32_e32 v120, v128, v156
	v_fma_f32 v40, -v49, v156, v40
	v_fma_f32 v41, v49, v152, v41
	v_fma_f32 v49, -v125, v154, v47
	v_fma_f32 v47, v125, v154, v47
	v_mul_f32_e32 v125, v128, v152
	s_nop 0
	v_fma_f32 v120, -v129, v152, v120
	v_fma_f32 v125, v129, v156, v125
	v_pk_fma_f32 v[128:129], v[0:1], v[154:155], v[0:1] op_sel:[1,0,0] op_sel_hi:[1,0,0] neg_lo:[1,0,0] neg_hi:[0,0,0]
	v_mul_f32_e32 v0, v42, v155
	s_nop 0
	v_add_f32_e32 v44, v40, v120
	v_sub_f32_e32 v120, v40, v120
	v_fma_f32 v171, -v43, v154, v0
	v_mul_f32_e32 v0, v42, v154
	v_sub_f32_e32 v42, v121, v134
	s_nop 0
	v_fma_f32 v177, v43, v155, v0
	v_mul_f32_e32 v0, v38, v156
	v_sub_f32_e32 v43, v130, v151
	s_nop 0
	v_fma_f32 v178, -v39, v152, v0
	v_mul_f32_e32 v0, v38, v152
	v_sub_f32_e32 v38, v122, v131
	s_nop 0
	v_fma_f32 v179, v39, v156, v0
	v_mul_f32_e32 v0, v36, v155
	v_sub_f32_e32 v39, v123, v132
	s_nop 0
	v_fma_f32 v180, -v37, v154, v0
	v_mul_f32_e32 v0, v36, v154
	v_add_f32_e32 v36, v121, v134
	v_add_f32_e32 v121, v48, v124
	s_nop 0
	v_fma_f32 v181, v37, v155, v0
	v_mul_f32_e32 v0, v34, v157
	v_add_f32_e32 v37, v130, v151
	s_nop 0
	v_fma_f32 v182, -v35, v153, v0
	v_mul_f32_e32 v0, v34, v153
	v_add_f32_e32 v34, v122, v131
	v_add_f32_e32 v122, v128, v171
	v_sub_f32_e32 v128, v128, v171
	s_nop 0
	v_fma_f32 v183, v35, v157, v0
	v_add_f32_e32 v35, v123, v132
	v_pk_add_f32 v[0:1], v[34:35], v[36:37] op_sel:[0,0] op_sel_hi:[1,1]
	v_pk_add_f32 v[34:35], v[34:35], v[36:37] op_sel:[0,0] op_sel_hi:[1,1] neg_lo:[0,1] neg_hi:[0,1]
	v_pk_add_f32 v[36:37], v[38:39], v[42:43] op_sel:[0,1] op_sel_hi:[1,0] neg_lo:[0,1] neg_hi:[0,0]
	v_pk_add_f32 v[38:39], v[38:39], v[42:43] op_sel:[0,1] op_sel_hi:[1,0] neg_lo:[0,0] neg_hi:[0,1]
	v_add_f32_e32 v43, v46, v47
	s_nop 0
	v_add_f32_e32 v42, v45, v49
	v_sub_f32_e32 v49, v45, v49
	v_sub_f32_e32 v47, v46, v47
	v_add_f32_e32 v45, v41, v125
	v_sub_f32_e32 v46, v41, v125
	v_sub_f32_e32 v125, v126, v170
	v_add_f32_e32 v123, v129, v177
	s_nop 0
	v_pk_add_f32 v[40:41], v[42:43], v[44:45] op_sel:[0,0] op_sel_hi:[1,1]
	v_pk_add_f32 v[42:43], v[42:43], v[44:45] op_sel:[0,0] op_sel_hi:[1,1] neg_lo:[0,1] neg_hi:[0,1]
	v_add_f32_e32 v45, v47, v120
	v_sub_f32_e32 v47, v47, v120
	v_add_f32_e32 v120, v126, v170
	v_sub_f32_e32 v126, v48, v124
	v_sub_f32_e32 v124, v129, v177
	v_sub_f32_e32 v44, v49, v46
	v_add_f32_e32 v46, v49, v46
	s_nop 0
	v_pk_add_f32 v[48:49], v[120:121], v[122:123] op_sel:[0,0] op_sel_hi:[1,1]
	v_pk_add_f32 v[120:121], v[120:121], v[122:123] op_sel:[0,0] op_sel_hi:[1,1] neg_lo:[0,1] neg_hi:[0,1]
	v_sub_f32_e32 v122, v125, v124
	v_add_f32_e32 v123, v126, v128
	v_add_f32_e32 v124, v125, v124
	v_sub_f32_e32 v125, v126, v128
	v_add_f32_e32 v128, v82, v180
	v_add_f32_e32 v129, v127, v181
	v_pk_add_f32 v[130:131], v[178:179], v[182:183] op_sel:[0,0] op_sel_hi:[1,1]
	v_sub_f32_e32 v82, v82, v180
	v_sub_f32_e32 v132, v127, v181
	v_sub_f32_e32 v134, v178, v182
	v_sub_f32_e32 v151, v179, v183
	s_nop 0
	v_pk_add_f32 v[126:127], v[128:129], v[130:131] op_sel:[0,0] op_sel_hi:[1,1]
	v_pk_add_f32 v[128:129], v[128:129], v[130:131] op_sel:[0,0] op_sel_hi:[1,1] neg_lo:[0,1] neg_hi:[0,1]
	v_add_f32_e32 v131, v132, v134
	v_sub_f32_e32 v130, v82, v151
	v_add_f32_e32 v178, v82, v151
	v_sub_f32_e32 v179, v132, v134
	ds_write_b64 v138, v[14:15]
	ds_write_b64 v137, v[0:1] offset:4096
	ds_write_b64 v138, v[22:23] offset:544
	ds_write_b64 v137, v[40:41] offset:4640
	ds_write_b64 v138, v[28:29] offset:1088
	ds_write_b64 v137, v[48:49] offset:5184
	ds_write_b64 v138, v[32:33] offset:1632
	ds_write_b64 v137, v[126:127] offset:5728
	ds_write_b64 v138, v[10:11] offset:2176
	ds_write_b64 v137, v[36:37] offset:6272
	ds_write_b64 v138, v[18:19] offset:2720
	ds_write_b64 v137, v[44:45] offset:6816
	ds_write_b64 v138, v[26:27] offset:3264
	ds_write_b64 v137, v[122:123] offset:7360
	ds_write_b64 v138, v[30:31] offset:3808
	ds_write_b64 v137, v[130:131] offset:7904
	ds_write_b64 v138, v[4:5] offset:4352
	ds_write_b64 v137, v[34:35] offset:8448
	ds_write_b64 v138, v[8:9] offset:4896
	ds_write_b64 v137, v[42:43] offset:8992
	ds_write_b64 v138, v[16:17] offset:5440
	ds_write_b64 v137, v[120:121] offset:9536
	ds_write_b64 v138, v[24:25] offset:5984
	ds_write_b64 v137, v[128:129] offset:10080
	ds_write_b64 v138, v[2:3] offset:6528
	ds_write_b64 v137, v[38:39] offset:10624
	ds_write_b64 v138, v[6:7] offset:7072
	ds_write_b64 v137, v[46:47] offset:11168
	ds_write_b64 v138, v[12:13] offset:7616
	ds_write_b64 v137, v[124:125] offset:11712
	ds_write_b64 v138, v[20:21] offset:8160
	ds_write_b64 v137, v[178:179] offset:12256
	v_lshl_add_u64 v[18:19], s[36:37], 0, v[86:87]
	v_add_co_u32_e32 v0, vcc, s87, v18
	v_lshl_add_u64 v[2:3], s[36:37], 0, v[88:89]
	s_nop 0
	v_addc_co_u32_e32 v1, vcc, 0, v19, vcc
	v_lshl_add_u64 v[4:5], s[36:37], 0, v[90:91]
	global_load_dwordx4 v[12:15], v[0:1], off nt
	global_load_ushort v177, v[2:3], off
	global_load_ushort v134, v[4:5], off
	v_add_co_u32_e32 v0, vcc, s88, v18
	v_lshl_add_u64 v[16:17], s[36:37], 0, v[98:99]
	s_nop 0
	v_addc_co_u32_e32 v1, vcc, 0, v19, vcc
	v_lshl_add_u64 v[2:3], s[36:37], 0, v[94:95]
	v_lshl_add_u64 v[4:5], s[36:37], 0, v[96:97]
	global_load_dwordx4 v[8:11], v[0:1], off nt
	global_load_ushort v179, v[2:3], off
	global_load_ushort v178, v[4:5], off
	v_add_co_u32_e32 v0, vcc, s87, v16
	v_lshl_add_u64 v[20:21], s[36:37], 0, v[102:103]
	s_nop 0
	v_addc_co_u32_e32 v1, vcc, 0, v17, vcc
	v_lshl_add_u64 v[2:3], s[36:37], 0, v[100:101]
	global_load_dwordx4 v[4:7], v[0:1], off nt
	global_load_ushort v131, v[2:3], off
	global_load_ushort v82, v[20:21], off
	v_lshl_add_u64 v[0:1], s[36:37], 0, v[104:105]
	v_lshl_add_u64 v[20:21], s[36:37], 0, v[106:107]
	v_lshl_add_u64 v[22:23], s[36:37], 0, v[108:109]
	global_load_dwordx4 v[0:3], v[0:1], off nt
	s_nop 0
	global_load_ushort v132, v[20:21], off
	global_load_ushort v130, v[22:23], off
	v_mov_b32_e32 v20, v92
	s_waitcnt lgkmcnt(0)
	s_barrier
	s_nop 0
	v_ashrrev_i32_e32 v22, 31, v20
	v_lshrrev_b32_e32 v22, 22, v22
	v_add_u32_e32 v22, v20, v22
	v_ashrrev_i32_e32 v22, 10, v22
	v_add_u32_e32 v21, 0x200, v20
	v_mul_i32_i24_e32 v23, 0x400, v22
	v_sub_u32_e32 v24, v20, v23
	v_ashrrev_i32_e32 v23, 31, v21
	v_lshrrev_b32_e32 v23, 22, v23
	v_add_u32_e32 v23, v21, v23
	v_lshl_add_u32 v22, v22, 14, v24
	v_ashrrev_i32_e32 v23, 10, v23
	v_mul_i32_i24_e32 v25, 0x3c00, v23
	v_mad_i32_i24 v21, v23, s64, v21
	v_ashrrev_i32_e32 v23, 4, v22
	v_lshlrev_b32_e32 v23, 3, v23
	v_ashrrev_i32_e32 v21, 4, v21
	v_and_b32_e32 v23, 0xffffffe0, v23
	v_lshlrev_b32_e32 v22, 3, v22
	v_lshlrev_b32_e32 v21, 3, v21
	v_add3_u32 v180, 0, v23, v22
	v_and_b32_e32 v21, 0xffffffe0, v21
	v_add_lshl_u32 v20, v25, v20, 3
	v_add3_u32 v181, 0, v21, v20
	v_add_u32_e32 v25, 0x11000, v180
	ds_read_b64 v[22:23], v180
	ds_read_b64 v[20:21], v181 offset:4096
	ds_read_b64 v[182:183], v180 offset:8704
	ds_read_b64 v[184:185], v181 offset:12800
	ds_read_b64 v[188:189], v180 offset:17408
	ds_read_b64 v[190:191], v181 offset:21504
	ds_read_b64 v[192:193], v180 offset:26112
	ds_read_b64 v[194:195], v181 offset:30208
	ds_read_b64 v[196:197], v180 offset:34816
	ds_read_b64 v[198:199], v181 offset:38912
	ds_read_b64 v[200:201], v180 offset:43520
	ds_read_b64 v[202:203], v181 offset:47616
	ds_read_b64 v[204:205], v180 offset:52224
	ds_read_b64 v[206:207], v181 offset:56320
	ds_read_b64 v[128:129], v180 offset:60928
	ds_read_b64 v[126:127], v181 offset:65024
	ds_read_b64 v[124:125], v25
	v_add_u32_e32 v25, 0x12000, v181
	ds_read_b64 v[122:123], v25
	v_add_u32_e32 v25, 0x13200, v180
	ds_read_b64 v[120:121], v25
	v_add_u32_e32 v25, 0x14200, v181
	ds_read_b64 v[48:49], v25
	v_add_u32_e32 v25, 0x15400, v180
	ds_read_b64 v[46:47], v25
	v_add_u32_e32 v25, 0x16400, v181
	ds_read_b64 v[44:45], v25
	v_add_u32_e32 v25, 0x17600, v180
	ds_read_b64 v[42:43], v25
	v_add_u32_e32 v25, 0x18600, v181
	ds_read_b64 v[40:41], v25
	v_add_u32_e32 v25, 0x19800, v180
	ds_read_b64 v[38:39], v25
	v_add_u32_e32 v25, 0x1a800, v181
	v_cvt_f32_i32_e32 v24, v24
	ds_read_b64 v[36:37], v25
	v_add_u32_e32 v25, 0x1ba00, v180
	ds_read_b64 v[34:35], v25
	v_add_u32_e32 v25, 0x1ca00, v181
	ds_read_b64 v[32:33], v25
	v_add_u32_e32 v25, 0x1dc00, v180
	ds_read_b64 v[28:29], v25
	v_add_u32_e32 v25, 0x1ec00, v181
	v_mul_f32_e32 v24, 0x38800000, v24
	ds_read_b64 v[30:31], v25
	v_add_u32_e32 v25, 0x1fe00, v180
	v_sin_f32_e32 v151, v24
	v_cos_f32_e32 v170, v24
	v_add_u32_e32 v24, 0x20e00, v181
	ds_read_b64 v[26:27], v25
	ds_read_b64 v[24:25], v24
	s_nop 1
	s_nop 0
	v_mul_f32_e32 v171, v170, v170
	v_mul_f32_e32 v186, v170, v151
	s_nop 0
	v_fma_f32 v171, -v151, v151, v171
	v_fma_f32 v208, v151, v170, v186
	s_nop 0
	v_mul_f32_e32 v186, v171, v170
	s_nop 0
	v_fma_f32 v209, -v208, v151, v186
	v_mul_f32_e32 v186, v171, v151
	s_nop 0
	v_fma_f32 v210, v208, v170, v186
	v_mul_f32_e32 v186, v171, v171
	s_nop 0
	v_fma_f32 v211, -v208, v208, v186
	v_mul_f32_e32 v186, v171, v208
	s_nop 0
	v_fma_f32 v212, v208, v171, v186
	v_mul_f32_e32 v186, v211, v170
	s_nop 0
	v_fma_f32 v213, -v212, v151, v186
	v_mul_f32_e32 v186, v211, v151
	s_nop 0
	v_fma_f32 v214, v212, v170, v186
	v_mul_f32_e32 v186, v209, v209
	s_nop 0
	v_fma_f32 v215, -v210, v210, v186
	v_mul_f32_e32 v186, v209, v210
	s_nop 0
	v_fma_f32 v216, v210, v209, v186
	v_mul_f32_e32 v186, v211, v209
	s_nop 0
	v_fma_f32 v217, -v212, v210, v186
	v_mul_f32_e32 v186, v211, v210
	s_nop 0
	v_fma_f32 v218, v212, v209, v186
	v_mul_f32_e32 v186, v211, v211
	s_nop 0
	v_fma_f32 v219, -v212, v212, v186
	v_mul_f32_e32 v186, v211, v212
	s_nop 0
	v_fma_f32 v220, v212, v211, v186
	v_mul_f32_e32 v186, v219, v170
	s_nop 0
	v_fma_f32 v221, -v220, v151, v186
	v_mul_f32_e32 v186, v219, v151
	s_nop 0
	v_fma_f32 v222, v220, v170, v186
	v_mul_f32_e32 v186, v213, v213
	s_nop 0
	v_fma_f32 v223, -v214, v214, v186
	v_mul_f32_e32 v186, v213, v214
	s_nop 0
	v_fma_f32 v224, v214, v213, v186
	v_mul_f32_e32 v186, v219, v209
	s_nop 0
	v_fma_f32 v225, -v220, v210, v186
	v_mul_f32_e32 v186, v219, v210
	s_nop 0
	v_fma_f32 v226, v220, v209, v186
	v_mul_f32_e32 v186, v215, v215
	s_nop 0
	v_fma_f32 v227, -v216, v216, v186
	v_mul_f32_e32 v186, v215, v216
	s_nop 0
	v_fma_f32 v228, v216, v215, v186
	v_mul_f32_e32 v186, v219, v213
	s_nop 0
	v_fma_f32 v229, -v220, v214, v186
	v_mul_f32_e32 v186, v219, v214
	s_nop 0
	v_fma_f32 v230, v220, v213, v186
	v_mul_f32_e32 v186, v217, v217
	s_nop 0
	v_fma_f32 v231, -v218, v218, v186
	v_mul_f32_e32 v186, v217, v218
	s_nop 0
	v_fma_f32 v232, v218, v217, v186
	v_mul_f32_e32 v186, v219, v217
	s_nop 0
	v_fma_f32 v233, -v220, v218, v186
	v_mul_f32_e32 v186, v219, v218
	s_nop 0
	v_fma_f32 v234, v220, v217, v186
	s_waitcnt lgkmcnt(0)
	v_mul_f32_e32 v186, v182, v170
	v_mul_f32_e32 v182, v182, v151
	s_nop 0
	v_fma_f32 v236, v183, v170, v182
	v_mul_f32_e32 v182, s71, v184
	v_fma_f32 v235, -v183, v151, v186
	v_mul_f32_e32 v183, s77, v184
	s_nop 0
	v_fma_f32 v182, -v185, s77, v182
	v_fma_f32 v183, v185, s71, v183
	s_nop 0
	v_mul_f32_e32 v184, v182, v170
	s_nop 0
	v_fma_f32 v186, -v183, v151, v184
	v_mul_f32_e32 v151, v182, v151
	v_mul_f32_e32 v182, s65, v190
	s_nop 0
	v_fma_f32 v182, -v191, s69, v182
	v_fma_f32 v187, v183, v170, v151
	v_mul_f32_e32 v183, s69, v190
	v_mul_f32_e32 v170, v188, v208
	v_mul_f32_e32 v151, v188, v171
	s_nop 0
	v_mul_f32_e32 v184, v182, v171
	v_mul_f32_e32 v182, v182, v208
	v_fma_f32 v183, v191, s65, v183
	v_fma_f32 v170, v189, v171, v170
	v_fma_f32 v151, -v189, v208, v151
	s_nop 0
	v_fma_f32 v185, v183, v171, v182
	v_mul_f32_e32 v182, v192, v210
	v_fma_f32 v184, -v183, v208, v184
	v_mul_f32_e32 v171, v192, v209
	v_mul_f32_e32 v183, s75, v194
	s_nop 0
	v_fma_f32 v192, v193, v209, v182
	v_mul_f32_e32 v182, s73, v194
	v_fma_f32 v183, v195, s73, v183
	v_fma_f32 v171, -v193, v210, v171
	s_nop 0
	v_fma_f32 v188, -v195, s75, v182
	s_nop 0
	v_mul_f32_e32 v182, v188, v209
	v_mul_f32_e32 v188, v188, v210
	s_nop 0
	v_fma_f32 v182, -v183, v210, v182
	v_fma_f32 v183, v183, v209, v188
	v_mul_f32_e32 v188, v196, v211
	s_waitcnt vmcnt(0)
	v_lshlrev_b32_e32 v210, 16, v13
	v_fma_f32 v193, -v197, v212, v188
	v_mul_f32_e32 v188, v196, v212
	s_nop 0
	v_fma_f32 v194, v197, v211, v188
	v_mul_f32_e32 v188, s67, v198
	s_nop 0
	v_fma_f32 v189, -v199, s67, v188
	v_fma_f32 v188, v199, s67, v188
	s_nop 0
	v_mul_f32_e32 v190, v189, v211
	v_mul_f32_e32 v189, v189, v212
	s_nop 0
	v_fma_f32 v195, -v188, v212, v190
	v_fma_f32 v196, v188, v211, v189
	v_mul_f32_e32 v188, v200, v213
	v_mul_f32_e32 v189, s73, v202
	v_lshlrev_b32_e32 v211, 16, v14
	v_fma_f32 v197, -v201, v214, v188
	v_mul_f32_e32 v188, v200, v214
	v_fma_f32 v189, v203, s75, v189
	v_and_b32_e32 v14, 0xffff0000, v14
	v_fma_f32 v198, v201, v213, v188
	v_mul_f32_e32 v188, s75, v202
	s_nop 0
	v_fma_f32 v188, -v203, s73, v188
	s_nop 0
	v_mul_f32_e32 v190, v188, v213
	v_mul_f32_e32 v188, v188, v214
	s_nop 0
	v_fma_f32 v191, v189, v213, v188
	v_mul_f32_e32 v188, v204, v215
	v_fma_f32 v190, -v189, v214, v190
	v_mul_f32_e32 v189, s65, v206
	s_nop 0
	v_fma_f32 v199, -v205, v216, v188
	v_mul_f32_e32 v188, v204, v216
	v_fma_f32 v189, v207, s69, v189
	s_nop 0
	v_fma_f32 v200, v205, v215, v188
	v_mul_f32_e32 v188, s69, v206
	s_nop 0
	v_fma_f32 v201, -v207, s65, v188
	s_nop 0
	v_mul_f32_e32 v188, v201, v215
	v_mul_f32_e32 v201, v201, v216
	s_nop 0
	v_fma_f32 v188, -v189, v216, v188
	v_fma_f32 v189, v189, v215, v201
	v_mul_f32_e32 v201, v128, v217
	v_mul_f32_e32 v128, v128, v218
	s_nop 0
	v_fma_f32 v201, -v129, v218, v201
	v_fma_f32 v128, v129, v217, v128
	v_mul_f32_e32 v129, s77, v126
	v_mul_f32_e32 v126, s71, v126
	s_nop 0
	v_fma_f32 v129, -v127, s71, v129
	v_fma_f32 v127, v127, s77, v126
	s_nop 0
	v_mul_f32_e32 v126, v129, v217
	v_mul_f32_e32 v129, v129, v218
	s_nop 0
	v_fma_f32 v126, -v127, v218, v126
	v_fma_f32 v127, v127, v217, v129
	v_mul_f32_e32 v129, v124, v219
	v_mul_f32_e32 v124, v124, v220
	s_nop 0
	v_fma_f32 v129, -v125, v220, v129
	v_fma_f32 v124, v125, v219, v124
	v_mul_f32_e32 v125, s59, v122
	v_mul_f32_e32 v122, s84, v122
	s_nop 0
	v_fma_f32 v125, -v123, s84, v125
	v_fma_f32 v122, v123, s59, v122
	s_nop 0
	v_mul_f32_e32 v123, v125, v219
	v_mul_f32_e32 v125, v125, v220
	s_nop 0
	v_fma_f32 v123, -v122, v220, v123
	v_fma_f32 v122, v122, v219, v125
	v_mul_f32_e32 v125, v120, v221
	v_mul_f32_e32 v120, v120, v222
	s_nop 0
	v_fma_f32 v125, -v121, v222, v125
	v_fma_f32 v120, v121, v221, v120
	v_mul_f32_e32 v121, s72, v48
	v_mul_f32_e32 v48, s71, v48
	s_nop 0
	v_fma_f32 v121, -v49, s71, v121
	v_fma_f32 v48, v49, s72, v48
	s_nop 0
	v_mul_f32_e32 v49, v121, v221
	v_mul_f32_e32 v121, v121, v222
	s_nop 0
	v_fma_f32 v49, -v48, v222, v49
	v_fma_f32 v48, v48, v221, v121
	v_mul_f32_e32 v121, v46, v223
	v_mul_f32_e32 v46, v46, v224
	s_nop 0
	v_fma_f32 v121, -v47, v224, v121
	v_fma_f32 v46, v47, v223, v46
	v_mul_f32_e32 v47, s66, v44
	v_mul_f32_e32 v44, s65, v44
	s_nop 0
	v_fma_f32 v47, -v45, s65, v47
	v_fma_f32 v44, v45, s66, v44
	s_nop 0
	v_mul_f32_e32 v45, v47, v223
	v_mul_f32_e32 v47, v47, v224
	s_nop 0
	v_fma_f32 v45, -v44, v224, v45
	v_fma_f32 v44, v44, v223, v47
	v_mul_f32_e32 v47, v42, v225
	v_mul_f32_e32 v42, v42, v226
	s_nop 0
	v_fma_f32 v47, -v43, v226, v47
	v_fma_f32 v42, v43, v225, v42
	v_mul_f32_e32 v43, s74, v40
	v_mul_f32_e32 v40, s73, v40
	s_nop 0
	v_fma_f32 v43, -v41, s73, v43
	v_fma_f32 v40, v41, s74, v40
	s_nop 0
	v_mul_f32_e32 v41, v43, v225
	v_mul_f32_e32 v43, v43, v226
	s_nop 0
	v_fma_f32 v41, -v40, v226, v41
	v_fma_f32 v40, v40, v225, v43
	v_mul_f32_e32 v43, v38, v227
	v_mul_f32_e32 v38, v38, v228
	s_nop 0
	v_fma_f32 v43, -v39, v228, v43
	v_fma_f32 v38, v39, v227, v38
	v_mul_f32_e32 v39, s68, v36
	v_mul_f32_e32 v36, s67, v36
	s_nop 0
	v_fma_f32 v39, -v37, s67, v39
	v_fma_f32 v36, v37, s68, v36
	s_nop 0
	v_mul_f32_e32 v37, v39, v227
	s_nop 0
	v_fma_f32 v202, -v36, v228, v37
	v_mul_f32_e32 v37, v39, v228
	s_nop 0
	v_fma_f32 v39, v36, v227, v37
	v_mul_f32_e32 v36, v34, v229
	v_mul_f32_e32 v34, v34, v230
	s_nop 0
	v_fma_f32 v36, -v35, v230, v36
	v_fma_f32 v34, v35, v229, v34
	v_mul_f32_e32 v35, s76, v32
	v_mul_f32_e32 v32, s75, v32
	s_nop 0
	v_fma_f32 v35, -v33, s75, v35
	v_fma_f32 v32, v33, s76, v32
	s_nop 0
	v_mul_f32_e32 v33, v35, v229
	s_nop 0
	v_fma_f32 v203, -v32, v230, v33
	v_mul_f32_e32 v33, v35, v230
	s_nop 0
	v_fma_f32 v204, v32, v229, v33
	v_mul_f32_e32 v32, v28, v231
	v_mul_f32_e32 v28, v28, v232
	v_sub_f32_e32 v33, v194, v38
	s_nop 0
	v_fma_f32 v32, -v29, v232, v32
	v_fma_f32 v28, v29, v231, v28
	v_mul_f32_e32 v29, s70, v30
	v_mul_f32_e32 v30, s69, v30
	s_nop 0
	v_fma_f32 v29, -v31, s69, v29
	v_fma_f32 v30, v31, s70, v30
	s_nop 0
	v_mul_f32_e32 v31, v29, v231
	v_mul_f32_e32 v29, v29, v232
	s_nop 0
	v_fma_f32 v206, v30, v231, v29
	v_mul_f32_e32 v29, v26, v233
	v_mul_f32_e32 v26, v26, v234
	v_fma_f32 v205, -v30, v232, v31
	v_add_f32_e32 v30, v194, v38
	v_sub_f32_e32 v31, v193, v43
	s_nop 0
	v_fma_f32 v29, -v27, v234, v29
	v_fma_f32 v26, v27, v233, v26
	v_mul_f32_e32 v27, s78, v24
	v_mul_f32_e32 v24, s77, v24
	s_nop 0
	v_fma_f32 v27, -v25, s77, v27
	v_fma_f32 v24, v25, s78, v24
	s_nop 0
	v_mul_f32_e32 v25, v27, v233
	s_nop 0
	v_fma_f32 v207, -v24, v234, v25
	v_mul_f32_e32 v25, v27, v234
	v_add_f32_e32 v27, v193, v43
	s_nop 0
	v_fma_f32 v208, v24, v233, v25
	v_add_f32_e32 v24, v22, v129
	v_add_f32_e32 v25, v23, v124
	v_sub_f32_e32 v22, v22, v129
	v_sub_f32_e32 v23, v23, v124
	s_nop 0
	v_add_f32_e32 v35, v24, v27
	v_add_f32_e32 v37, v25, v30
	v_sub_f32_e32 v38, v24, v27
	v_sub_f32_e32 v43, v25, v30
	v_sub_f32_e32 v24, v22, v33
	v_add_f32_e32 v25, v23, v31
	v_add_f32_e32 v33, v22, v33
	v_sub_f32_e32 v124, v23, v31
	v_add_f32_e32 v22, v235, v125
	v_add_f32_e32 v23, v236, v120
	v_sub_f32_e32 v27, v235, v125
	v_sub_f32_e32 v30, v236, v120
	v_add_f32_e32 v31, v197, v36
	v_add_f32_e32 v120, v198, v34
	v_sub_f32_e32 v36, v197, v36
	v_sub_f32_e32 v34, v198, v34
	s_nop 0
	v_add_f32_e32 v125, v22, v31
	v_add_f32_e32 v129, v23, v120
	v_sub_f32_e32 v22, v22, v31
	v_sub_f32_e32 v23, v23, v120
	v_sub_f32_e32 v31, v27, v34
	v_add_f32_e32 v120, v30, v36
	v_add_f32_e32 v27, v27, v34
	v_sub_f32_e32 v30, v30, v36
	v_add_f32_e32 v34, v151, v121
	v_add_f32_e32 v36, v170, v46
	v_sub_f32_e32 v121, v151, v121
	v_sub_f32_e32 v46, v170, v46
	v_add_f32_e32 v151, v199, v32
	v_add_f32_e32 v170, v200, v28
	v_sub_f32_e32 v32, v199, v32
	v_sub_f32_e32 v28, v200, v28
	s_nop 0
	v_mul_f32_e32 v22, v22, v154
	v_add_f32_e32 v193, v34, v151
	v_add_f32_e32 v194, v36, v170
	v_sub_f32_e32 v34, v34, v151
	v_sub_f32_e32 v36, v36, v170
	v_sub_f32_e32 v151, v121, v28
	v_add_f32_e32 v170, v46, v32
	v_add_f32_e32 v28, v121, v28
	v_sub_f32_e32 v32, v46, v32
	v_add_f32_e32 v121, v192, v42
	v_pk_add_f32 v[46:47], v[170:171], v[46:47] op_sel:[1,1] op_sel_hi:[1,1] neg_lo:[0,0] neg_hi:[0,1]
	v_sub_f32_e32 v42, v192, v42
	v_add_f32_e32 v171, v201, v29
	v_add_f32_e32 v192, v128, v26
	v_sub_f32_e32 v29, v201, v29
	v_sub_f32_e32 v26, v128, v26
	s_nop 0
	v_xor_b32_e32 v36, 0x80000000, v36
	v_add_f32_e32 v128, v46, v171
	v_add_f32_e32 v197, v121, v192
	v_sub_f32_e32 v46, v46, v171
	v_sub_f32_e32 v121, v121, v192
	v_sub_f32_e32 v171, v47, v26
	v_add_f32_e32 v192, v42, v29
	v_add_f32_e32 v26, v47, v26
	v_sub_f32_e32 v29, v42, v29
	v_mul_f32_e32 v42, v31, v152
	v_mul_f32_e32 v31, v31, v156
	v_mul_f32_e32 v47, v151, v154
	s_nop 0
	v_mul_f32_e32 v151, v171, v156
	v_fma_f32 v42, -v120, v156, v42
	v_fma_f32 v31, v120, v152, v31
	v_fma_f32 v120, -v170, v154, v47
	v_fma_f32 v47, v170, v154, v47
	v_mul_f32_e32 v170, v171, v152
	s_nop 0
	v_fma_f32 v151, -v192, v152, v151
	v_fma_f32 v171, -v23, v154, v22
	v_fma_f32 v170, v192, v156, v170
	v_fma_f32 v192, v23, v154, v22
	v_mul_f32_e32 v22, v46, v155
	v_add_f32_e32 v23, v37, v194
	s_nop 0
	v_fma_f32 v198, -v121, v154, v22
	v_mul_f32_e32 v22, v46, v154
	s_nop 0
	v_fma_f32 v46, v121, v155, v22
	v_mul_f32_e32 v22, v27, v156
	s_nop 0
	v_fma_f32 v121, -v30, v152, v22
	v_mul_f32_e32 v22, v27, v152
	v_add_f32_e32 v27, v129, v197
	s_nop 0
	v_fma_f32 v199, v30, v156, v22
	v_mul_f32_e32 v22, v28, v155
	v_sub_f32_e32 v30, v125, v128
	v_add_f32_e32 v27, v23, v27
	s_nop 0
	v_fma_f32 v200, -v32, v154, v22
	v_mul_f32_e32 v22, v28, v154
	v_sub_f32_e32 v28, v35, v193
	s_nop 0
	v_fma_f32 v32, v32, v155, v22
	v_mul_f32_e32 v22, v26, v157
	s_nop 0
	v_fma_f32 v201, -v29, v153, v22
	v_mul_f32_e32 v22, v26, v153
	v_add_f32_e32 v26, v125, v128
	v_sub_f32_e32 v125, v191, v204
	s_nop 0
	v_fma_f32 v209, v29, v157, v22
	v_add_f32_e32 v22, v35, v193
	v_sub_f32_e32 v29, v37, v194
	v_sub_f32_e32 v35, v129, v197
	v_sub_f32_e32 v37, v42, v151
	v_and_b32_e32 v197, 0xffff0000, v13
	v_add_f32_e32 v26, v22, v26
	v_sub_f32_e32 v22, v28, v35
	v_add_f32_e32 v23, v29, v30
	v_add_f32_e32 v28, v24, v120
	v_add_f32_e32 v29, v25, v47
	v_sub_f32_e32 v24, v24, v120
	v_sub_f32_e32 v25, v25, v47
	v_add_f32_e32 v30, v42, v151
	v_add_f32_e32 v35, v31, v170
	v_sub_f32_e32 v42, v31, v170
	v_sub_f32_e32 v47, v195, v202
	v_add_f32_e32 v151, v188, v205
	s_nop 0
	v_add_f32_e32 v25, v25, v37
	v_add_f32_e32 v30, v28, v30
	v_add_f32_e32 v31, v29, v35
	v_sub_f32_e32 v24, v24, v42
	v_add_f32_e32 v28, v38, v36
	v_add_f32_e32 v29, v43, v34
	v_sub_f32_e32 v36, v38, v36
	v_sub_f32_e32 v37, v43, v34
	v_add_f32_e32 v34, v171, v198
	v_add_f32_e32 v35, v192, v46
	v_sub_f32_e32 v38, v171, v198
	v_sub_f32_e32 v42, v192, v46
	v_sub_f32_e32 v43, v121, v201
	v_sub_f32_e32 v46, v199, v209
	s_nop 0
	v_pk_add_f32 v[34:35], v[28:29], v[34:35] op_sel:[0,0] op_sel_hi:[1,1]
	v_add_f32_e32 v29, v37, v38
	v_sub_f32_e32 v28, v36, v42
	v_add_f32_e32 v36, v33, v200
	v_add_f32_e32 v37, v124, v32
	v_sub_f32_e32 v33, v33, v200
	v_sub_f32_e32 v38, v124, v32
	v_add_f32_e32 v32, v121, v201
	v_add_f32_e32 v42, v199, v209
	v_add_f32_e32 v170, v189, v206
	v_sub_f32_e32 v171, v188, v205
	v_and_b32_e32 v205, 0xffff0000, v8
	v_add_f32_e32 v36, v36, v32
	v_add_f32_e32 v37, v37, v42
	v_sub_f32_e32 v32, v33, v46
	v_add_f32_e32 v33, v38, v43
	v_add_f32_e32 v38, v20, v123
	v_add_f32_e32 v42, v21, v122
	v_pk_add_f32 v[20:21], v[20:21], v[122:123] op_sel:[0,1] op_sel_hi:[1,0] neg_lo:[0,1] neg_hi:[0,1]
	v_add_f32_e32 v43, v195, v202
	v_add_f32_e32 v46, v196, v39
	v_sub_f32_e32 v39, v196, v39
	v_and_b32_e32 v195, 0xffff0000, v12
	v_add_f32_e32 v120, v38, v43
	v_add_f32_e32 v121, v42, v46
	v_sub_f32_e32 v122, v38, v43
	v_sub_f32_e32 v46, v42, v46
	v_sub_f32_e32 v42, v20, v39
	v_add_f32_e32 v43, v21, v47
	v_add_f32_e32 v123, v20, v39
	v_sub_f32_e32 v124, v21, v47
	v_pk_add_f32 v[20:21], v[186:187], v[48:49] op_sel:[0,1] op_sel_hi:[1,0]
	v_pk_add_f32 v[38:39], v[186:187], v[48:49] op_sel:[0,1] op_sel_hi:[1,0] neg_lo:[0,1] neg_hi:[0,1]
	v_add_f32_e32 v47, v190, v203
	v_add_f32_e32 v48, v191, v204
	v_sub_f32_e32 v49, v190, v203
	v_mov_b32_e32 v196, v195
	v_add_f32_e32 v128, v20, v47
	v_add_f32_e32 v129, v21, v48
	v_sub_f32_e32 v20, v20, v47
	v_sub_f32_e32 v21, v21, v48
	v_sub_f32_e32 v47, v38, v125
	v_add_f32_e32 v48, v39, v49
	v_add_f32_e32 v38, v38, v125
	v_sub_f32_e32 v39, v39, v49
	v_add_f32_e32 v49, v184, v45
	v_add_f32_e32 v125, v185, v44
	v_pk_add_f32 v[44:45], v[184:185], v[44:45] op_sel:[1,0] op_sel_hi:[0,1] neg_lo:[0,1] neg_hi:[0,1]
	v_sub_f32_e32 v184, v189, v206
	s_nop 0
	v_mul_f32_e32 v20, v20, v154
	v_add_f32_e32 v185, v49, v151
	v_add_f32_e32 v186, v125, v170
	v_sub_f32_e32 v49, v49, v151
	v_sub_f32_e32 v125, v125, v170
	v_sub_f32_e32 v151, v45, v184
	v_add_f32_e32 v170, v44, v171
	v_add_f32_e32 v45, v45, v184
	v_sub_f32_e32 v44, v44, v171
	v_add_f32_e32 v171, v182, v41
	v_add_f32_e32 v184, v183, v40
	v_pk_add_f32 v[40:41], v[182:183], v[40:41] op_sel:[1,0] op_sel_hi:[0,1] neg_lo:[0,1] neg_hi:[0,1]
	v_add_f32_e32 v182, v126, v207
	v_sub_f32_e32 v126, v126, v207
	v_add_f32_e32 v183, v127, v208
	v_sub_f32_e32 v127, v127, v208
	s_nop 0
	v_xor_b32_e32 v125, 0x80000000, v125
	v_add_f32_e32 v187, v171, v182
	v_add_f32_e32 v188, v184, v183
	v_sub_f32_e32 v171, v171, v182
	v_sub_f32_e32 v182, v184, v183
	v_add_f32_e32 v184, v40, v126
	v_sub_f32_e32 v40, v40, v126
	v_mul_f32_e32 v126, v47, v152
	v_mul_f32_e32 v47, v47, v156
	v_sub_f32_e32 v183, v41, v127
	v_add_f32_e32 v41, v41, v127
	v_lshlrev_b32_e32 v204, 16, v8
	v_fma_f32 v126, -v48, v156, v126
	v_fma_f32 v47, v48, v152, v47
	v_mul_f32_e32 v48, v151, v154
	v_mul_f32_e32 v151, v183, v156
	v_mov_b32_e32 v13, v210
	v_fma_f32 v127, -v170, v154, v48
	v_fma_f32 v48, v170, v154, v48
	v_mul_f32_e32 v170, v183, v152
	v_fma_f32 v151, -v184, v152, v151
	v_fma_f32 v183, -v21, v154, v20
	v_lshlrev_b32_e32 v199, 16, v15
	v_fma_f32 v170, v184, v156, v170
	v_fma_f32 v184, v21, v154, v20
	v_mul_f32_e32 v20, v171, v155
	v_add_f32_e32 v21, v121, v186
	v_and_b32_e32 v15, 0xffff0000, v15
	v_fma_f32 v189, -v182, v154, v20
	v_mul_f32_e32 v20, v171, v154
	v_mov_b32_e32 v198, v14
	v_fma_f32 v171, v182, v155, v20
	v_mul_f32_e32 v20, v38, v156
	v_and_b32_e32 v207, 0xffff0000, v9
	v_fma_f32 v182, -v39, v152, v20
	v_mul_f32_e32 v20, v38, v152
	v_sub_f32_e32 v38, v120, v185
	v_mov_b32_e32 v206, v205
	v_fma_f32 v190, v39, v156, v20
	v_mul_f32_e32 v20, v45, v155
	v_sub_f32_e32 v39, v121, v186
	v_sub_f32_e32 v121, v184, v171
	v_lshlrev_b32_e32 v209, 16, v11
	v_fma_f32 v191, -v44, v154, v20
	v_mul_f32_e32 v20, v45, v154
	v_sub_f32_e32 v45, v129, v188
	v_and_b32_e32 v11, 0xffff0000, v11
	v_fma_f32 v192, v44, v155, v20
	v_mul_f32_e32 v20, v41, v157
	v_sub_f32_e32 v44, v128, v187
	v_pk_add_f32 v[38:39], v[38:39], v[44:45] op_sel:[0,1] op_sel_hi:[1,0] neg_lo:[0,1] neg_hi:[0,0]
	v_add_f32_e32 v45, v47, v170
	v_sub_f32_e32 v47, v47, v170
	v_mov_b32_e32 v202, v209
	v_fma_f32 v193, -v40, v153, v20
	v_mul_f32_e32 v20, v41, v153
	v_add_f32_e32 v41, v129, v188
	v_add_f32_e32 v44, v126, v151
	s_nop 0
	v_fma_f32 v194, v40, v157, v20
	v_add_f32_e32 v20, v120, v185
	v_add_f32_e32 v40, v128, v187
	v_pk_add_f32 v[20:21], v[20:21], v[40:41] op_sel:[0,0] op_sel_hi:[1,1]
	v_add_f32_e32 v41, v43, v48
	v_sub_f32_e32 v43, v43, v48
	v_sub_f32_e32 v48, v126, v151
	v_sub_f32_e32 v120, v183, v189
	s_nop 0
	v_add_f32_e32 v40, v42, v127
	v_sub_f32_e32 v42, v42, v127
	v_pk_add_f32 v[40:41], v[40:41], v[44:45] op_sel:[0,0] op_sel_hi:[1,1]
	v_add_f32_e32 v43, v43, v48
	v_add_f32_e32 v45, v46, v49
	v_sub_f32_e32 v48, v46, v49
	s_nop 0
	v_sub_f32_e32 v42, v42, v47
	v_add_f32_e32 v44, v122, v125
	v_sub_f32_e32 v47, v122, v125
	v_add_f32_e32 v46, v183, v189
	v_add_f32_e32 v49, v184, v171
	v_add_f32_e32 v122, v182, v193
	v_sub_f32_e32 v125, v190, v194
	v_lshl_add_u64 v[126:127], v[58:59], 1, s[44:45]
	v_add_f32_e32 v44, v44, v46
	v_add_f32_e32 v45, v45, v49
	v_sub_f32_e32 v46, v47, v121
	v_add_f32_e32 v47, v48, v120
	v_add_f32_e32 v48, v123, v191
	v_add_f32_e32 v49, v124, v192
	v_sub_f32_e32 v120, v123, v191
	v_sub_f32_e32 v121, v124, v192
	v_add_f32_e32 v123, v190, v194
	v_sub_f32_e32 v124, v182, v193
	s_nop 0
	v_lshl_add_u64 v[128:129], v[60:61], 1, s[44:45]
	v_pk_add_f32 v[48:49], v[48:49], v[122:123] op_sel:[0,0] op_sel_hi:[1,1]
	v_pk_add_f32 v[120:121], v[120:121], v[124:125] op_sel:[0,1] op_sel_hi:[1,0] neg_lo:[0,1] neg_hi:[0,0]
	ds_write_b64 v180, v[26:27]
	ds_write_b64 v181, v[20:21] offset:4096
	ds_write_b64 v180, v[30:31] offset:8704
	ds_write_b64 v181, v[40:41] offset:12800
	ds_write_b64 v180, v[34:35] offset:17408
	ds_write_b64 v181, v[44:45] offset:21504
	ds_write_b64 v180, v[36:37] offset:26112
	ds_write_b64 v181, v[48:49] offset:30208
	ds_write_b64 v180, v[22:23] offset:34816
	ds_write_b64 v181, v[38:39] offset:38912
	ds_write_b64 v180, v[24:25] offset:43520
	ds_write_b64 v181, v[42:43] offset:47616
	ds_write_b64 v180, v[28:29] offset:52224
	ds_write_b64 v181, v[46:47] offset:56320
	ds_write_b64 v180, v[32:33] offset:60928
	ds_write_b64 v181, v[120:121] offset:65024
	s_waitcnt lgkmcnt(0)
	s_barrier
	v_lshl_add_u64 v[34:35], v[84:85], 0, s[0:1]
	s_add_u32 s0, s40, s26
	s_addc_u32 s1, s41, s27
	global_load_dword v21, v83, s[48:49]
	global_load_dword v20, v175, s[48:49]
	global_load_dword v22, v83, s[0:1]
	global_load_dword v24, v176, s[48:49]
	v_add_co_u32_e32 v32, vcc, s58, v34
	v_lshl_add_u64 v[38:39], v[50:51], 1, s[44:45]
	s_nop 0
	v_addc_co_u32_e32 v33, vcc, 0, v35, vcc
	v_add_co_u32_e32 v36, vcc, s60, v34
	v_lshl_add_u64 v[46:47], v[52:53], 1, s[44:45]
	s_nop 0
	v_addc_co_u32_e32 v37, vcc, 0, v35, vcc
	v_add_co_u32_e32 v40, vcc, s61, v34
	v_lshl_add_u64 v[48:49], v[54:55], 1, s[44:45]
	s_nop 0
	v_addc_co_u32_e32 v41, vcc, 0, v35, vcc
	v_lshl_add_u64 v[124:125], v[56:57], 1, s[44:45]
	global_load_ushort v23, v[34:35], off nt
	global_load_ushort v25, v[34:35], off offset:2048 nt
	global_load_ushort v26, v[32:33], off offset:2048 nt
	global_load_ushort v27, v[40:41], off nt
	global_load_ushort v28, v[34:35], off offset:3072 nt
	global_load_ushort v30, v[32:33], off offset:3072 nt
	s_nop 0
	global_load_ushort v32, v[32:33], off offset:1024 nt
	s_nop 0
	global_load_ushort v31, v[34:35], off offset:1024 nt
	global_load_ushort v42, v[36:37], off offset:-4096 nt
	global_load_ushort v44, v[36:37], off nt
	global_load_ushort v45, v[36:37], off offset:2048 nt
	global_load_ushort v121, v[36:37], off offset:3072 nt
	global_load_ushort v122, v[36:37], off offset:1024 nt
	global_load_ushort v29, v[40:41], off offset:2048 nt
	global_load_ushort v33, v[38:39], off nt
	global_load_ushort v34, v[46:47], off nt
	global_load_ushort v35, v[48:49], off nt
	s_nop 0
	global_load_ushort v36, v[124:125], off nt
	global_load_ushort v37, v[126:127], off nt
	global_load_ushort v38, v[40:41], off offset:3072 nt
	global_load_ushort v39, v[40:41], off offset:1024 nt
	v_lshl_add_u64 v[46:47], v[66:67], 1, s[44:45]
	v_lshl_add_u64 v[48:49], v[68:69], 1, s[44:45]
	v_lshl_add_u64 v[180:181], v[62:63], 1, s[44:45]
	v_lshl_add_u64 v[182:183], v[64:65], 1, s[44:45]
	v_lshl_add_u64 v[124:125], v[70:71], 1, s[44:45]
	v_lshl_add_u64 v[126:127], v[72:73], 1, s[44:45]
	v_lshl_add_u64 v[184:185], v[74:75], 1, s[44:45]
	global_load_ushort v40, v[128:129], off nt
	global_load_ushort v41, v[180:181], off nt
	global_load_ushort v43, v[182:183], off nt
	s_nop 0
	global_load_ushort v46, v[46:47], off nt
	s_nop 0
	global_load_ushort v47, v[48:49], off nt
	s_nop 0
	global_load_ushort v48, v[124:125], off nt
	global_load_ushort v49, v[126:127], off nt
	global_load_ushort v120, v[184:185], off nt
	v_lshl_add_u64 v[124:125], v[76:77], 1, s[44:45]
	v_lshl_add_u64 v[126:127], v[78:79], 1, s[44:45]
	v_lshl_add_u64 v[128:129], v[80:81], 1, s[44:45]
	global_load_ushort v123, v[124:125], off nt
	s_nop 0
	global_load_ushort v124, v[126:127], off nt
	global_load_ushort v125, v[128:129], off nt
	v_lshlrev_b32_e32 v126, 16, v177
	v_cndmask_b32_e64 v191, 0, v126, s[12:13]
	v_lshlrev_b32_e32 v126, 16, v134
	v_lshlrev_b32_e32 v194, 16, v12
	v_lshlrev_b32_e32 v12, 16, v179
	v_mov_b32_e32 v190, v210
	v_cndmask_b32_e64 v193, 0, v126, s[4:5]
	v_cndmask_b32_e64 v201, 0, v12, s[12:13]
	v_lshlrev_b32_e32 v12, 16, v178
	ds_read_b128 v[126:129], v145
	ds_read_b128 v[178:181], v145 offset:16
	ds_read_b128 v[182:185], v145 offset:32
	ds_read_b128 v[186:189], v145 offset:48
	v_cndmask_b32_e64 v203, 0, v12, s[4:5]
	v_mov_b32_e32 v12, v194
	v_mov_b32_e32 v192, v199
	s_add_u32 s24, s24, s34
	s_addc_u32 s25, s25, s35
	s_add_u32 s42, s42, s34
	s_addc_u32 s43, s43, s35
	s_add_u32 s40, s40, s34
	s_addc_u32 s41, s41, s35
	s_add_u32 s36, s36, s38
	s_addc_u32 s37, s37, s39
	s_mov_b32 s44, s52
	s_waitcnt vmcnt(35)
	v_mov_b32_e32 v8, v21
	s_waitcnt vmcnt(34)
	v_pk_mul_f32 v[190:191], v[190:191], v[20:21]
	s_nop 0
	v_pk_fma_f32 v[190:191], v[20:21], v[194:195], v[190:191] op_sel:[0,0,1] op_sel_hi:[1,1,0]
	v_pk_mul_f32 v[194:195], v[20:21], v[196:197] op_sel_hi:[0,1]
	s_waitcnt vmcnt(30)
	v_pk_fma_f32 v[190:191], v[24:25], v[196:197], v[190:191] op_sel_hi:[0,1,1]
	v_pk_fma_f32 v[12:13], v[8:9], v[12:13], v[194:195] op_sel_hi:[0,1,1]
	v_pk_add_f32 v[190:191], v[22:23], v[190:191] op_sel_hi:[0,1]
	v_pk_fma_f32 v[12:13], v[24:25], v[210:211], v[12:13] op_sel_hi:[0,1,1]
	s_waitcnt lgkmcnt(3)
	v_mov_b32_e32 v194, v126
	s_waitcnt lgkmcnt(2)
	v_mov_b32_e32 v195, v178
	v_pk_add_f32 v[12:13], v[22:23], v[12:13] op_sel_hi:[0,1]
	v_pk_mul_f32 v[190:191], v[194:195], v[190:191]
	v_mov_b32_e32 v194, v128
	v_mov_b32_e32 v195, v180
	v_pk_mul_f32 v[12:13], v[194:195], v[12:13]
	v_pk_mov_b32 v[194:195], v[196:197], v[14:15] op_sel:[1,0]
	v_mov_b32_e32 v196, v211
	v_mov_b32_e32 v197, v199
	v_pk_mul_f32 v[196:197], v[20:21], v[196:197] op_sel_hi:[0,1]
	v_pk_fma_f32 v[194:195], v[8:9], v[194:195], v[196:197] op_sel_hi:[0,1,1]
	v_mov_b32_e32 v210, v15
	v_pk_fma_f32 v[194:195], v[24:25], v[14:15], v[194:195] op_sel_hi:[0,1,1]
	v_pk_mul_f32 v[14:15], v[20:21], v[210:211]
	v_pk_add_f32 v[194:195], v[22:23], v[194:195] op_sel_hi:[0,1]
	v_pk_fma_f32 v[14:15], v[20:21], v[198:199], v[14:15] op_sel:[0,0,1] op_sel_hi:[1,1,0]
	v_bfe_u32 v134, v13, 16, 1
	v_pk_fma_f32 v[14:15], v[24:25], v[192:193], v[14:15] op_sel_hi:[0,1,1]
	s_waitcnt lgkmcnt(1)
	v_mov_b32_e32 v192, v182
	s_waitcnt lgkmcnt(0)
	v_mov_b32_e32 v193, v186
	v_pk_add_f32 v[14:15], v[22:23], v[14:15] op_sel_hi:[0,1]
	v_pk_mul_f32 v[192:193], v[194:195], v[192:193]
	v_mov_b32_e32 v194, v184
	v_mov_b32_e32 v195, v188
	v_pk_mul_f32 v[14:15], v[14:15], v[194:195]
	v_add3_u32 v13, v13, v134, s89
	v_bfe_u32 v126, v15, 16, 1
	v_bfe_u32 v128, v14, 16, 1
	v_bfe_u32 v134, v190, 16, 1
	v_bfe_u32 v151, v12, 16, 1
	v_add3_u32 v14, v14, v128, s89
	v_add3_u32 v15, v15, v126, s89
	v_bfe_u32 v126, v192, 16, 1
	v_bfe_u32 v128, v193, 16, 1
	v_add3_u32 v134, v190, v134, s89
	v_lshlrev_b32_e32 v190, 16, v9
	v_add3_u32 v12, v12, v151, s89
	v_bfe_u32 v151, v191, 16, 1
	v_add3_u32 v128, v193, v128, s89
	v_add3_u32 v126, v192, v126, s89
	v_mov_b32_e32 v192, v204
	v_mov_b32_e32 v193, v190
	v_mov_b32_e32 v200, v190
	v_pk_mul_f32 v[196:197], v[20:21], v[206:207] op_sel_hi:[0,1]
	v_add3_u32 v151, v191, v151, s89
	v_lshlrev_b32_e32 v191, 16, v10
	v_pk_mul_f32 v[194:195], v[200:201], v[20:21]
	v_pk_fma_f32 v[192:193], v[8:9], v[192:193], v[196:197] op_sel_hi:[0,1,1]
	v_pk_fma_f32 v[194:195], v[20:21], v[204:205], v[194:195] op_sel:[0,0,1] op_sel_hi:[1,1,0]
	v_pk_fma_f32 v[192:193], v[24:25], v[190:191], v[192:193] op_sel_hi:[0,1,1]
	v_lshrrev_b32_e32 v128, 16, v128
	v_pk_fma_f32 v[194:195], v[24:25], v[206:207], v[194:195] op_sel_hi:[0,1,1]
	v_pk_add_f32 v[192:193], v[22:23], v[192:193] op_sel_hi:[0,1]
	v_mov_b32_e32 v180, v129
	v_lshrrev_b32_e32 v126, 16, v126
	v_and_or_b32 v15, v15, s85, v128
	v_pk_add_f32 v[194:195], v[22:23], v[194:195] op_sel_hi:[0,1]
	v_mov_b32_e32 v178, v127
	v_pk_mul_f32 v[128:129], v[180:181], v[192:193]
	v_and_b32_e32 v10, 0xffff0000, v10
	v_mov_b32_e32 v180, v191
	v_mov_b32_e32 v181, v209
	v_and_or_b32 v14, v14, s85, v126
	v_pk_mul_f32 v[126:127], v[178:179], v[194:195]
	v_pk_mov_b32 v[178:179], v[206:207], v[10:11] op_sel:[1,0]
	v_pk_mul_f32 v[180:181], v[20:21], v[180:181] op_sel_hi:[0,1]
	v_pk_fma_f32 v[178:179], v[8:9], v[178:179], v[180:181] op_sel_hi:[0,1,1]
	v_mov_b32_e32 v190, v11
	v_mov_b32_e32 v208, v10
	v_pk_fma_f32 v[178:179], v[24:25], v[10:11], v[178:179] op_sel_hi:[0,1,1]
	v_pk_mul_f32 v[10:11], v[20:21], v[190:191]
	v_mov_b32_e32 v188, v185
	v_pk_fma_f32 v[10:11], v[20:21], v[208:209], v[10:11] op_sel:[0,0,1] op_sel_hi:[1,1,0]
	v_pk_add_f32 v[178:179], v[22:23], v[178:179] op_sel_hi:[0,1]
	v_pk_fma_f32 v[10:11], v[24:25], v[202:203], v[10:11] op_sel_hi:[0,1,1]
	v_pk_add_f32 v[10:11], v[22:23], v[10:11] op_sel_hi:[0,1]
	v_mov_b32_e32 v186, v183
	v_pk_mul_f32 v[10:11], v[10:11], v[188:189]
	v_lshrrev_b32_e32 v134, 16, v134
	v_lshrrev_b32_e32 v151, 16, v151
	v_pk_mul_f32 v[178:179], v[178:179], v[186:187]
	v_bfe_u32 v9, v11, 16, 1
	v_bfe_u32 v170, v128, 16, 1
	v_and_or_b32 v13, v13, s85, v151
	v_and_or_b32 v12, v12, s85, v134
	v_bfe_u32 v134, v10, 16, 1
	v_bfe_u32 v151, v129, 16, 1
	v_add3_u32 v9, v11, v9, s89
	v_add3_u32 v11, v128, v170, s89
	v_bfe_u32 v128, v178, 16, 1
	v_add3_u32 v10, v10, v134, s89
	v_add3_u32 v134, v129, v151, s89
	v_bfe_u32 v151, v126, 16, 1
	v_add3_u32 v128, v178, v128, s89
	v_add3_u32 v126, v126, v151, s89
	v_lshrrev_b32_e32 v128, 16, v128
	v_bfe_u32 v129, v179, 16, 1
	v_bfe_u32 v170, v127, 16, 1
	v_lshrrev_b32_e32 v126, 16, v126
	v_and_or_b32 v128, v10, s85, v128
	v_add_co_u32_e32 v10, vcc, s90, v18
	v_add3_u32 v129, v179, v129, s89
	v_add3_u32 v127, v127, v170, s89
	v_and_or_b32 v126, v11, s85, v126
	v_addc_co_u32_e32 v11, vcc, 0, v19, vcc
	v_lshrrev_b32_e32 v129, 16, v129
	v_lshrrev_b32_e32 v127, 16, v127
	global_store_dwordx4 v[10:11], v[12:15], off
	v_add_co_u32_e32 v10, vcc, s91, v18
	v_and_or_b32 v129, v9, s85, v129
	v_and_or_b32 v127, v134, s85, v127
	v_addc_co_u32_e32 v11, vcc, 0, v19, vcc
	v_lshlrev_b32_e32 v9, 16, v131
	v_lshlrev_b32_e32 v200, 16, v5
	global_store_dwordx4 v[10:11], v[126:129], off
	v_cndmask_b32_e64 v15, 0, v9, s[6:7]
	v_lshlrev_b32_e32 v186, 16, v4
	v_and_b32_e32 v187, 0xffff0000, v4
	v_lshlrev_b32_e32 v4, 16, v132
	v_mov_b32_e32 v14, v200
	v_and_b32_e32 v131, 0xffff0000, v5
	v_cndmask_b32_e64 v191, 0, v4, s[6:7]
	v_lshlrev_b32_e32 v4, 16, v130
	ds_read_b128 v[10:13], v146 offset:32768
	ds_read_b128 v[126:129], v146 offset:32784
	ds_read_b128 v[178:181], v146 offset:32800
	ds_read_b128 v[182:185], v146 offset:32816
	v_mov_b32_e32 v130, v187
	v_pk_mul_f32 v[14:15], v[14:15], v[20:21]
	v_lshlrev_b32_e32 v9, 16, v82
	v_cndmask_b32_e64 v193, 0, v4, s[8:9]
	v_mov_b32_e32 v4, v186
	v_mov_b32_e32 v5, v200
	v_pk_fma_f32 v[14:15], v[20:21], v[186:187], v[14:15] op_sel:[0,0,1] op_sel_hi:[1,1,0]
	v_pk_mul_f32 v[186:187], v[20:21], v[130:131] op_sel_hi:[0,1]
	v_lshlrev_b32_e32 v201, 16, v6
	v_pk_fma_f32 v[14:15], v[24:25], v[130:131], v[14:15] op_sel_hi:[0,1,1]
	v_pk_fma_f32 v[4:5], v[8:9], v[4:5], v[186:187] op_sel_hi:[0,1,1]
	v_pk_add_f32 v[14:15], v[22:23], v[14:15] op_sel_hi:[0,1]
	v_pk_fma_f32 v[4:5], v[24:25], v[200:201], v[4:5] op_sel_hi:[0,1,1]
	s_waitcnt lgkmcnt(3)
	v_mov_b32_e32 v186, v10
	s_waitcnt lgkmcnt(2)
	v_mov_b32_e32 v187, v126
	v_lshlrev_b32_e32 v189, 16, v7
	v_pk_add_f32 v[4:5], v[22:23], v[4:5] op_sel_hi:[0,1]
	v_pk_mul_f32 v[14:15], v[14:15], v[186:187]
	v_mov_b32_e32 v186, v12
	v_mov_b32_e32 v187, v128
	v_pk_mul_f32 v[4:5], v[4:5], v[186:187]
	v_and_b32_e32 v7, 0xffff0000, v7
	v_and_b32_e32 v6, 0xffff0000, v6
	v_mov_b32_e32 v186, v201
	v_mov_b32_e32 v187, v189
	v_pk_mov_b32 v[130:131], v[130:131], v[6:7] op_sel:[1,0]
	v_pk_mul_f32 v[186:187], v[20:21], v[186:187] op_sel_hi:[0,1]
	v_pk_fma_f32 v[130:131], v[8:9], v[130:131], v[186:187] op_sel_hi:[0,1,1]
	v_mov_b32_e32 v200, v7
	v_mov_b32_e32 v188, v6
	v_pk_fma_f32 v[130:131], v[24:25], v[6:7], v[130:131] op_sel_hi:[0,1,1]
	v_pk_mul_f32 v[6:7], v[20:21], v[200:201]
	v_cndmask_b32_e64 v19, 0, v9, s[8:9]
	v_mov_b32_e32 v18, v189
	v_pk_fma_f32 v[6:7], v[20:21], v[188:189], v[6:7] op_sel:[0,0,1] op_sel_hi:[1,1,0]
	v_pk_add_f32 v[130:131], v[22:23], v[130:131] op_sel_hi:[0,1]
	v_pk_fma_f32 v[6:7], v[24:25], v[18:19], v[6:7] op_sel_hi:[0,1,1]
	s_waitcnt lgkmcnt(1)
	v_mov_b32_e32 v18, v178
	s_waitcnt lgkmcnt(0)
	v_mov_b32_e32 v19, v182
	v_pk_add_f32 v[6:7], v[22:23], v[6:7] op_sel_hi:[0,1]
	v_pk_mul_f32 v[18:19], v[130:131], v[18:19]
	v_mov_b32_e32 v130, v180
	v_mov_b32_e32 v131, v184
	v_pk_mul_f32 v[6:7], v[6:7], v[130:131]
	v_lshlrev_b32_e32 v194, 16, v0
	v_and_b32_e32 v195, 0xffff0000, v0
	v_bfe_u32 v0, v7, 16, 1
	v_bfe_u32 v10, v5, 16, 1
	v_add3_u32 v0, v7, v0, s89
	v_bfe_u32 v7, v18, 16, 1
	v_bfe_u32 v9, v6, 16, 1
	v_add3_u32 v5, v5, v10, s89
	v_bfe_u32 v10, v14, 16, 1
	v_add3_u32 v7, v18, v7, s89
	v_add3_u32 v6, v6, v9, s89
	v_add3_u32 v10, v14, v10, s89
	v_lshrrev_b32_e32 v14, 16, v7
	v_and_or_b32 v6, v6, s85, v14
	v_lshlrev_b32_e32 v14, 16, v1
	v_bfe_u32 v9, v19, 16, 1
	v_mov_b32_e32 v190, v14
	v_bfe_u32 v12, v4, 16, 1
	v_add3_u32 v9, v19, v9, s89
	v_pk_mul_f32 v[18:19], v[190:191], v[20:21]
	v_and_b32_e32 v197, 0xffff0000, v1
	v_add3_u32 v4, v4, v12, s89
	v_bfe_u32 v12, v15, 16, 1
	v_mov_b32_e32 v196, v195
	v_pk_fma_f32 v[18:19], v[20:21], v[194:195], v[18:19] op_sel:[0,0,1] op_sel_hi:[1,1,0]
	v_add3_u32 v12, v15, v12, s89
	v_pk_fma_f32 v[18:19], v[24:25], v[196:197], v[18:19] op_sel_hi:[0,1,1]
	v_lshlrev_b32_e32 v199, 16, v3
	v_lshrrev_b32_e32 v7, 16, v9
	v_lshrrev_b32_e32 v9, 16, v10
	v_lshrrev_b32_e32 v10, 16, v12
	v_lshlrev_b32_e32 v15, 16, v2
	v_pk_add_f32 v[18:19], v[22:23], v[18:19] op_sel_hi:[0,1]
	v_mov_b32_e32 v126, v11
	v_and_or_b32 v7, v0, s85, v7
	v_and_or_b32 v5, v5, s85, v10
	v_mov_b32_e32 v0, v194
	v_mov_b32_e32 v1, v14
	v_pk_mul_f32 v[130:131], v[20:21], v[196:197] op_sel_hi:[0,1]
	v_pk_mul_f32 v[10:11], v[18:19], v[126:127]
	v_and_b32_e32 v3, 0xffff0000, v3
	v_and_b32_e32 v2, 0xffff0000, v2
	v_mov_b32_e32 v18, v15
	v_mov_b32_e32 v19, v199
	v_pk_fma_f32 v[0:1], v[8:9], v[0:1], v[130:131] op_sel_hi:[0,1,1]
	v_mov_b32_e32 v128, v13
	v_pk_mov_b32 v[12:13], v[196:197], v[2:3] op_sel:[1,0]
	v_pk_mul_f32 v[18:19], v[20:21], v[18:19] op_sel_hi:[0,1]
	v_and_or_b32 v4, v4, s85, v9
	v_pk_fma_f32 v[0:1], v[24:25], v[14:15], v[0:1] op_sel_hi:[0,1,1]
	v_pk_fma_f32 v[8:9], v[8:9], v[12:13], v[18:19] op_sel_hi:[0,1,1]
	v_mov_b32_e32 v14, v3
	v_mov_b32_e32 v198, v2
	v_pk_fma_f32 v[8:9], v[24:25], v[2:3], v[8:9] op_sel_hi:[0,1,1]
	v_pk_mul_f32 v[2:3], v[20:21], v[14:15]
	v_mov_b32_e32 v192, v199
	v_pk_fma_f32 v[2:3], v[20:21], v[198:199], v[2:3] op_sel:[0,0,1] op_sel_hi:[1,1,0]
	v_mov_b32_e32 v184, v181
	v_pk_fma_f32 v[2:3], v[24:25], v[192:193], v[2:3] op_sel_hi:[0,1,1]
	v_pk_add_f32 v[2:3], v[22:23], v[2:3] op_sel_hi:[0,1]
	v_pk_add_f32 v[8:9], v[22:23], v[8:9] op_sel_hi:[0,1]
	v_mov_b32_e32 v182, v179
	v_pk_mul_f32 v[2:3], v[2:3], v[184:185]
	v_pk_mul_f32 v[8:9], v[8:9], v[182:183]
	v_bfe_u32 v12, v3, 16, 1
	v_pk_add_f32 v[0:1], v[22:23], v[0:1] op_sel_hi:[0,1]
	v_bfe_u32 v13, v2, 16, 1
	v_add3_u32 v3, v3, v12, s89
	v_bfe_u32 v12, v8, 16, 1
	v_pk_mul_f32 v[0:1], v[0:1], v[128:129]
	v_add3_u32 v2, v2, v13, s89
	v_bfe_u32 v13, v9, 16, 1
	v_add3_u32 v8, v8, v12, s89
	v_bfe_u32 v14, v1, 16, 1
	v_bfe_u32 v15, v0, 16, 1
	v_add3_u32 v9, v9, v13, s89
	v_lshrrev_b32_e32 v8, 16, v8
	v_add3_u32 v0, v0, v15, s89
	v_add3_u32 v1, v1, v14, s89
	v_bfe_u32 v14, v10, 16, 1
	v_bfe_u32 v15, v11, 16, 1
	v_lshrrev_b32_e32 v9, 16, v9
	v_and_or_b32 v2, v2, s85, v8
	v_add_co_u32_e32 v8, vcc, s90, v16
	v_add3_u32 v11, v11, v15, s89
	v_add3_u32 v10, v10, v14, s89
	v_and_or_b32 v3, v3, s85, v9
	v_addc_co_u32_e32 v9, vcc, 0, v17, vcc
	v_lshrrev_b32_e32 v10, 16, v10
	v_lshrrev_b32_e32 v11, 16, v11
	global_store_dwordx4 v[8:9], v[4:7], off
	v_and_or_b32 v1, v1, s85, v11
	v_and_or_b32 v0, v0, s85, v10
	v_add_co_u32_e32 v4, vcc, s91, v16
	s_nop 1
	v_addc_co_u32_e32 v5, vcc, 0, v17, vcc
	global_store_dwordx4 v[4:5], v[0:3], off
	s_waitcnt lgkmcnt(0)
	s_barrier
	s_and_b64 vcc, exec, s[46:47]
	s_cbranch_vccz .LBB0_414
